# GEMM k-step: DMA-landing wait (vmcnt) moved down to the late barrier, so the first four MFMAs issue before it
# speedup vs baseline: 1.0210x; 1.0048x over previous
.Lgy_nn_a:
	s_waitcnt lgkmcnt(0)
	v_add_u32_e32 v240, s61, v238
	v_add_u32_e32 v241, s61, v239
	s_setprio 1
	v_mfma_f32_16x16x32_bf16 v[2:5], v[162:165], v[130:133], 0
	v_mfma_f32_16x16x32_bf16 v[6:9], v[166:169], v[130:133], 0
	v_mfma_f32_16x16x32_bf16 v[10:13], v[170:173], v[130:133], 0
	v_mfma_f32_16x16x32_bf16 v[14:17], v[174:177], v[130:133], 0
	s_waitcnt vmcnt(6)
	s_barrier
	v_mfma_f32_16x16x32_bf16 v[18:21], v[162:165], v[134:137], 0
	s_add_i32 m0, s60, s62
	v_mfma_f32_16x16x32_bf16 v[22:25], v[166:169], v[134:137], 0
	global_load_lds_dwordx4 v226, s[54:55]
	v_mfma_f32_16x16x32_bf16 v[26:29], v[170:173], v[134:137], 0
	v_mfma_f32_16x16x32_bf16 v[30:33], v[174:177], v[134:137], 0
	v_mfma_f32_16x16x32_bf16 v[34:37], v[162:165], v[138:141], 0
	ds_read_b128 v[210:213], v241 offset:0
	v_mfma_f32_16x16x32_bf16 v[38:41], v[166:169], v[138:141], 0
	ds_read_b128 v[214:217], v241 offset:256
	v_mfma_f32_16x16x32_bf16 v[42:45], v[170:173], v[138:141], 0
	ds_read_b128 v[218:221], v241 offset:512
	global_load_lds_dwordx4 v226, s[54:55] offset:1024
	v_mfma_f32_16x16x32_bf16 v[46:49], v[174:177], v[138:141], 0
	ds_read_b128 v[222:225], v241 offset:768
	v_mfma_f32_16x16x32_bf16 v[50:53], v[162:165], v[142:145], 0
	ds_read_b128 v[178:181], v240 offset:0
	v_mfma_f32_16x16x32_bf16 v[54:57], v[166:169], v[142:145], 0
	ds_read_b128 v[182:185], v240 offset:1024
	v_mfma_f32_16x16x32_bf16 v[58:61], v[170:173], v[142:145], 0
	ds_read_b128 v[186:189], v240 offset:2048
	v_mfma_f32_16x16x32_bf16 v[62:65], v[174:177], v[142:145], 0
	ds_read_b128 v[190:193], v240 offset:3072
	global_load_lds_dwordx4 v226, s[54:55] offset:2048
	v_mfma_f32_16x16x32_bf16 v[66:69], v[162:165], v[146:149], 0
	ds_read_b128 v[194:197], v240 offset:4096
	v_mfma_f32_16x16x32_bf16 v[70:73], v[166:169], v[146:149], 0
	ds_read_b128 v[198:201], v240 offset:5120
	v_mfma_f32_16x16x32_bf16 v[74:77], v[170:173], v[146:149], 0
	ds_read_b128 v[202:205], v240 offset:6144
	v_mfma_f32_16x16x32_bf16 v[78:81], v[174:177], v[146:149], 0
	ds_read_b128 v[206:209], v240 offset:7168
	v_mfma_f32_16x16x32_bf16 v[82:85], v[162:165], v[150:153], 0
	global_load_lds_dwordx4 v226, s[54:55] offset:3072
	v_mfma_f32_16x16x32_bf16 v[86:89], v[166:169], v[150:153], 0
	v_mfma_f32_16x16x32_bf16 v[90:93], v[170:173], v[150:153], 0
	v_mfma_f32_16x16x32_bf16 v[94:97], v[174:177], v[150:153], 0
	v_mfma_f32_16x16x32_bf16 v[98:101], v[162:165], v[154:157], 0
	s_add_i32 m0, s60, s63
	v_mfma_f32_16x16x32_bf16 v[102:105], v[166:169], v[154:157], 0
	global_load_lds_dwordx4 v230, s[56:57]
	v_mfma_f32_16x16x32_bf16 v[106:109], v[170:173], v[154:157], 0
	v_mfma_f32_16x16x32_bf16 v[110:113], v[174:177], v[154:157], 0
	v_mfma_f32_16x16x32_bf16 v[114:117], v[162:165], v[158:161], 0
	v_mfma_f32_16x16x32_bf16 v[118:121], v[166:169], v[158:161], 0
	v_mfma_f32_16x16x32_bf16 v[122:125], v[170:173], v[158:161], 0
	global_load_lds_dwordx4 v231, s[56:57] offset:1024
	v_mfma_f32_16x16x32_bf16 v[126:129], v[174:177], v[158:161], 0
	s_setprio 0
	s_add_i32 s60, s60, 0x6000
	s_cmp_eq_u32 s60, 0x12000
	s_cselect_b32 s60, 0, s60
	s_add_u32 s54, s54, s72
	s_addc_u32 s55, s55, 0
	s_add_u32 s56, s56, s73
	s_addc_u32 s57, s57, 0
	s_add_i32 s61, s61, 0x6000
	s_cmp_eq_u32 s61, 0x12000
	s_cselect_b32 s61, 0, s61
	s_waitcnt lgkmcnt(0)
	v_add_u32_e32 v240, s61, v238
	v_add_u32_e32 v241, s61, v239
	s_setprio 1
	v_mfma_f32_16x16x32_bf16 v[2:5], v[210:213], v[178:181], v[2:5]
	v_mfma_f32_16x16x32_bf16 v[6:9], v[214:217], v[178:181], v[6:9]
	v_mfma_f32_16x16x32_bf16 v[10:13], v[218:221], v[178:181], v[10:13]
	v_mfma_f32_16x16x32_bf16 v[14:17], v[222:225], v[178:181], v[14:17]
	s_waitcnt vmcnt(6)
	s_barrier
	v_mfma_f32_16x16x32_bf16 v[18:21], v[210:213], v[182:185], v[18:21]
	s_add_i32 m0, s60, s62
	v_mfma_f32_16x16x32_bf16 v[22:25], v[214:217], v[182:185], v[22:25]
	global_load_lds_dwordx4 v226, s[54:55]
	v_mfma_f32_16x16x32_bf16 v[26:29], v[218:221], v[182:185], v[26:29]
	v_mfma_f32_16x16x32_bf16 v[30:33], v[222:225], v[182:185], v[30:33]
	v_mfma_f32_16x16x32_bf16 v[34:37], v[210:213], v[186:189], v[34:37]
	ds_read_b128 v[162:165], v241 offset:0
	v_mfma_f32_16x16x32_bf16 v[38:41], v[214:217], v[186:189], v[38:41]
	ds_read_b128 v[166:169], v241 offset:256
	v_mfma_f32_16x16x32_bf16 v[42:45], v[218:221], v[186:189], v[42:45]
	ds_read_b128 v[170:173], v241 offset:512
	global_load_lds_dwordx4 v226, s[54:55] offset:1024
	v_mfma_f32_16x16x32_bf16 v[46:49], v[222:225], v[186:189], v[46:49]
	ds_read_b128 v[174:177], v241 offset:768
	v_mfma_f32_16x16x32_bf16 v[50:53], v[210:213], v[190:193], v[50:53]
	ds_read_b128 v[130:133], v240 offset:0
	v_mfma_f32_16x16x32_bf16 v[54:57], v[214:217], v[190:193], v[54:57]
	ds_read_b128 v[134:137], v240 offset:1024
	v_mfma_f32_16x16x32_bf16 v[58:61], v[218:221], v[190:193], v[58:61]
	ds_read_b128 v[138:141], v240 offset:2048
	v_mfma_f32_16x16x32_bf16 v[62:65], v[222:225], v[190:193], v[62:65]
	ds_read_b128 v[142:145], v240 offset:3072
	global_load_lds_dwordx4 v226, s[54:55] offset:2048
	v_mfma_f32_16x16x32_bf16 v[66:69], v[210:213], v[194:197], v[66:69]
	ds_read_b128 v[146:149], v240 offset:4096
	v_mfma_f32_16x16x32_bf16 v[70:73], v[214:217], v[194:197], v[70:73]
	ds_read_b128 v[150:153], v240 offset:5120
	v_mfma_f32_16x16x32_bf16 v[74:77], v[218:221], v[194:197], v[74:77]
	ds_read_b128 v[154:157], v240 offset:6144
	v_mfma_f32_16x16x32_bf16 v[78:81], v[222:225], v[194:197], v[78:81]
	ds_read_b128 v[158:161], v240 offset:7168
	v_mfma_f32_16x16x32_bf16 v[82:85], v[210:213], v[198:201], v[82:85]
	global_load_lds_dwordx4 v226, s[54:55] offset:3072
	v_mfma_f32_16x16x32_bf16 v[86:89], v[214:217], v[198:201], v[86:89]
	v_mfma_f32_16x16x32_bf16 v[90:93], v[218:221], v[198:201], v[90:93]
	v_mfma_f32_16x16x32_bf16 v[94:97], v[222:225], v[198:201], v[94:97]
	v_mfma_f32_16x16x32_bf16 v[98:101], v[210:213], v[202:205], v[98:101]
	s_add_i32 m0, s60, s63
	v_mfma_f32_16x16x32_bf16 v[102:105], v[214:217], v[202:205], v[102:105]
	global_load_lds_dwordx4 v230, s[56:57]
	v_mfma_f32_16x16x32_bf16 v[106:109], v[218:221], v[202:205], v[106:109]
	v_mfma_f32_16x16x32_bf16 v[110:113], v[222:225], v[202:205], v[110:113]
	v_mfma_f32_16x16x32_bf16 v[114:117], v[210:213], v[206:209], v[114:117]
	v_mfma_f32_16x16x32_bf16 v[118:121], v[214:217], v[206:209], v[118:121]
	v_mfma_f32_16x16x32_bf16 v[122:125], v[218:221], v[206:209], v[122:125]
	global_load_lds_dwordx4 v231, s[56:57] offset:1024
	v_mfma_f32_16x16x32_bf16 v[126:129], v[222:225], v[206:209], v[126:129]
	s_setprio 0
	s_add_i32 s60, s60, 0x6000
	s_cmp_eq_u32 s60, 0x12000
	s_cselect_b32 s60, 0, s60
	s_add_u32 s54, s54, s72
	s_addc_u32 s55, s55, 0
	s_add_u32 s56, s56, s73
	s_addc_u32 s57, s57, 0
	s_add_i32 s61, s61, 0x6000
	s_cmp_eq_u32 s61, 0x12000
	s_cselect_b32 s61, 0, s61
	s_branch .Lgy_main

.Lgy_nn_b:
	s_waitcnt lgkmcnt(0)
	v_add_u32_e32 v240, s61, v238
	v_add_u32_e32 v241, s61, v239
	s_setprio 1
	v_mfma_f32_16x16x32_bf16 v[2:5], v[162:165], v[130:133], 0
	v_mfma_f32_16x16x32_bf16 v[6:9], v[166:169], v[130:133], 0
	v_mfma_f32_16x16x32_bf16 v[10:13], v[170:173], v[130:133], 0
	v_mfma_f32_16x16x32_bf16 v[14:17], v[174:177], v[130:133], 0
	s_waitcnt vmcnt(22)
	s_barrier
	v_mfma_f32_16x16x32_bf16 v[18:21], v[162:165], v[134:137], 0
	s_add_i32 m0, s60, s62
	v_mfma_f32_16x16x32_bf16 v[22:25], v[166:169], v[134:137], 0
	global_load_lds_dwordx4 v226, s[54:55]
	v_mfma_f32_16x16x32_bf16 v[26:29], v[170:173], v[134:137], 0
	v_mfma_f32_16x16x32_bf16 v[30:33], v[174:177], v[134:137], 0
	v_mfma_f32_16x16x32_bf16 v[34:37], v[162:165], v[138:141], 0
	ds_read_b128 v[210:213], v241 offset:0
	v_mfma_f32_16x16x32_bf16 v[38:41], v[166:169], v[138:141], 0
	ds_read_b128 v[214:217], v241 offset:256
	v_mfma_f32_16x16x32_bf16 v[42:45], v[170:173], v[138:141], 0
	ds_read_b128 v[218:221], v241 offset:512
	global_load_lds_dwordx4 v226, s[54:55] offset:1024
	v_mfma_f32_16x16x32_bf16 v[46:49], v[174:177], v[138:141], 0
	ds_read_b128 v[222:225], v241 offset:768
	v_mfma_f32_16x16x32_bf16 v[50:53], v[162:165], v[142:145], 0
	ds_read_b128 v[178:181], v240 offset:0
	v_mfma_f32_16x16x32_bf16 v[54:57], v[166:169], v[142:145], 0
	ds_read_b128 v[182:185], v240 offset:1024
	v_mfma_f32_16x16x32_bf16 v[58:61], v[170:173], v[142:145], 0
	ds_read_b128 v[186:189], v240 offset:2048
	v_mfma_f32_16x16x32_bf16 v[62:65], v[174:177], v[142:145], 0
	ds_read_b128 v[190:193], v240 offset:3072
	global_load_lds_dwordx4 v226, s[54:55] offset:2048
	v_mfma_f32_16x16x32_bf16 v[66:69], v[162:165], v[146:149], 0
	ds_read_b128 v[194:197], v240 offset:4096
	v_mfma_f32_16x16x32_bf16 v[70:73], v[166:169], v[146:149], 0
	ds_read_b128 v[198:201], v240 offset:5120
	v_mfma_f32_16x16x32_bf16 v[74:77], v[170:173], v[146:149], 0
	ds_read_b128 v[202:205], v240 offset:6144
	v_mfma_f32_16x16x32_bf16 v[78:81], v[174:177], v[146:149], 0
	ds_read_b128 v[206:209], v240 offset:7168
	v_mfma_f32_16x16x32_bf16 v[82:85], v[162:165], v[150:153], 0
	global_load_lds_dwordx4 v226, s[54:55] offset:3072
	v_mfma_f32_16x16x32_bf16 v[86:89], v[166:169], v[150:153], 0
	v_mfma_f32_16x16x32_bf16 v[90:93], v[170:173], v[150:153], 0
	v_mfma_f32_16x16x32_bf16 v[94:97], v[174:177], v[150:153], 0
	v_mfma_f32_16x16x32_bf16 v[98:101], v[162:165], v[154:157], 0
	s_add_i32 m0, s60, s63
	v_mfma_f32_16x16x32_bf16 v[102:105], v[166:169], v[154:157], 0
	global_load_lds_dwordx4 v230, s[56:57]
	v_mfma_f32_16x16x32_bf16 v[106:109], v[170:173], v[154:157], 0
	v_mfma_f32_16x16x32_bf16 v[110:113], v[174:177], v[154:157], 0
	v_mfma_f32_16x16x32_bf16 v[114:117], v[162:165], v[158:161], 0
	v_mfma_f32_16x16x32_bf16 v[118:121], v[166:169], v[158:161], 0
	v_mfma_f32_16x16x32_bf16 v[122:125], v[170:173], v[158:161], 0
	global_load_lds_dwordx4 v231, s[56:57] offset:1024
	v_mfma_f32_16x16x32_bf16 v[126:129], v[174:177], v[158:161], 0
	s_setprio 0
	s_add_i32 s60, s60, 0x6000
	s_cmp_eq_u32 s60, 0x12000
	s_cselect_b32 s60, 0, s60
	s_add_u32 s54, s54, s72
	s_addc_u32 s55, s55, 0
	s_add_u32 s56, s56, s73
	s_addc_u32 s57, s57, 0
	s_add_i32 s61, s61, 0x6000
	s_cmp_eq_u32 s61, 0x12000
	s_cselect_b32 s61, 0, s61
	s_waitcnt lgkmcnt(0)
	v_add_u32_e32 v240, s61, v238
	v_add_u32_e32 v241, s61, v239
	s_setprio 1
	v_mfma_f32_16x16x32_bf16 v[2:5], v[210:213], v[178:181], v[2:5]
	v_mfma_f32_16x16x32_bf16 v[6:9], v[214:217], v[178:181], v[6:9]
	v_mfma_f32_16x16x32_bf16 v[10:13], v[218:221], v[178:181], v[10:13]
	v_mfma_f32_16x16x32_bf16 v[14:17], v[222:225], v[178:181], v[14:17]
	s_waitcnt vmcnt(22)
	s_barrier
	v_mfma_f32_16x16x32_bf16 v[18:21], v[210:213], v[182:185], v[18:21]
	s_add_i32 m0, s60, s62
	v_mfma_f32_16x16x32_bf16 v[22:25], v[214:217], v[182:185], v[22:25]
	global_load_lds_dwordx4 v226, s[54:55]
	v_mfma_f32_16x16x32_bf16 v[26:29], v[218:221], v[182:185], v[26:29]
	v_mfma_f32_16x16x32_bf16 v[30:33], v[222:225], v[182:185], v[30:33]
	v_mfma_f32_16x16x32_bf16 v[34:37], v[210:213], v[186:189], v[34:37]
	ds_read_b128 v[162:165], v241 offset:0
	v_mfma_f32_16x16x32_bf16 v[38:41], v[214:217], v[186:189], v[38:41]
	ds_read_b128 v[166:169], v241 offset:256
	v_mfma_f32_16x16x32_bf16 v[42:45], v[218:221], v[186:189], v[42:45]
	ds_read_b128 v[170:173], v241 offset:512
	global_load_lds_dwordx4 v226, s[54:55] offset:1024
	v_mfma_f32_16x16x32_bf16 v[46:49], v[222:225], v[186:189], v[46:49]
	ds_read_b128 v[174:177], v241 offset:768
	v_mfma_f32_16x16x32_bf16 v[50:53], v[210:213], v[190:193], v[50:53]
	ds_read_b128 v[130:133], v240 offset:0
	v_mfma_f32_16x16x32_bf16 v[54:57], v[214:217], v[190:193], v[54:57]
	ds_read_b128 v[134:137], v240 offset:1024
	v_mfma_f32_16x16x32_bf16 v[58:61], v[218:221], v[190:193], v[58:61]
	ds_read_b128 v[138:141], v240 offset:2048
	v_mfma_f32_16x16x32_bf16 v[62:65], v[222:225], v[190:193], v[62:65]
	ds_read_b128 v[142:145], v240 offset:3072
	global_load_lds_dwordx4 v226, s[54:55] offset:2048
	v_mfma_f32_16x16x32_bf16 v[66:69], v[210:213], v[194:197], v[66:69]
	ds_read_b128 v[146:149], v240 offset:4096
	v_mfma_f32_16x16x32_bf16 v[70:73], v[214:217], v[194:197], v[70:73]
	ds_read_b128 v[150:153], v240 offset:5120
	v_mfma_f32_16x16x32_bf16 v[74:77], v[218:221], v[194:197], v[74:77]
	ds_read_b128 v[154:157], v240 offset:6144
	v_mfma_f32_16x16x32_bf16 v[78:81], v[222:225], v[194:197], v[78:81]
	ds_read_b128 v[158:161], v240 offset:7168
	v_mfma_f32_16x16x32_bf16 v[82:85], v[210:213], v[198:201], v[82:85]
	global_load_lds_dwordx4 v226, s[54:55] offset:3072
	v_mfma_f32_16x16x32_bf16 v[86:89], v[214:217], v[198:201], v[86:89]
	v_mfma_f32_16x16x32_bf16 v[90:93], v[218:221], v[198:201], v[90:93]
	v_mfma_f32_16x16x32_bf16 v[94:97], v[222:225], v[198:201], v[94:97]
	v_mfma_f32_16x16x32_bf16 v[98:101], v[210:213], v[202:205], v[98:101]
	s_add_i32 m0, s60, s63
	v_mfma_f32_16x16x32_bf16 v[102:105], v[214:217], v[202:205], v[102:105]
	global_load_lds_dwordx4 v230, s[56:57]
	v_mfma_f32_16x16x32_bf16 v[106:109], v[218:221], v[202:205], v[106:109]
	v_mfma_f32_16x16x32_bf16 v[110:113], v[222:225], v[202:205], v[110:113]
	v_mfma_f32_16x16x32_bf16 v[114:117], v[210:213], v[206:209], v[114:117]
	v_mfma_f32_16x16x32_bf16 v[118:121], v[214:217], v[206:209], v[118:121]
	v_mfma_f32_16x16x32_bf16 v[122:125], v[218:221], v[206:209], v[122:125]
	global_load_lds_dwordx4 v231, s[56:57] offset:1024
	v_mfma_f32_16x16x32_bf16 v[126:129], v[222:225], v[206:209], v[126:129]
	s_setprio 0
	s_add_i32 s60, s60, 0x6000
	s_cmp_eq_u32 s60, 0x12000
	s_cselect_b32 s60, 0, s60
	s_add_u32 s54, s54, s72
	s_addc_u32 s55, s55, 0
	s_add_u32 s56, s56, s73
	s_addc_u32 s57, s57, 0
	s_add_i32 s61, s61, 0x6000
	s_cmp_eq_u32 s61, 0x12000
	s_cselect_b32 s61, 0, s61

.Lgy_kloop:
	s_waitcnt lgkmcnt(0)
	v_add_u32_e32 v240, s61, v238
	v_add_u32_e32 v241, s61, v239
	s_setprio 1
	v_mfma_f32_16x16x32_bf16 v[2:5], v[162:165], v[130:133], v[2:5]
	v_mfma_f32_16x16x32_bf16 v[6:9], v[166:169], v[130:133], v[6:9]
	v_mfma_f32_16x16x32_bf16 v[10:13], v[170:173], v[130:133], v[10:13]
	v_mfma_f32_16x16x32_bf16 v[14:17], v[174:177], v[130:133], v[14:17]
	s_waitcnt vmcnt(6)
	s_barrier
	v_mfma_f32_16x16x32_bf16 v[18:21], v[162:165], v[134:137], v[18:21]
	s_add_i32 m0, s60, s62
	v_mfma_f32_16x16x32_bf16 v[22:25], v[166:169], v[134:137], v[22:25]
	global_load_lds_dwordx4 v226, s[54:55]
	v_mfma_f32_16x16x32_bf16 v[26:29], v[170:173], v[134:137], v[26:29]
	v_mfma_f32_16x16x32_bf16 v[30:33], v[174:177], v[134:137], v[30:33]
	v_mfma_f32_16x16x32_bf16 v[34:37], v[162:165], v[138:141], v[34:37]
	ds_read_b128 v[210:213], v241 offset:0
	v_mfma_f32_16x16x32_bf16 v[38:41], v[166:169], v[138:141], v[38:41]
	ds_read_b128 v[214:217], v241 offset:256
	v_mfma_f32_16x16x32_bf16 v[42:45], v[170:173], v[138:141], v[42:45]
	ds_read_b128 v[218:221], v241 offset:512
	global_load_lds_dwordx4 v226, s[54:55] offset:1024
	v_mfma_f32_16x16x32_bf16 v[46:49], v[174:177], v[138:141], v[46:49]
	ds_read_b128 v[222:225], v241 offset:768
	v_mfma_f32_16x16x32_bf16 v[50:53], v[162:165], v[142:145], v[50:53]
	ds_read_b128 v[178:181], v240 offset:0
	v_mfma_f32_16x16x32_bf16 v[54:57], v[166:169], v[142:145], v[54:57]
	ds_read_b128 v[182:185], v240 offset:1024
	v_mfma_f32_16x16x32_bf16 v[58:61], v[170:173], v[142:145], v[58:61]
	ds_read_b128 v[186:189], v240 offset:2048
	v_mfma_f32_16x16x32_bf16 v[62:65], v[174:177], v[142:145], v[62:65]
	ds_read_b128 v[190:193], v240 offset:3072
	global_load_lds_dwordx4 v226, s[54:55] offset:2048
	v_mfma_f32_16x16x32_bf16 v[66:69], v[162:165], v[146:149], v[66:69]
	ds_read_b128 v[194:197], v240 offset:4096
	v_mfma_f32_16x16x32_bf16 v[70:73], v[166:169], v[146:149], v[70:73]
	ds_read_b128 v[198:201], v240 offset:5120
	v_mfma_f32_16x16x32_bf16 v[74:77], v[170:173], v[146:149], v[74:77]
	ds_read_b128 v[202:205], v240 offset:6144
	v_mfma_f32_16x16x32_bf16 v[78:81], v[174:177], v[146:149], v[78:81]
	ds_read_b128 v[206:209], v240 offset:7168
	v_mfma_f32_16x16x32_bf16 v[82:85], v[162:165], v[150:153], v[82:85]
	global_load_lds_dwordx4 v226, s[54:55] offset:3072
	v_mfma_f32_16x16x32_bf16 v[86:89], v[166:169], v[150:153], v[86:89]
	v_mfma_f32_16x16x32_bf16 v[90:93], v[170:173], v[150:153], v[90:93]
	v_mfma_f32_16x16x32_bf16 v[94:97], v[174:177], v[150:153], v[94:97]
	v_mfma_f32_16x16x32_bf16 v[98:101], v[162:165], v[154:157], v[98:101]
	s_add_i32 m0, s60, s63
	v_mfma_f32_16x16x32_bf16 v[102:105], v[166:169], v[154:157], v[102:105]
	global_load_lds_dwordx4 v230, s[56:57]
	v_mfma_f32_16x16x32_bf16 v[106:109], v[170:173], v[154:157], v[106:109]
	v_mfma_f32_16x16x32_bf16 v[110:113], v[174:177], v[154:157], v[110:113]
	v_mfma_f32_16x16x32_bf16 v[114:117], v[162:165], v[158:161], v[114:117]
	v_mfma_f32_16x16x32_bf16 v[118:121], v[166:169], v[158:161], v[118:121]
	v_mfma_f32_16x16x32_bf16 v[122:125], v[170:173], v[158:161], v[122:125]
	global_load_lds_dwordx4 v231, s[56:57] offset:1024
	v_mfma_f32_16x16x32_bf16 v[126:129], v[174:177], v[158:161], v[126:129]
	s_setprio 0
	s_add_i32 s60, s60, 0x6000
	s_cmp_eq_u32 s60, 0x12000
	s_cselect_b32 s60, 0, s60
	s_add_u32 s54, s54, s72
	s_addc_u32 s55, s55, 0
	s_add_u32 s56, s56, s73
	s_addc_u32 s57, s57, 0
	s_add_i32 s61, s61, 0x6000
	s_cmp_eq_u32 s61, 0x12000
	s_cselect_b32 s61, 0, s61
	s_waitcnt lgkmcnt(0)
	v_add_u32_e32 v240, s61, v238
	v_add_u32_e32 v241, s61, v239
	s_setprio 1
	v_mfma_f32_16x16x32_bf16 v[2:5], v[210:213], v[178:181], v[2:5]
	v_mfma_f32_16x16x32_bf16 v[6:9], v[214:217], v[178:181], v[6:9]
	v_mfma_f32_16x16x32_bf16 v[10:13], v[218:221], v[178:181], v[10:13]
	v_mfma_f32_16x16x32_bf16 v[14:17], v[222:225], v[178:181], v[14:17]
	s_waitcnt vmcnt(6)
	s_barrier
	v_mfma_f32_16x16x32_bf16 v[18:21], v[210:213], v[182:185], v[18:21]
	s_add_i32 m0, s60, s62
	v_mfma_f32_16x16x32_bf16 v[22:25], v[214:217], v[182:185], v[22:25]
	global_load_lds_dwordx4 v226, s[54:55]
	v_mfma_f32_16x16x32_bf16 v[26:29], v[218:221], v[182:185], v[26:29]
	v_mfma_f32_16x16x32_bf16 v[30:33], v[222:225], v[182:185], v[30:33]
	v_mfma_f32_16x16x32_bf16 v[34:37], v[210:213], v[186:189], v[34:37]
	ds_read_b128 v[162:165], v241 offset:0
	v_mfma_f32_16x16x32_bf16 v[38:41], v[214:217], v[186:189], v[38:41]
	ds_read_b128 v[166:169], v241 offset:256
	v_mfma_f32_16x16x32_bf16 v[42:45], v[218:221], v[186:189], v[42:45]
	ds_read_b128 v[170:173], v241 offset:512
	global_load_lds_dwordx4 v226, s[54:55] offset:1024
	v_mfma_f32_16x16x32_bf16 v[46:49], v[222:225], v[186:189], v[46:49]
	ds_read_b128 v[174:177], v241 offset:768
	v_mfma_f32_16x16x32_bf16 v[50:53], v[210:213], v[190:193], v[50:53]
	ds_read_b128 v[130:133], v240 offset:0
	v_mfma_f32_16x16x32_bf16 v[54:57], v[214:217], v[190:193], v[54:57]
	ds_read_b128 v[134:137], v240 offset:1024
	v_mfma_f32_16x16x32_bf16 v[58:61], v[218:221], v[190:193], v[58:61]
	ds_read_b128 v[138:141], v240 offset:2048
	v_mfma_f32_16x16x32_bf16 v[62:65], v[222:225], v[190:193], v[62:65]
	ds_read_b128 v[142:145], v240 offset:3072
	global_load_lds_dwordx4 v226, s[54:55] offset:2048
	v_mfma_f32_16x16x32_bf16 v[66:69], v[210:213], v[194:197], v[66:69]
	ds_read_b128 v[146:149], v240 offset:4096
	v_mfma_f32_16x16x32_bf16 v[70:73], v[214:217], v[194:197], v[70:73]
	ds_read_b128 v[150:153], v240 offset:5120
	v_mfma_f32_16x16x32_bf16 v[74:77], v[218:221], v[194:197], v[74:77]
	ds_read_b128 v[154:157], v240 offset:6144
	v_mfma_f32_16x16x32_bf16 v[78:81], v[222:225], v[194:197], v[78:81]
	ds_read_b128 v[158:161], v240 offset:7168
	v_mfma_f32_16x16x32_bf16 v[82:85], v[210:213], v[198:201], v[82:85]
	global_load_lds_dwordx4 v226, s[54:55] offset:3072
	v_mfma_f32_16x16x32_bf16 v[86:89], v[214:217], v[198:201], v[86:89]
	v_mfma_f32_16x16x32_bf16 v[90:93], v[218:221], v[198:201], v[90:93]
	v_mfma_f32_16x16x32_bf16 v[94:97], v[222:225], v[198:201], v[94:97]
	v_mfma_f32_16x16x32_bf16 v[98:101], v[210:213], v[202:205], v[98:101]
	s_add_i32 m0, s60, s63
	v_mfma_f32_16x16x32_bf16 v[102:105], v[214:217], v[202:205], v[102:105]
	global_load_lds_dwordx4 v230, s[56:57]
	v_mfma_f32_16x16x32_bf16 v[106:109], v[218:221], v[202:205], v[106:109]
	v_mfma_f32_16x16x32_bf16 v[110:113], v[222:225], v[202:205], v[110:113]
	v_mfma_f32_16x16x32_bf16 v[114:117], v[210:213], v[206:209], v[114:117]
	v_mfma_f32_16x16x32_bf16 v[118:121], v[214:217], v[206:209], v[118:121]
	v_mfma_f32_16x16x32_bf16 v[122:125], v[218:221], v[206:209], v[122:125]
	global_load_lds_dwordx4 v231, s[56:57] offset:1024
	v_mfma_f32_16x16x32_bf16 v[126:129], v[222:225], v[206:209], v[126:129]
	s_setprio 0
	s_add_i32 s60, s60, 0x6000
	s_cmp_eq_u32 s60, 0x12000
	s_cselect_b32 s60, 0, s60
	s_add_u32 s54, s54, s72
	s_addc_u32 s55, s55, 0
	s_add_u32 s56, s56, s73
	s_addc_u32 s57, s57, 0
	s_add_i32 s61, s61, 0x6000
	s_cmp_eq_u32 s61, 0x12000
	s_cselect_b32 s61, 0, s61
	s_add_i32 s40, s40, -1
	s_cmp_lg_u32 s40, 0
	s_cbranch_scc1 .Lgy_kloop
.Lgy_kdone:
	s_cmp_eq_u32 s37, 0
	s_cbranch_scc1 .Lgy_tail_last
	s_waitcnt lgkmcnt(0)
	v_add_u32_e32 v240, s61, v238
	v_add_u32_e32 v241, s61, v239
	s_setprio 1
	v_mfma_f32_16x16x32_bf16 v[2:5], v[162:165], v[130:133], v[2:5]
	v_mfma_f32_16x16x32_bf16 v[6:9], v[166:169], v[130:133], v[6:9]
	v_mfma_f32_16x16x32_bf16 v[10:13], v[170:173], v[130:133], v[10:13]
	v_mfma_f32_16x16x32_bf16 v[14:17], v[174:177], v[130:133], v[14:17]
	s_waitcnt vmcnt(6)
	s_barrier
	v_mfma_f32_16x16x32_bf16 v[18:21], v[162:165], v[134:137], v[18:21]
	s_add_i32 m0, s60, s62
	v_mfma_f32_16x16x32_bf16 v[22:25], v[166:169], v[134:137], v[22:25]
	global_load_lds_dwordx4 v226, s[54:55]
	v_mfma_f32_16x16x32_bf16 v[26:29], v[170:173], v[134:137], v[26:29]
	v_mfma_f32_16x16x32_bf16 v[30:33], v[174:177], v[134:137], v[30:33]
	v_mfma_f32_16x16x32_bf16 v[34:37], v[162:165], v[138:141], v[34:37]
	ds_read_b128 v[210:213], v241 offset:0
	v_mfma_f32_16x16x32_bf16 v[38:41], v[166:169], v[138:141], v[38:41]
	ds_read_b128 v[214:217], v241 offset:256
	v_mfma_f32_16x16x32_bf16 v[42:45], v[170:173], v[138:141], v[42:45]
	ds_read_b128 v[218:221], v241 offset:512
	global_load_lds_dwordx4 v226, s[54:55] offset:1024
	v_mfma_f32_16x16x32_bf16 v[46:49], v[174:177], v[138:141], v[46:49]
	ds_read_b128 v[222:225], v241 offset:768
	v_mfma_f32_16x16x32_bf16 v[50:53], v[162:165], v[142:145], v[50:53]
	ds_read_b128 v[178:181], v240 offset:0
	v_mfma_f32_16x16x32_bf16 v[54:57], v[166:169], v[142:145], v[54:57]
	ds_read_b128 v[182:185], v240 offset:1024
	v_mfma_f32_16x16x32_bf16 v[58:61], v[170:173], v[142:145], v[58:61]
	ds_read_b128 v[186:189], v240 offset:2048
	v_mfma_f32_16x16x32_bf16 v[62:65], v[174:177], v[142:145], v[62:65]
	ds_read_b128 v[190:193], v240 offset:3072
	global_load_lds_dwordx4 v226, s[54:55] offset:2048
	v_mfma_f32_16x16x32_bf16 v[66:69], v[162:165], v[146:149], v[66:69]
	ds_read_b128 v[194:197], v240 offset:4096
	v_mfma_f32_16x16x32_bf16 v[70:73], v[166:169], v[146:149], v[70:73]
	ds_read_b128 v[198:201], v240 offset:5120
	v_mfma_f32_16x16x32_bf16 v[74:77], v[170:173], v[146:149], v[74:77]
	ds_read_b128 v[202:205], v240 offset:6144
	v_mfma_f32_16x16x32_bf16 v[78:81], v[174:177], v[146:149], v[78:81]
	ds_read_b128 v[206:209], v240 offset:7168
	v_mfma_f32_16x16x32_bf16 v[82:85], v[162:165], v[150:153], v[82:85]
	global_load_lds_dwordx4 v226, s[54:55] offset:3072
	v_mfma_f32_16x16x32_bf16 v[86:89], v[166:169], v[150:153], v[86:89]
	v_mfma_f32_16x16x32_bf16 v[90:93], v[170:173], v[150:153], v[90:93]
	v_mfma_f32_16x16x32_bf16 v[94:97], v[174:177], v[150:153], v[94:97]
	v_mfma_f32_16x16x32_bf16 v[98:101], v[162:165], v[154:157], v[98:101]
	s_add_i32 m0, s60, s63
	v_mfma_f32_16x16x32_bf16 v[102:105], v[166:169], v[154:157], v[102:105]
	global_load_lds_dwordx4 v230, s[56:57]
	v_mfma_f32_16x16x32_bf16 v[106:109], v[170:173], v[154:157], v[106:109]
	v_mfma_f32_16x16x32_bf16 v[110:113], v[174:177], v[154:157], v[110:113]
	v_mfma_f32_16x16x32_bf16 v[114:117], v[162:165], v[158:161], v[114:117]
	v_mfma_f32_16x16x32_bf16 v[118:121], v[166:169], v[158:161], v[118:121]
	v_mfma_f32_16x16x32_bf16 v[122:125], v[170:173], v[158:161], v[122:125]
	global_load_lds_dwordx4 v231, s[56:57] offset:1024
	v_mfma_f32_16x16x32_bf16 v[126:129], v[174:177], v[158:161], v[126:129]
	s_setprio 0
	s_add_i32 s60, s60, 0x6000
	s_cmp_eq_u32 s60, 0x12000
	s_cselect_b32 s60, 0, s60
	s_add_u32 s54, s54, s72
	s_addc_u32 s55, s55, 0
	s_add_u32 s56, s56, s73
	s_addc_u32 s57, s57, 0
	s_add_i32 s61, s61, 0x6000
	s_cmp_eq_u32 s61, 0x12000
	s_cselect_b32 s61, 0, s61
	v_mov_b32_e32 v226, v232
	v_mov_b32_e32 v230, v236
	v_mov_b32_e32 v231, v237
	s_mov_b64 s[54:55], s[48:49]
	s_mov_b64 s[56:57], s[50:51]
	s_waitcnt lgkmcnt(0)
	v_add_u32_e32 v240, s61, v238
	v_add_u32_e32 v241, s61, v239
	s_setprio 1
	v_mfma_f32_16x16x32_bf16 v[2:5], v[210:213], v[178:181], v[2:5]
	v_mfma_f32_16x16x32_bf16 v[6:9], v[214:217], v[178:181], v[6:9]
	v_mfma_f32_16x16x32_bf16 v[10:13], v[218:221], v[178:181], v[10:13]
	v_mfma_f32_16x16x32_bf16 v[14:17], v[222:225], v[178:181], v[14:17]
	s_waitcnt vmcnt(6)
	s_barrier
	v_mfma_f32_16x16x32_bf16 v[18:21], v[210:213], v[182:185], v[18:21]
	s_add_i32 m0, s60, s62
	v_mfma_f32_16x16x32_bf16 v[22:25], v[214:217], v[182:185], v[22:25]
	global_load_lds_dwordx4 v226, s[54:55]
	v_mfma_f32_16x16x32_bf16 v[26:29], v[218:221], v[182:185], v[26:29]
	v_mfma_f32_16x16x32_bf16 v[30:33], v[222:225], v[182:185], v[30:33]
	v_mfma_f32_16x16x32_bf16 v[34:37], v[210:213], v[186:189], v[34:37]
	ds_read_b128 v[162:165], v241 offset:0
	v_mfma_f32_16x16x32_bf16 v[38:41], v[214:217], v[186:189], v[38:41]
	ds_read_b128 v[166:169], v241 offset:256
	v_mfma_f32_16x16x32_bf16 v[42:45], v[218:221], v[186:189], v[42:45]
	ds_read_b128 v[170:173], v241 offset:512
	global_load_lds_dwordx4 v226, s[54:55] offset:1024
	v_mfma_f32_16x16x32_bf16 v[46:49], v[222:225], v[186:189], v[46:49]
	ds_read_b128 v[174:177], v241 offset:768
	v_mfma_f32_16x16x32_bf16 v[50:53], v[210:213], v[190:193], v[50:53]
	ds_read_b128 v[130:133], v240 offset:0
	v_mfma_f32_16x16x32_bf16 v[54:57], v[214:217], v[190:193], v[54:57]
	ds_read_b128 v[134:137], v240 offset:1024
	v_mfma_f32_16x16x32_bf16 v[58:61], v[218:221], v[190:193], v[58:61]
	ds_read_b128 v[138:141], v240 offset:2048
	v_mfma_f32_16x16x32_bf16 v[62:65], v[222:225], v[190:193], v[62:65]
	ds_read_b128 v[142:145], v240 offset:3072
	global_load_lds_dwordx4 v226, s[54:55] offset:2048
	v_mfma_f32_16x16x32_bf16 v[66:69], v[210:213], v[194:197], v[66:69]
	ds_read_b128 v[146:149], v240 offset:4096
	v_mfma_f32_16x16x32_bf16 v[70:73], v[214:217], v[194:197], v[70:73]
	ds_read_b128 v[150:153], v240 offset:5120
	v_mfma_f32_16x16x32_bf16 v[74:77], v[218:221], v[194:197], v[74:77]
	ds_read_b128 v[154:157], v240 offset:6144
	v_mfma_f32_16x16x32_bf16 v[78:81], v[222:225], v[194:197], v[78:81]
	ds_read_b128 v[158:161], v240 offset:7168
	v_mfma_f32_16x16x32_bf16 v[82:85], v[210:213], v[198:201], v[82:85]
	global_load_lds_dwordx4 v226, s[54:55] offset:3072
	v_mfma_f32_16x16x32_bf16 v[86:89], v[214:217], v[198:201], v[86:89]
	v_mfma_f32_16x16x32_bf16 v[90:93], v[218:221], v[198:201], v[90:93]
	v_mfma_f32_16x16x32_bf16 v[94:97], v[222:225], v[198:201], v[94:97]
	v_mfma_f32_16x16x32_bf16 v[98:101], v[210:213], v[202:205], v[98:101]
	s_add_i32 m0, s60, s63
	v_mfma_f32_16x16x32_bf16 v[102:105], v[214:217], v[202:205], v[102:105]
	global_load_lds_dwordx4 v230, s[56:57]
	v_mfma_f32_16x16x32_bf16 v[106:109], v[218:221], v[202:205], v[106:109]
	v_mfma_f32_16x16x32_bf16 v[110:113], v[222:225], v[202:205], v[110:113]
	v_mfma_f32_16x16x32_bf16 v[114:117], v[210:213], v[206:209], v[114:117]
	v_mfma_f32_16x16x32_bf16 v[118:121], v[214:217], v[206:209], v[118:121]
	v_mfma_f32_16x16x32_bf16 v[122:125], v[218:221], v[206:209], v[122:125]
	global_load_lds_dwordx4 v231, s[56:57] offset:1024
	v_mfma_f32_16x16x32_bf16 v[126:129], v[222:225], v[206:209], v[126:129]
	s_setprio 0
	s_add_i32 s60, s60, 0x6000
	s_cmp_eq_u32 s60, 0x12000
	s_cselect_b32 s60, 0, s60
	s_add_u32 s54, s54, s72
	s_addc_u32 s55, s55, 0
	s_add_u32 s56, s56, s73
	s_addc_u32 s57, s57, 0
	s_add_i32 s61, s61, 0x6000
	s_cmp_eq_u32 s61, 0x12000
	s_cselect_b32 s61, 0, s61
	s_waitcnt lgkmcnt(0)
	v_add_u32_e32 v240, s61, v238
	v_add_u32_e32 v241, s61, v239
	s_setprio 1
	v_mfma_f32_16x16x32_bf16 v[2:5], v[162:165], v[130:133], v[2:5]
	v_mfma_f32_16x16x32_bf16 v[6:9], v[166:169], v[130:133], v[6:9]
	v_mfma_f32_16x16x32_bf16 v[10:13], v[170:173], v[130:133], v[10:13]
	v_mfma_f32_16x16x32_bf16 v[14:17], v[174:177], v[130:133], v[14:17]
	s_waitcnt vmcnt(6)
	s_barrier
	v_mfma_f32_16x16x32_bf16 v[18:21], v[162:165], v[134:137], v[18:21]
	s_add_i32 m0, s60, s62
	v_mfma_f32_16x16x32_bf16 v[22:25], v[166:169], v[134:137], v[22:25]
	global_load_lds_dwordx4 v226, s[54:55]
	v_mfma_f32_16x16x32_bf16 v[26:29], v[170:173], v[134:137], v[26:29]
	v_mfma_f32_16x16x32_bf16 v[30:33], v[174:177], v[134:137], v[30:33]
	v_mfma_f32_16x16x32_bf16 v[34:37], v[162:165], v[138:141], v[34:37]
	ds_read_b128 v[210:213], v241 offset:0
	v_mfma_f32_16x16x32_bf16 v[38:41], v[166:169], v[138:141], v[38:41]
	ds_read_b128 v[214:217], v241 offset:256
	v_mfma_f32_16x16x32_bf16 v[42:45], v[170:173], v[138:141], v[42:45]
	ds_read_b128 v[218:221], v241 offset:512
	global_load_lds_dwordx4 v226, s[54:55] offset:1024
	v_mfma_f32_16x16x32_bf16 v[46:49], v[174:177], v[138:141], v[46:49]
	ds_read_b128 v[222:225], v241 offset:768
	v_mfma_f32_16x16x32_bf16 v[50:53], v[162:165], v[142:145], v[50:53]
	ds_read_b128 v[178:181], v240 offset:0
	v_mfma_f32_16x16x32_bf16 v[54:57], v[166:169], v[142:145], v[54:57]
	ds_read_b128 v[182:185], v240 offset:1024
	v_mfma_f32_16x16x32_bf16 v[58:61], v[170:173], v[142:145], v[58:61]
	ds_read_b128 v[186:189], v240 offset:2048
	v_mfma_f32_16x16x32_bf16 v[62:65], v[174:177], v[142:145], v[62:65]
	ds_read_b128 v[190:193], v240 offset:3072
	global_load_lds_dwordx4 v226, s[54:55] offset:2048
	v_mfma_f32_16x16x32_bf16 v[66:69], v[162:165], v[146:149], v[66:69]
	ds_read_b128 v[194:197], v240 offset:4096
	v_mfma_f32_16x16x32_bf16 v[70:73], v[166:169], v[146:149], v[70:73]
	ds_read_b128 v[198:201], v240 offset:5120
	v_mfma_f32_16x16x32_bf16 v[74:77], v[170:173], v[146:149], v[74:77]
	ds_read_b128 v[202:205], v240 offset:6144
	v_mfma_f32_16x16x32_bf16 v[78:81], v[174:177], v[146:149], v[78:81]
	ds_read_b128 v[206:209], v240 offset:7168
	v_mfma_f32_16x16x32_bf16 v[82:85], v[162:165], v[150:153], v[82:85]
	global_load_lds_dwordx4 v226, s[54:55] offset:3072
	v_mfma_f32_16x16x32_bf16 v[86:89], v[166:169], v[150:153], v[86:89]
	v_mfma_f32_16x16x32_bf16 v[90:93], v[170:173], v[150:153], v[90:93]
	v_mfma_f32_16x16x32_bf16 v[94:97], v[174:177], v[150:153], v[94:97]
	v_mfma_f32_16x16x32_bf16 v[98:101], v[162:165], v[154:157], v[98:101]
	s_add_i32 m0, s60, s63
	v_mfma_f32_16x16x32_bf16 v[102:105], v[166:169], v[154:157], v[102:105]
	global_load_lds_dwordx4 v230, s[56:57]
	v_mfma_f32_16x16x32_bf16 v[106:109], v[170:173], v[154:157], v[106:109]
	v_mfma_f32_16x16x32_bf16 v[110:113], v[174:177], v[154:157], v[110:113]
	v_mfma_f32_16x16x32_bf16 v[114:117], v[162:165], v[158:161], v[114:117]
	v_mfma_f32_16x16x32_bf16 v[118:121], v[166:169], v[158:161], v[118:121]
	v_mfma_f32_16x16x32_bf16 v[122:125], v[170:173], v[158:161], v[122:125]
	global_load_lds_dwordx4 v231, s[56:57] offset:1024
	v_mfma_f32_16x16x32_bf16 v[126:129], v[174:177], v[158:161], v[126:129]
	s_setprio 0
	s_add_i32 s60, s60, 0x6000
	s_cmp_eq_u32 s60, 0x12000
	s_cselect_b32 s60, 0, s60
	s_add_u32 s54, s54, s72
	s_addc_u32 s55, s55, 0
	s_add_u32 s56, s56, s73
	s_addc_u32 s57, s57, 0
	s_add_i32 s61, s61, 0x6000
	s_cmp_eq_u32 s61, 0x12000
	s_cselect_b32 s61, 0, s61
	s_waitcnt lgkmcnt(0)
	v_add_u32_e32 v240, s61, v238
	v_add_u32_e32 v241, s61, v239
	s_setprio 1
	v_mfma_f32_16x16x32_bf16 v[2:5], v[210:213], v[178:181], v[2:5]
	v_mfma_f32_16x16x32_bf16 v[6:9], v[214:217], v[178:181], v[6:9]
	v_mfma_f32_16x16x32_bf16 v[10:13], v[218:221], v[178:181], v[10:13]
	v_mfma_f32_16x16x32_bf16 v[14:17], v[222:225], v[178:181], v[14:17]
	s_waitcnt vmcnt(6)
	s_barrier
	v_mfma_f32_16x16x32_bf16 v[18:21], v[210:213], v[182:185], v[18:21]
	s_add_i32 m0, s60, s62
	v_mfma_f32_16x16x32_bf16 v[22:25], v[214:217], v[182:185], v[22:25]
	global_load_lds_dwordx4 v226, s[54:55]
	v_mfma_f32_16x16x32_bf16 v[26:29], v[218:221], v[182:185], v[26:29]
	v_mfma_f32_16x16x32_bf16 v[30:33], v[222:225], v[182:185], v[30:33]
	v_mfma_f32_16x16x32_bf16 v[34:37], v[210:213], v[186:189], v[34:37]
	ds_read_b128 v[162:165], v241 offset:0
	v_mfma_f32_16x16x32_bf16 v[38:41], v[214:217], v[186:189], v[38:41]
	ds_read_b128 v[166:169], v241 offset:256
	v_mfma_f32_16x16x32_bf16 v[42:45], v[218:221], v[186:189], v[42:45]
	ds_read_b128 v[170:173], v241 offset:512
	global_load_lds_dwordx4 v226, s[54:55] offset:1024
	v_mfma_f32_16x16x32_bf16 v[46:49], v[222:225], v[186:189], v[46:49]
	ds_read_b128 v[174:177], v241 offset:768
	v_mfma_f32_16x16x32_bf16 v[50:53], v[210:213], v[190:193], v[50:53]
	ds_read_b128 v[130:133], v240 offset:0
	v_mfma_f32_16x16x32_bf16 v[54:57], v[214:217], v[190:193], v[54:57]
	ds_read_b128 v[134:137], v240 offset:1024
	v_mfma_f32_16x16x32_bf16 v[58:61], v[218:221], v[190:193], v[58:61]
	ds_read_b128 v[138:141], v240 offset:2048
	v_mfma_f32_16x16x32_bf16 v[62:65], v[222:225], v[190:193], v[62:65]
	ds_read_b128 v[142:145], v240 offset:3072
	global_load_lds_dwordx4 v226, s[54:55] offset:2048
	v_mfma_f32_16x16x32_bf16 v[66:69], v[210:213], v[194:197], v[66:69]
	ds_read_b128 v[146:149], v240 offset:4096
	v_mfma_f32_16x16x32_bf16 v[70:73], v[214:217], v[194:197], v[70:73]
	ds_read_b128 v[150:153], v240 offset:5120
	v_mfma_f32_16x16x32_bf16 v[74:77], v[218:221], v[194:197], v[74:77]
	ds_read_b128 v[154:157], v240 offset:6144
	v_mfma_f32_16x16x32_bf16 v[78:81], v[222:225], v[194:197], v[78:81]
	ds_read_b128 v[158:161], v240 offset:7168
	v_mfma_f32_16x16x32_bf16 v[82:85], v[210:213], v[198:201], v[82:85]
	global_load_lds_dwordx4 v226, s[54:55] offset:3072
	v_mfma_f32_16x16x32_bf16 v[86:89], v[214:217], v[198:201], v[86:89]
	v_mfma_f32_16x16x32_bf16 v[90:93], v[218:221], v[198:201], v[90:93]
	v_mfma_f32_16x16x32_bf16 v[94:97], v[222:225], v[198:201], v[94:97]
	v_mfma_f32_16x16x32_bf16 v[98:101], v[210:213], v[202:205], v[98:101]
	s_add_i32 m0, s60, s63
	v_mfma_f32_16x16x32_bf16 v[102:105], v[214:217], v[202:205], v[102:105]
	global_load_lds_dwordx4 v230, s[56:57]
	v_mfma_f32_16x16x32_bf16 v[106:109], v[218:221], v[202:205], v[106:109]
	v_mfma_f32_16x16x32_bf16 v[110:113], v[222:225], v[202:205], v[110:113]
	v_mfma_f32_16x16x32_bf16 v[114:117], v[210:213], v[206:209], v[114:117]
	v_mfma_f32_16x16x32_bf16 v[118:121], v[214:217], v[206:209], v[118:121]
	v_mfma_f32_16x16x32_bf16 v[122:125], v[218:221], v[206:209], v[122:125]
	global_load_lds_dwordx4 v231, s[56:57] offset:1024
	v_mfma_f32_16x16x32_bf16 v[126:129], v[222:225], v[206:209], v[126:129]
	s_setprio 0
	s_add_i32 s60, s60, 0x6000
	s_cmp_eq_u32 s60, 0x12000
	s_cselect_b32 s60, 0, s60
	s_add_u32 s54, s54, s72
	s_addc_u32 s55, s55, 0
	s_add_u32 s56, s56, s73
	s_addc_u32 s57, s57, 0
	s_add_i32 s61, s61, 0x6000
	s_cmp_eq_u32 s61, 0x12000
	s_cselect_b32 s61, 0, s61
	s_nop 7
	s_nop 1
	s_lshl_b32 s26, s35, 11
	s_lshl_b32 s27, s36, 1
	s_add_i32 s26, s26, s27
	s_add_u32 s18, s52, s26
	s_addc_u32 s19, s53, 0
	v_cvt_pk_bf16_f32 v2, v2, v3
	v_cvt_pk_bf16_f32 v3, v4, v5
	v_cvt_pk_bf16_f32 v4, v6, v7
	v_cvt_pk_bf16_f32 v5, v8, v9
	v_cvt_pk_bf16_f32 v6, v10, v11
	v_cvt_pk_bf16_f32 v7, v12, v13
	v_cvt_pk_bf16_f32 v8, v14, v15
	v_cvt_pk_bf16_f32 v9, v16, v17
	global_store_dwordx4 v242, v[2:5], s[18:19]
	global_store_dwordx4 v242, v[6:9], s[18:19] offset:16
	s_add_u32 s18, s18, 0x8000
	s_addc_u32 s19, s19, 0
	v_cvt_pk_bf16_f32 v18, v18, v19
	v_cvt_pk_bf16_f32 v19, v20, v21
	v_cvt_pk_bf16_f32 v20, v22, v23
	v_cvt_pk_bf16_f32 v21, v24, v25
	v_cvt_pk_bf16_f32 v22, v26, v27
	v_cvt_pk_bf16_f32 v23, v28, v29
	v_cvt_pk_bf16_f32 v24, v30, v31
	v_cvt_pk_bf16_f32 v25, v32, v33
	global_store_dwordx4 v242, v[18:21], s[18:19]
	global_store_dwordx4 v242, v[22:25], s[18:19] offset:16
	s_add_u32 s18, s18, 0x8000
	s_addc_u32 s19, s19, 0
	v_cvt_pk_bf16_f32 v34, v34, v35
	v_cvt_pk_bf16_f32 v35, v36, v37
	v_cvt_pk_bf16_f32 v36, v38, v39
	v_cvt_pk_bf16_f32 v37, v40, v41
	v_cvt_pk_bf16_f32 v38, v42, v43
	v_cvt_pk_bf16_f32 v39, v44, v45
	v_cvt_pk_bf16_f32 v40, v46, v47
	v_cvt_pk_bf16_f32 v41, v48, v49
	global_store_dwordx4 v242, v[34:37], s[18:19]
	global_store_dwordx4 v242, v[38:41], s[18:19] offset:16
	s_add_u32 s18, s18, 0x8000
	s_addc_u32 s19, s19, 0
	v_cvt_pk_bf16_f32 v50, v50, v51
	v_cvt_pk_bf16_f32 v51, v52, v53
	v_cvt_pk_bf16_f32 v52, v54, v55
	v_cvt_pk_bf16_f32 v53, v56, v57
	v_cvt_pk_bf16_f32 v54, v58, v59
	v_cvt_pk_bf16_f32 v55, v60, v61
	v_cvt_pk_bf16_f32 v56, v62, v63
	v_cvt_pk_bf16_f32 v57, v64, v65
	global_store_dwordx4 v242, v[50:53], s[18:19]
	global_store_dwordx4 v242, v[54:57], s[18:19] offset:16
	s_add_u32 s18, s18, 0x8000
	s_addc_u32 s19, s19, 0
	v_cvt_pk_bf16_f32 v66, v66, v67
	v_cvt_pk_bf16_f32 v67, v68, v69
	v_cvt_pk_bf16_f32 v68, v70, v71
	v_cvt_pk_bf16_f32 v69, v72, v73
	v_cvt_pk_bf16_f32 v70, v74, v75
	v_cvt_pk_bf16_f32 v71, v76, v77
	v_cvt_pk_bf16_f32 v72, v78, v79
	v_cvt_pk_bf16_f32 v73, v80, v81
	global_store_dwordx4 v242, v[66:69], s[18:19]
	global_store_dwordx4 v242, v[70:73], s[18:19] offset:16
	s_add_u32 s18, s18, 0x8000
	s_addc_u32 s19, s19, 0
	v_cvt_pk_bf16_f32 v82, v82, v83
	v_cvt_pk_bf16_f32 v83, v84, v85
	v_cvt_pk_bf16_f32 v84, v86, v87
	v_cvt_pk_bf16_f32 v85, v88, v89
	v_cvt_pk_bf16_f32 v86, v90, v91
	v_cvt_pk_bf16_f32 v87, v92, v93
	v_cvt_pk_bf16_f32 v88, v94, v95
	v_cvt_pk_bf16_f32 v89, v96, v97
	global_store_dwordx4 v242, v[82:85], s[18:19]
	global_store_dwordx4 v242, v[86:89], s[18:19] offset:16
	s_add_u32 s18, s18, 0x8000
	s_addc_u32 s19, s19, 0
	v_cvt_pk_bf16_f32 v98, v98, v99
	v_cvt_pk_bf16_f32 v99, v100, v101
	v_cvt_pk_bf16_f32 v100, v102, v103
	v_cvt_pk_bf16_f32 v101, v104, v105
	v_cvt_pk_bf16_f32 v102, v106, v107
	v_cvt_pk_bf16_f32 v103, v108, v109
	v_cvt_pk_bf16_f32 v104, v110, v111
	v_cvt_pk_bf16_f32 v105, v112, v113
	global_store_dwordx4 v242, v[98:101], s[18:19]
	global_store_dwordx4 v242, v[102:105], s[18:19] offset:16
	s_add_u32 s18, s18, 0x8000
	s_addc_u32 s19, s19, 0
	v_cvt_pk_bf16_f32 v114, v114, v115
	v_cvt_pk_bf16_f32 v115, v116, v117
	v_cvt_pk_bf16_f32 v116, v118, v119
	v_cvt_pk_bf16_f32 v117, v120, v121
	v_cvt_pk_bf16_f32 v118, v122, v123
	v_cvt_pk_bf16_f32 v119, v124, v125
	v_cvt_pk_bf16_f32 v120, v126, v127
	v_cvt_pk_bf16_f32 v121, v128, v129
	global_store_dwordx4 v242, v[114:117], s[18:19]
	global_store_dwordx4 v242, v[118:121], s[18:19] offset:16
	s_mov_b32 s34, s38
	s_mov_b32 s35, s30
	s_mov_b32 s36, s31
	s_branch .Lgy_tile
.Lgy_tail_last:
	s_waitcnt lgkmcnt(0)
	v_add_u32_e32 v240, s61, v238
	v_add_u32_e32 v241, s61, v239
	s_setprio 1
	v_mfma_f32_16x16x32_bf16 v[2:5], v[162:165], v[130:133], v[2:5]
	v_mfma_f32_16x16x32_bf16 v[6:9], v[166:169], v[130:133], v[6:9]
	v_mfma_f32_16x16x32_bf16 v[10:13], v[170:173], v[130:133], v[10:13]
	v_mfma_f32_16x16x32_bf16 v[14:17], v[174:177], v[130:133], v[14:17]
	s_waitcnt vmcnt(6)
	s_barrier
	v_mfma_f32_16x16x32_bf16 v[18:21], v[162:165], v[134:137], v[18:21]
	s_add_i32 m0, s60, s62
	v_mfma_f32_16x16x32_bf16 v[22:25], v[166:169], v[134:137], v[22:25]
	global_load_lds_dwordx4 v226, s[54:55]
	v_mfma_f32_16x16x32_bf16 v[26:29], v[170:173], v[134:137], v[26:29]
	v_mfma_f32_16x16x32_bf16 v[30:33], v[174:177], v[134:137], v[30:33]
	v_mfma_f32_16x16x32_bf16 v[34:37], v[162:165], v[138:141], v[34:37]
	ds_read_b128 v[210:213], v241 offset:0
	v_mfma_f32_16x16x32_bf16 v[38:41], v[166:169], v[138:141], v[38:41]
	ds_read_b128 v[214:217], v241 offset:256
	v_mfma_f32_16x16x32_bf16 v[42:45], v[170:173], v[138:141], v[42:45]
	ds_read_b128 v[218:221], v241 offset:512
	global_load_lds_dwordx4 v226, s[54:55] offset:1024
	v_mfma_f32_16x16x32_bf16 v[46:49], v[174:177], v[138:141], v[46:49]
	ds_read_b128 v[222:225], v241 offset:768
	v_mfma_f32_16x16x32_bf16 v[50:53], v[162:165], v[142:145], v[50:53]
	ds_read_b128 v[178:181], v240 offset:0
	v_mfma_f32_16x16x32_bf16 v[54:57], v[166:169], v[142:145], v[54:57]
	ds_read_b128 v[182:185], v240 offset:1024
	v_mfma_f32_16x16x32_bf16 v[58:61], v[170:173], v[142:145], v[58:61]
	ds_read_b128 v[186:189], v240 offset:2048
	v_mfma_f32_16x16x32_bf16 v[62:65], v[174:177], v[142:145], v[62:65]
	ds_read_b128 v[190:193], v240 offset:3072
	global_load_lds_dwordx4 v226, s[54:55] offset:2048
	v_mfma_f32_16x16x32_bf16 v[66:69], v[162:165], v[146:149], v[66:69]
	ds_read_b128 v[194:197], v240 offset:4096
	v_mfma_f32_16x16x32_bf16 v[70:73], v[166:169], v[146:149], v[70:73]
	ds_read_b128 v[198:201], v240 offset:5120
	v_mfma_f32_16x16x32_bf16 v[74:77], v[170:173], v[146:149], v[74:77]
	ds_read_b128 v[202:205], v240 offset:6144
	v_mfma_f32_16x16x32_bf16 v[78:81], v[174:177], v[146:149], v[78:81]
	ds_read_b128 v[206:209], v240 offset:7168
	v_mfma_f32_16x16x32_bf16 v[82:85], v[162:165], v[150:153], v[82:85]
	global_load_lds_dwordx4 v226, s[54:55] offset:3072
	v_mfma_f32_16x16x32_bf16 v[86:89], v[166:169], v[150:153], v[86:89]
	v_mfma_f32_16x16x32_bf16 v[90:93], v[170:173], v[150:153], v[90:93]
	v_mfma_f32_16x16x32_bf16 v[94:97], v[174:177], v[150:153], v[94:97]
	v_mfma_f32_16x16x32_bf16 v[98:101], v[162:165], v[154:157], v[98:101]
	s_add_i32 m0, s60, s63
	v_mfma_f32_16x16x32_bf16 v[102:105], v[166:169], v[154:157], v[102:105]
	global_load_lds_dwordx4 v230, s[56:57]
	v_mfma_f32_16x16x32_bf16 v[106:109], v[170:173], v[154:157], v[106:109]
	v_mfma_f32_16x16x32_bf16 v[110:113], v[174:177], v[154:157], v[110:113]
	v_mfma_f32_16x16x32_bf16 v[114:117], v[162:165], v[158:161], v[114:117]
	v_mfma_f32_16x16x32_bf16 v[118:121], v[166:169], v[158:161], v[118:121]
	v_mfma_f32_16x16x32_bf16 v[122:125], v[170:173], v[158:161], v[122:125]
	global_load_lds_dwordx4 v231, s[56:57] offset:1024
	v_mfma_f32_16x16x32_bf16 v[126:129], v[174:177], v[158:161], v[126:129]
	s_setprio 0
	s_add_i32 s60, s60, 0x6000
	s_cmp_eq_u32 s60, 0x12000
	s_cselect_b32 s60, 0, s60
	s_add_u32 s54, s54, s72
	s_addc_u32 s55, s55, 0
	s_add_u32 s56, s56, s73
	s_addc_u32 s57, s57, 0
	s_add_i32 s61, s61, 0x6000
	s_cmp_eq_u32 s61, 0x12000
	s_cselect_b32 s61, 0, s61
	s_waitcnt lgkmcnt(0)
	v_add_u32_e32 v240, s61, v238
	v_add_u32_e32 v241, s61, v239
	s_setprio 1
	v_mfma_f32_16x16x32_bf16 v[2:5], v[210:213], v[178:181], v[2:5]
	v_mfma_f32_16x16x32_bf16 v[6:9], v[214:217], v[178:181], v[6:9]
	v_mfma_f32_16x16x32_bf16 v[10:13], v[218:221], v[178:181], v[10:13]
	v_mfma_f32_16x16x32_bf16 v[14:17], v[222:225], v[178:181], v[14:17]
	s_waitcnt vmcnt(6)
	s_barrier
	v_mfma_f32_16x16x32_bf16 v[18:21], v[210:213], v[182:185], v[18:21]
	v_mfma_f32_16x16x32_bf16 v[22:25], v[214:217], v[182:185], v[22:25]
	v_mfma_f32_16x16x32_bf16 v[26:29], v[218:221], v[182:185], v[26:29]
	v_mfma_f32_16x16x32_bf16 v[30:33], v[222:225], v[182:185], v[30:33]
	v_mfma_f32_16x16x32_bf16 v[34:37], v[210:213], v[186:189], v[34:37]
	ds_read_b128 v[162:165], v241 offset:0
	v_mfma_f32_16x16x32_bf16 v[38:41], v[214:217], v[186:189], v[38:41]
	ds_read_b128 v[166:169], v241 offset:256
	v_mfma_f32_16x16x32_bf16 v[42:45], v[218:221], v[186:189], v[42:45]
	ds_read_b128 v[170:173], v241 offset:512
	v_mfma_f32_16x16x32_bf16 v[46:49], v[222:225], v[186:189], v[46:49]
	ds_read_b128 v[174:177], v241 offset:768
	v_mfma_f32_16x16x32_bf16 v[50:53], v[210:213], v[190:193], v[50:53]
	ds_read_b128 v[130:133], v240 offset:0
	v_mfma_f32_16x16x32_bf16 v[54:57], v[214:217], v[190:193], v[54:57]
	ds_read_b128 v[134:137], v240 offset:1024
	v_mfma_f32_16x16x32_bf16 v[58:61], v[218:221], v[190:193], v[58:61]
	ds_read_b128 v[138:141], v240 offset:2048
	v_mfma_f32_16x16x32_bf16 v[62:65], v[222:225], v[190:193], v[62:65]
	ds_read_b128 v[142:145], v240 offset:3072
	v_mfma_f32_16x16x32_bf16 v[66:69], v[210:213], v[194:197], v[66:69]
	ds_read_b128 v[146:149], v240 offset:4096
	v_mfma_f32_16x16x32_bf16 v[70:73], v[214:217], v[194:197], v[70:73]
	ds_read_b128 v[150:153], v240 offset:5120
	v_mfma_f32_16x16x32_bf16 v[74:77], v[218:221], v[194:197], v[74:77]
	ds_read_b128 v[154:157], v240 offset:6144
	v_mfma_f32_16x16x32_bf16 v[78:81], v[222:225], v[194:197], v[78:81]
	ds_read_b128 v[158:161], v240 offset:7168
	v_mfma_f32_16x16x32_bf16 v[82:85], v[210:213], v[198:201], v[82:85]
	v_mfma_f32_16x16x32_bf16 v[86:89], v[214:217], v[198:201], v[86:89]
	v_mfma_f32_16x16x32_bf16 v[90:93], v[218:221], v[198:201], v[90:93]
	v_mfma_f32_16x16x32_bf16 v[94:97], v[222:225], v[198:201], v[94:97]
	v_mfma_f32_16x16x32_bf16 v[98:101], v[210:213], v[202:205], v[98:101]
	v_mfma_f32_16x16x32_bf16 v[102:105], v[214:217], v[202:205], v[102:105]
	v_mfma_f32_16x16x32_bf16 v[106:109], v[218:221], v[202:205], v[106:109]
	v_mfma_f32_16x16x32_bf16 v[110:113], v[222:225], v[202:205], v[110:113]
	v_mfma_f32_16x16x32_bf16 v[114:117], v[210:213], v[206:209], v[114:117]
	v_mfma_f32_16x16x32_bf16 v[118:121], v[214:217], v[206:209], v[118:121]
	v_mfma_f32_16x16x32_bf16 v[122:125], v[218:221], v[206:209], v[122:125]
	v_mfma_f32_16x16x32_bf16 v[126:129], v[222:225], v[206:209], v[126:129]
	s_setprio 0
	s_add_i32 s61, s61, 0x6000
	s_cmp_eq_u32 s61, 0x12000
	s_cselect_b32 s61, 0, s61
	s_waitcnt lgkmcnt(0)
	v_add_u32_e32 v240, s61, v238
	v_add_u32_e32 v241, s61, v239
	s_setprio 1
	v_mfma_f32_16x16x32_bf16 v[2:5], v[162:165], v[130:133], v[2:5]
	v_mfma_f32_16x16x32_bf16 v[6:9], v[166:169], v[130:133], v[6:9]
	v_mfma_f32_16x16x32_bf16 v[10:13], v[170:173], v[130:133], v[10:13]
	v_mfma_f32_16x16x32_bf16 v[14:17], v[174:177], v[130:133], v[14:17]
	s_waitcnt vmcnt(0)
	s_barrier
	v_mfma_f32_16x16x32_bf16 v[18:21], v[162:165], v[134:137], v[18:21]
	v_mfma_f32_16x16x32_bf16 v[22:25], v[166:169], v[134:137], v[22:25]
	v_mfma_f32_16x16x32_bf16 v[26:29], v[170:173], v[134:137], v[26:29]
	v_mfma_f32_16x16x32_bf16 v[30:33], v[174:177], v[134:137], v[30:33]
	v_mfma_f32_16x16x32_bf16 v[34:37], v[162:165], v[138:141], v[34:37]
	ds_read_b128 v[210:213], v241 offset:0
	v_mfma_f32_16x16x32_bf16 v[38:41], v[166:169], v[138:141], v[38:41]
	ds_read_b128 v[214:217], v241 offset:256
	v_mfma_f32_16x16x32_bf16 v[42:45], v[170:173], v[138:141], v[42:45]
	ds_read_b128 v[218:221], v241 offset:512
	v_mfma_f32_16x16x32_bf16 v[46:49], v[174:177], v[138:141], v[46:49]
	ds_read_b128 v[222:225], v241 offset:768
	v_mfma_f32_16x16x32_bf16 v[50:53], v[162:165], v[142:145], v[50:53]
	ds_read_b128 v[178:181], v240 offset:0
	v_mfma_f32_16x16x32_bf16 v[54:57], v[166:169], v[142:145], v[54:57]
	ds_read_b128 v[182:185], v240 offset:1024
	v_mfma_f32_16x16x32_bf16 v[58:61], v[170:173], v[142:145], v[58:61]
	ds_read_b128 v[186:189], v240 offset:2048
	v_mfma_f32_16x16x32_bf16 v[62:65], v[174:177], v[142:145], v[62:65]
	ds_read_b128 v[190:193], v240 offset:3072
	v_mfma_f32_16x16x32_bf16 v[66:69], v[162:165], v[146:149], v[66:69]
	ds_read_b128 v[194:197], v240 offset:4096
	v_mfma_f32_16x16x32_bf16 v[70:73], v[166:169], v[146:149], v[70:73]
	ds_read_b128 v[198:201], v240 offset:5120
	v_mfma_f32_16x16x32_bf16 v[74:77], v[170:173], v[146:149], v[74:77]
	ds_read_b128 v[202:205], v240 offset:6144
	v_mfma_f32_16x16x32_bf16 v[78:81], v[174:177], v[146:149], v[78:81]
	ds_read_b128 v[206:209], v240 offset:7168
	v_mfma_f32_16x16x32_bf16 v[82:85], v[162:165], v[150:153], v[82:85]
	v_mfma_f32_16x16x32_bf16 v[86:89], v[166:169], v[150:153], v[86:89]
	v_mfma_f32_16x16x32_bf16 v[90:93], v[170:173], v[150:153], v[90:93]
	v_mfma_f32_16x16x32_bf16 v[94:97], v[174:177], v[150:153], v[94:97]
	v_mfma_f32_16x16x32_bf16 v[98:101], v[162:165], v[154:157], v[98:101]
	v_mfma_f32_16x16x32_bf16 v[102:105], v[166:169], v[154:157], v[102:105]
	v_mfma_f32_16x16x32_bf16 v[106:109], v[170:173], v[154:157], v[106:109]
	v_mfma_f32_16x16x32_bf16 v[110:113], v[174:177], v[154:157], v[110:113]
	v_mfma_f32_16x16x32_bf16 v[114:117], v[162:165], v[158:161], v[114:117]
	v_mfma_f32_16x16x32_bf16 v[118:121], v[166:169], v[158:161], v[118:121]
	v_mfma_f32_16x16x32_bf16 v[122:125], v[170:173], v[158:161], v[122:125]
	v_mfma_f32_16x16x32_bf16 v[126:129], v[174:177], v[158:161], v[126:129]
	s_setprio 0
	s_add_i32 s61, s61, 0x6000
	s_cmp_eq_u32 s61, 0x12000
	s_cselect_b32 s61, 0, s61
	s_waitcnt lgkmcnt(0)
	s_setprio 1
	v_mfma_f32_16x16x32_bf16 v[2:5], v[210:213], v[178:181], v[2:5]
	v_mfma_f32_16x16x32_bf16 v[6:9], v[214:217], v[178:181], v[6:9]
	v_mfma_f32_16x16x32_bf16 v[10:13], v[218:221], v[178:181], v[10:13]
	v_mfma_f32_16x16x32_bf16 v[14:17], v[222:225], v[178:181], v[14:17]
	s_barrier
	v_mfma_f32_16x16x32_bf16 v[18:21], v[210:213], v[182:185], v[18:21]
	v_mfma_f32_16x16x32_bf16 v[22:25], v[214:217], v[182:185], v[22:25]
	v_mfma_f32_16x16x32_bf16 v[26:29], v[218:221], v[182:185], v[26:29]
	v_mfma_f32_16x16x32_bf16 v[30:33], v[222:225], v[182:185], v[30:33]
	v_mfma_f32_16x16x32_bf16 v[34:37], v[210:213], v[186:189], v[34:37]
	v_mfma_f32_16x16x32_bf16 v[38:41], v[214:217], v[186:189], v[38:41]
	v_mfma_f32_16x16x32_bf16 v[42:45], v[218:221], v[186:189], v[42:45]
	v_mfma_f32_16x16x32_bf16 v[46:49], v[222:225], v[186:189], v[46:49]
	v_mfma_f32_16x16x32_bf16 v[50:53], v[210:213], v[190:193], v[50:53]
	v_mfma_f32_16x16x32_bf16 v[54:57], v[214:217], v[190:193], v[54:57]
	v_mfma_f32_16x16x32_bf16 v[58:61], v[218:221], v[190:193], v[58:61]
	v_mfma_f32_16x16x32_bf16 v[62:65], v[222:225], v[190:193], v[62:65]
	v_mfma_f32_16x16x32_bf16 v[66:69], v[210:213], v[194:197], v[66:69]
	v_mfma_f32_16x16x32_bf16 v[70:73], v[214:217], v[194:197], v[70:73]
	v_mfma_f32_16x16x32_bf16 v[74:77], v[218:221], v[194:197], v[74:77]
	v_mfma_f32_16x16x32_bf16 v[78:81], v[222:225], v[194:197], v[78:81]
	v_mfma_f32_16x16x32_bf16 v[82:85], v[210:213], v[198:201], v[82:85]
	v_mfma_f32_16x16x32_bf16 v[86:89], v[214:217], v[198:201], v[86:89]
	v_mfma_f32_16x16x32_bf16 v[90:93], v[218:221], v[198:201], v[90:93]
	v_mfma_f32_16x16x32_bf16 v[94:97], v[222:225], v[198:201], v[94:97]
	v_mfma_f32_16x16x32_bf16 v[98:101], v[210:213], v[202:205], v[98:101]
	v_mfma_f32_16x16x32_bf16 v[102:105], v[214:217], v[202:205], v[102:105]
	v_mfma_f32_16x16x32_bf16 v[106:109], v[218:221], v[202:205], v[106:109]
	v_mfma_f32_16x16x32_bf16 v[110:113], v[222:225], v[202:205], v[110:113]
	v_mfma_f32_16x16x32_bf16 v[114:117], v[210:213], v[206:209], v[114:117]
	v_mfma_f32_16x16x32_bf16 v[118:121], v[214:217], v[206:209], v[118:121]
	v_mfma_f32_16x16x32_bf16 v[122:125], v[218:221], v[206:209], v[122:125]
	v_mfma_f32_16x16x32_bf16 v[126:129], v[222:225], v[206:209], v[126:129]
	s_setprio 0
	s_nop 7
	s_nop 1
	s_lshl_b32 s26, s35, 11
	s_lshl_b32 s27, s36, 1
	s_add_i32 s26, s26, s27
	s_add_u32 s18, s52, s26
	s_addc_u32 s19, s53, 0
	v_cvt_pk_bf16_f32 v2, v2, v3
	v_cvt_pk_bf16_f32 v3, v4, v5
	v_cvt_pk_bf16_f32 v4, v6, v7
	v_cvt_pk_bf16_f32 v5, v8, v9
	v_cvt_pk_bf16_f32 v6, v10, v11
	v_cvt_pk_bf16_f32 v7, v12, v13
	v_cvt_pk_bf16_f32 v8, v14, v15
	v_cvt_pk_bf16_f32 v9, v16, v17
	global_store_dwordx4 v242, v[2:5], s[18:19]
	global_store_dwordx4 v242, v[6:9], s[18:19] offset:16
	s_add_u32 s18, s18, 0x8000
	s_addc_u32 s19, s19, 0
	v_cvt_pk_bf16_f32 v18, v18, v19
	v_cvt_pk_bf16_f32 v19, v20, v21
	v_cvt_pk_bf16_f32 v20, v22, v23
	v_cvt_pk_bf16_f32 v21, v24, v25
	v_cvt_pk_bf16_f32 v22, v26, v27
	v_cvt_pk_bf16_f32 v23, v28, v29
	v_cvt_pk_bf16_f32 v24, v30, v31
	v_cvt_pk_bf16_f32 v25, v32, v33
	global_store_dwordx4 v242, v[18:21], s[18:19]
	global_store_dwordx4 v242, v[22:25], s[18:19] offset:16
	s_add_u32 s18, s18, 0x8000
	s_addc_u32 s19, s19, 0
	v_cvt_pk_bf16_f32 v34, v34, v35
	v_cvt_pk_bf16_f32 v35, v36, v37
	v_cvt_pk_bf16_f32 v36, v38, v39
	v_cvt_pk_bf16_f32 v37, v40, v41
	v_cvt_pk_bf16_f32 v38, v42, v43
	v_cvt_pk_bf16_f32 v39, v44, v45
	v_cvt_pk_bf16_f32 v40, v46, v47
	v_cvt_pk_bf16_f32 v41, v48, v49
	global_store_dwordx4 v242, v[34:37], s[18:19]
	global_store_dwordx4 v242, v[38:41], s[18:19] offset:16
	s_add_u32 s18, s18, 0x8000
	s_addc_u32 s19, s19, 0
	v_cvt_pk_bf16_f32 v50, v50, v51
	v_cvt_pk_bf16_f32 v51, v52, v53
	v_cvt_pk_bf16_f32 v52, v54, v55
	v_cvt_pk_bf16_f32 v53, v56, v57
	v_cvt_pk_bf16_f32 v54, v58, v59
	v_cvt_pk_bf16_f32 v55, v60, v61
	v_cvt_pk_bf16_f32 v56, v62, v63
	v_cvt_pk_bf16_f32 v57, v64, v65
	global_store_dwordx4 v242, v[50:53], s[18:19]
	global_store_dwordx4 v242, v[54:57], s[18:19] offset:16
	s_add_u32 s18, s18, 0x8000
	s_addc_u32 s19, s19, 0
	v_cvt_pk_bf16_f32 v66, v66, v67
	v_cvt_pk_bf16_f32 v67, v68, v69
	v_cvt_pk_bf16_f32 v68, v70, v71
	v_cvt_pk_bf16_f32 v69, v72, v73
	v_cvt_pk_bf16_f32 v70, v74, v75
	v_cvt_pk_bf16_f32 v71, v76, v77
	v_cvt_pk_bf16_f32 v72, v78, v79
	v_cvt_pk_bf16_f32 v73, v80, v81
	global_store_dwordx4 v242, v[66:69], s[18:19]
	global_store_dwordx4 v242, v[70:73], s[18:19] offset:16
	s_add_u32 s18, s18, 0x8000
	s_addc_u32 s19, s19, 0
	v_cvt_pk_bf16_f32 v82, v82, v83
	v_cvt_pk_bf16_f32 v83, v84, v85
	v_cvt_pk_bf16_f32 v84, v86, v87
	v_cvt_pk_bf16_f32 v85, v88, v89
	v_cvt_pk_bf16_f32 v86, v90, v91
	v_cvt_pk_bf16_f32 v87, v92, v93
	v_cvt_pk_bf16_f32 v88, v94, v95
	v_cvt_pk_bf16_f32 v89, v96, v97
	global_store_dwordx4 v242, v[82:85], s[18:19]
	global_store_dwordx4 v242, v[86:89], s[18:19] offset:16
	s_add_u32 s18, s18, 0x8000
	s_addc_u32 s19, s19, 0
	v_cvt_pk_bf16_f32 v98, v98, v99
	v_cvt_pk_bf16_f32 v99, v100, v101
	v_cvt_pk_bf16_f32 v100, v102, v103
	v_cvt_pk_bf16_f32 v101, v104, v105
	v_cvt_pk_bf16_f32 v102, v106, v107
	v_cvt_pk_bf16_f32 v103, v108, v109
	v_cvt_pk_bf16_f32 v104, v110, v111
	v_cvt_pk_bf16_f32 v105, v112, v113
	global_store_dwordx4 v242, v[98:101], s[18:19]
	global_store_dwordx4 v242, v[102:105], s[18:19] offset:16
	s_add_u32 s18, s18, 0x8000
	s_addc_u32 s19, s19, 0
	v_cvt_pk_bf16_f32 v114, v114, v115
	v_cvt_pk_bf16_f32 v115, v116, v117
	v_cvt_pk_bf16_f32 v116, v118, v119
	v_cvt_pk_bf16_f32 v117, v120, v121
	v_cvt_pk_bf16_f32 v118, v122, v123
	v_cvt_pk_bf16_f32 v119, v124, v125
	v_cvt_pk_bf16_f32 v120, v126, v127
	v_cvt_pk_bf16_f32 v121, v128, v129
	global_store_dwordx4 v242, v[114:117], s[18:19]
	global_store_dwordx4 v242, v[118:121], s[18:19] offset:16

.Lup_nn_a:
	s_waitcnt lgkmcnt(0)
	v_add_u32_e32 v240, s61, v238
	v_add_u32_e32 v241, s61, v239
	s_setprio 1
	v_mfma_f32_16x16x32_bf16 v[2:5], v[162:165], v[130:133], 0
	v_mfma_f32_16x16x32_bf16 v[6:9], v[166:169], v[130:133], 0
	v_mfma_f32_16x16x32_bf16 v[10:13], v[170:173], v[130:133], 0
	v_mfma_f32_16x16x32_bf16 v[14:17], v[174:177], v[130:133], 0
	s_waitcnt vmcnt(6)
	s_barrier
	v_mfma_f32_16x16x32_bf16 v[18:21], v[162:165], v[134:137], 0
	s_add_i32 m0, s60, s62
	v_mfma_f32_16x16x32_bf16 v[22:25], v[166:169], v[134:137], 0
	global_load_lds_dwordx4 v226, s[54:55]
	v_mfma_f32_16x16x32_bf16 v[26:29], v[170:173], v[134:137], 0
	v_mfma_f32_16x16x32_bf16 v[30:33], v[174:177], v[134:137], 0
	v_mfma_f32_16x16x32_bf16 v[34:37], v[162:165], v[138:141], 0
	ds_read_b128 v[210:213], v241 offset:0
	v_mfma_f32_16x16x32_bf16 v[38:41], v[166:169], v[138:141], 0
	ds_read_b128 v[214:217], v241 offset:256
	v_mfma_f32_16x16x32_bf16 v[42:45], v[170:173], v[138:141], 0
	ds_read_b128 v[218:221], v241 offset:2048
	global_load_lds_dwordx4 v226, s[54:55] offset:1024
	v_mfma_f32_16x16x32_bf16 v[46:49], v[174:177], v[138:141], 0
	ds_read_b128 v[222:225], v241 offset:2304
	v_mfma_f32_16x16x32_bf16 v[50:53], v[162:165], v[142:145], 0
	ds_read_b128 v[178:181], v240 offset:0
	v_mfma_f32_16x16x32_bf16 v[54:57], v[166:169], v[142:145], 0
	ds_read_b128 v[182:185], v240 offset:1024
	v_mfma_f32_16x16x32_bf16 v[58:61], v[170:173], v[142:145], 0
	ds_read_b128 v[186:189], v240 offset:2048
	v_mfma_f32_16x16x32_bf16 v[62:65], v[174:177], v[142:145], 0
	ds_read_b128 v[190:193], v240 offset:3072
	global_load_lds_dwordx4 v226, s[54:55] offset:2048
	v_mfma_f32_16x16x32_bf16 v[66:69], v[162:165], v[146:149], 0
	ds_read_b128 v[194:197], v240 offset:4096
	v_mfma_f32_16x16x32_bf16 v[70:73], v[166:169], v[146:149], 0
	ds_read_b128 v[198:201], v240 offset:5120
	v_mfma_f32_16x16x32_bf16 v[74:77], v[170:173], v[146:149], 0
	ds_read_b128 v[202:205], v240 offset:6144
	v_mfma_f32_16x16x32_bf16 v[78:81], v[174:177], v[146:149], 0
	ds_read_b128 v[206:209], v240 offset:7168
	v_mfma_f32_16x16x32_bf16 v[82:85], v[162:165], v[150:153], 0
	global_load_lds_dwordx4 v226, s[54:55] offset:3072
	v_mfma_f32_16x16x32_bf16 v[86:89], v[166:169], v[150:153], 0
	v_mfma_f32_16x16x32_bf16 v[90:93], v[170:173], v[150:153], 0
	v_mfma_f32_16x16x32_bf16 v[94:97], v[174:177], v[150:153], 0
	v_mfma_f32_16x16x32_bf16 v[98:101], v[162:165], v[154:157], 0
	s_add_i32 m0, s60, s63
	v_mfma_f32_16x16x32_bf16 v[102:105], v[166:169], v[154:157], 0
	global_load_lds_dwordx4 v230, s[56:57]
	v_mfma_f32_16x16x32_bf16 v[106:109], v[170:173], v[154:157], 0
	v_mfma_f32_16x16x32_bf16 v[110:113], v[174:177], v[154:157], 0
	v_mfma_f32_16x16x32_bf16 v[114:117], v[162:165], v[158:161], 0
	v_mfma_f32_16x16x32_bf16 v[118:121], v[166:169], v[158:161], 0
	v_mfma_f32_16x16x32_bf16 v[122:125], v[170:173], v[158:161], 0
	global_load_lds_dwordx4 v231, s[56:57] offset:1024
	v_mfma_f32_16x16x32_bf16 v[126:129], v[174:177], v[158:161], 0
	s_setprio 0
	s_add_i32 s60, s60, 0x6000
	s_cmp_eq_u32 s60, 0x12000
	s_cselect_b32 s60, 0, s60
	s_add_u32 s54, s54, s72
	s_addc_u32 s55, s55, 0
	s_add_u32 s56, s56, s73
	s_addc_u32 s57, s57, 0
	s_add_i32 s61, s61, 0x6000
	s_cmp_eq_u32 s61, 0x12000
	s_cselect_b32 s61, 0, s61
	v_mbcnt_lo_u32_b32 v0, -1, 0
	v_lshlrev_b32_e32 v0, 4, v0
	s_lshl_b32 s26, s36, 1
	v_add_u32_e32 v0, s26, v0
	s_lshl_b32 s26, s41, 8
	s_add_i32 m0, s26, 0x13010
	s_mov_b64 exec, 0xffff
	global_load_lds_dwordx4 v0, s[82:83]
	s_mov_b64 exec, -1
	s_waitcnt lgkmcnt(0)
	v_add_u32_e32 v240, s61, v238
	v_add_u32_e32 v241, s61, v239
	s_setprio 1
	v_mfma_f32_16x16x32_bf16 v[2:5], v[210:213], v[178:181], v[2:5]
	v_mfma_f32_16x16x32_bf16 v[6:9], v[214:217], v[178:181], v[6:9]
	v_mfma_f32_16x16x32_bf16 v[10:13], v[218:221], v[178:181], v[10:13]
	v_mfma_f32_16x16x32_bf16 v[14:17], v[222:225], v[178:181], v[14:17]
	s_waitcnt vmcnt(6)
	s_barrier
	v_mfma_f32_16x16x32_bf16 v[18:21], v[210:213], v[182:185], v[18:21]
	s_add_i32 m0, s60, s62
	v_mfma_f32_16x16x32_bf16 v[22:25], v[214:217], v[182:185], v[22:25]
	global_load_lds_dwordx4 v226, s[54:55]
	v_mfma_f32_16x16x32_bf16 v[26:29], v[218:221], v[182:185], v[26:29]
	v_mfma_f32_16x16x32_bf16 v[30:33], v[222:225], v[182:185], v[30:33]
	v_mfma_f32_16x16x32_bf16 v[34:37], v[210:213], v[186:189], v[34:37]
	ds_read_b128 v[162:165], v241 offset:0
	v_mfma_f32_16x16x32_bf16 v[38:41], v[214:217], v[186:189], v[38:41]
	ds_read_b128 v[166:169], v241 offset:256
	v_mfma_f32_16x16x32_bf16 v[42:45], v[218:221], v[186:189], v[42:45]
	ds_read_b128 v[170:173], v241 offset:2048
	global_load_lds_dwordx4 v226, s[54:55] offset:1024
	v_mfma_f32_16x16x32_bf16 v[46:49], v[222:225], v[186:189], v[46:49]
	ds_read_b128 v[174:177], v241 offset:2304
	v_mfma_f32_16x16x32_bf16 v[50:53], v[210:213], v[190:193], v[50:53]
	ds_read_b128 v[130:133], v240 offset:0
	v_mfma_f32_16x16x32_bf16 v[54:57], v[214:217], v[190:193], v[54:57]
	ds_read_b128 v[134:137], v240 offset:1024
	v_mfma_f32_16x16x32_bf16 v[58:61], v[218:221], v[190:193], v[58:61]
	ds_read_b128 v[138:141], v240 offset:2048
	v_mfma_f32_16x16x32_bf16 v[62:65], v[222:225], v[190:193], v[62:65]
	ds_read_b128 v[142:145], v240 offset:3072
	global_load_lds_dwordx4 v226, s[54:55] offset:2048
	v_mfma_f32_16x16x32_bf16 v[66:69], v[210:213], v[194:197], v[66:69]
	ds_read_b128 v[146:149], v240 offset:4096
	v_mfma_f32_16x16x32_bf16 v[70:73], v[214:217], v[194:197], v[70:73]
	ds_read_b128 v[150:153], v240 offset:5120
	v_mfma_f32_16x16x32_bf16 v[74:77], v[218:221], v[194:197], v[74:77]
	ds_read_b128 v[154:157], v240 offset:6144
	v_mfma_f32_16x16x32_bf16 v[78:81], v[222:225], v[194:197], v[78:81]
	ds_read_b128 v[158:161], v240 offset:7168
	v_mfma_f32_16x16x32_bf16 v[82:85], v[210:213], v[198:201], v[82:85]
	global_load_lds_dwordx4 v226, s[54:55] offset:3072
	v_mfma_f32_16x16x32_bf16 v[86:89], v[214:217], v[198:201], v[86:89]
	v_mfma_f32_16x16x32_bf16 v[90:93], v[218:221], v[198:201], v[90:93]
	v_mfma_f32_16x16x32_bf16 v[94:97], v[222:225], v[198:201], v[94:97]
	v_mfma_f32_16x16x32_bf16 v[98:101], v[210:213], v[202:205], v[98:101]
	s_add_i32 m0, s60, s63
	v_mfma_f32_16x16x32_bf16 v[102:105], v[214:217], v[202:205], v[102:105]
	global_load_lds_dwordx4 v230, s[56:57]
	v_mfma_f32_16x16x32_bf16 v[106:109], v[218:221], v[202:205], v[106:109]
	v_mfma_f32_16x16x32_bf16 v[110:113], v[222:225], v[202:205], v[110:113]
	v_mfma_f32_16x16x32_bf16 v[114:117], v[210:213], v[206:209], v[114:117]
	v_mfma_f32_16x16x32_bf16 v[118:121], v[214:217], v[206:209], v[118:121]
	v_mfma_f32_16x16x32_bf16 v[122:125], v[218:221], v[206:209], v[122:125]
	global_load_lds_dwordx4 v231, s[56:57] offset:1024
	v_mfma_f32_16x16x32_bf16 v[126:129], v[222:225], v[206:209], v[126:129]
	s_setprio 0
	s_add_i32 s60, s60, 0x6000
	s_cmp_eq_u32 s60, 0x12000
	s_cselect_b32 s60, 0, s60
	s_add_u32 s54, s54, s72
	s_addc_u32 s55, s55, 0
	s_add_u32 s56, s56, s73
	s_addc_u32 s57, s57, 0
	s_add_i32 s61, s61, 0x6000
	s_cmp_eq_u32 s61, 0x12000
	s_cselect_b32 s61, 0, s61
	s_branch .Lup_main

.Lup_nn_b:
	s_waitcnt lgkmcnt(0)
	v_add_u32_e32 v240, s61, v238
	v_add_u32_e32 v241, s61, v239
	s_setprio 1
	v_mfma_f32_16x16x32_bf16 v[2:5], v[162:165], v[130:133], 0
	v_mfma_f32_16x16x32_bf16 v[6:9], v[166:169], v[130:133], 0
	v_mfma_f32_16x16x32_bf16 v[10:13], v[170:173], v[130:133], 0
	v_mfma_f32_16x16x32_bf16 v[14:17], v[174:177], v[130:133], 0
	s_waitcnt vmcnt(14)
	s_barrier
	v_mfma_f32_16x16x32_bf16 v[18:21], v[162:165], v[134:137], 0
	s_add_i32 m0, s60, s62
	v_mfma_f32_16x16x32_bf16 v[22:25], v[166:169], v[134:137], 0
	global_load_lds_dwordx4 v226, s[54:55]
	v_mfma_f32_16x16x32_bf16 v[26:29], v[170:173], v[134:137], 0
	v_mfma_f32_16x16x32_bf16 v[30:33], v[174:177], v[134:137], 0
	v_mfma_f32_16x16x32_bf16 v[34:37], v[162:165], v[138:141], 0
	ds_read_b128 v[210:213], v241 offset:0
	v_mfma_f32_16x16x32_bf16 v[38:41], v[166:169], v[138:141], 0
	ds_read_b128 v[214:217], v241 offset:256
	v_mfma_f32_16x16x32_bf16 v[42:45], v[170:173], v[138:141], 0
	ds_read_b128 v[218:221], v241 offset:2048
	global_load_lds_dwordx4 v226, s[54:55] offset:1024
	v_mfma_f32_16x16x32_bf16 v[46:49], v[174:177], v[138:141], 0
	ds_read_b128 v[222:225], v241 offset:2304
	v_mfma_f32_16x16x32_bf16 v[50:53], v[162:165], v[142:145], 0
	ds_read_b128 v[178:181], v240 offset:0
	v_mfma_f32_16x16x32_bf16 v[54:57], v[166:169], v[142:145], 0
	ds_read_b128 v[182:185], v240 offset:1024
	v_mfma_f32_16x16x32_bf16 v[58:61], v[170:173], v[142:145], 0
	ds_read_b128 v[186:189], v240 offset:2048
	v_mfma_f32_16x16x32_bf16 v[62:65], v[174:177], v[142:145], 0
	ds_read_b128 v[190:193], v240 offset:3072
	global_load_lds_dwordx4 v226, s[54:55] offset:2048
	v_mfma_f32_16x16x32_bf16 v[66:69], v[162:165], v[146:149], 0
	ds_read_b128 v[194:197], v240 offset:4096
	v_mfma_f32_16x16x32_bf16 v[70:73], v[166:169], v[146:149], 0
	ds_read_b128 v[198:201], v240 offset:5120
	v_mfma_f32_16x16x32_bf16 v[74:77], v[170:173], v[146:149], 0
	ds_read_b128 v[202:205], v240 offset:6144
	v_mfma_f32_16x16x32_bf16 v[78:81], v[174:177], v[146:149], 0
	ds_read_b128 v[206:209], v240 offset:7168
	v_mfma_f32_16x16x32_bf16 v[82:85], v[162:165], v[150:153], 0
	global_load_lds_dwordx4 v226, s[54:55] offset:3072
	v_mfma_f32_16x16x32_bf16 v[86:89], v[166:169], v[150:153], 0
	v_mfma_f32_16x16x32_bf16 v[90:93], v[170:173], v[150:153], 0
	v_mfma_f32_16x16x32_bf16 v[94:97], v[174:177], v[150:153], 0
	v_mfma_f32_16x16x32_bf16 v[98:101], v[162:165], v[154:157], 0
	s_add_i32 m0, s60, s63
	v_mfma_f32_16x16x32_bf16 v[102:105], v[166:169], v[154:157], 0
	global_load_lds_dwordx4 v230, s[56:57]
	v_mfma_f32_16x16x32_bf16 v[106:109], v[170:173], v[154:157], 0
	v_mfma_f32_16x16x32_bf16 v[110:113], v[174:177], v[154:157], 0
	v_mfma_f32_16x16x32_bf16 v[114:117], v[162:165], v[158:161], 0
	v_mfma_f32_16x16x32_bf16 v[118:121], v[166:169], v[158:161], 0
	v_mfma_f32_16x16x32_bf16 v[122:125], v[170:173], v[158:161], 0
	global_load_lds_dwordx4 v231, s[56:57] offset:1024
	v_mfma_f32_16x16x32_bf16 v[126:129], v[174:177], v[158:161], 0
	s_setprio 0
	s_add_i32 s60, s60, 0x6000
	s_cmp_eq_u32 s60, 0x12000
	s_cselect_b32 s60, 0, s60
	s_add_u32 s54, s54, s72
	s_addc_u32 s55, s55, 0
	s_add_u32 s56, s56, s73
	s_addc_u32 s57, s57, 0
	s_add_i32 s61, s61, 0x6000
	s_cmp_eq_u32 s61, 0x12000
	s_cselect_b32 s61, 0, s61
	v_mbcnt_lo_u32_b32 v0, -1, 0
	v_lshlrev_b32_e32 v0, 4, v0
	s_lshl_b32 s26, s36, 1
	v_add_u32_e32 v0, s26, v0
	s_lshl_b32 s26, s41, 8
	s_add_i32 m0, s26, 0x13010
	s_mov_b64 exec, 0xffff
	global_load_lds_dwordx4 v0, s[82:83]
	s_mov_b64 exec, -1
	s_waitcnt lgkmcnt(0)
	v_add_u32_e32 v240, s61, v238
	v_add_u32_e32 v241, s61, v239
	s_setprio 1
	v_mfma_f32_16x16x32_bf16 v[2:5], v[210:213], v[178:181], v[2:5]
	v_mfma_f32_16x16x32_bf16 v[6:9], v[214:217], v[178:181], v[6:9]
	v_mfma_f32_16x16x32_bf16 v[10:13], v[218:221], v[178:181], v[10:13]
	v_mfma_f32_16x16x32_bf16 v[14:17], v[222:225], v[178:181], v[14:17]
	s_waitcnt vmcnt(14)
	s_barrier
	v_mfma_f32_16x16x32_bf16 v[18:21], v[210:213], v[182:185], v[18:21]
	s_add_i32 m0, s60, s62
	v_mfma_f32_16x16x32_bf16 v[22:25], v[214:217], v[182:185], v[22:25]
	global_load_lds_dwordx4 v226, s[54:55]
	v_mfma_f32_16x16x32_bf16 v[26:29], v[218:221], v[182:185], v[26:29]
	v_mfma_f32_16x16x32_bf16 v[30:33], v[222:225], v[182:185], v[30:33]
	v_mfma_f32_16x16x32_bf16 v[34:37], v[210:213], v[186:189], v[34:37]
	ds_read_b128 v[162:165], v241 offset:0
	v_mfma_f32_16x16x32_bf16 v[38:41], v[214:217], v[186:189], v[38:41]
	ds_read_b128 v[166:169], v241 offset:256
	v_mfma_f32_16x16x32_bf16 v[42:45], v[218:221], v[186:189], v[42:45]
	ds_read_b128 v[170:173], v241 offset:2048
	global_load_lds_dwordx4 v226, s[54:55] offset:1024
	v_mfma_f32_16x16x32_bf16 v[46:49], v[222:225], v[186:189], v[46:49]
	ds_read_b128 v[174:177], v241 offset:2304
	v_mfma_f32_16x16x32_bf16 v[50:53], v[210:213], v[190:193], v[50:53]
	ds_read_b128 v[130:133], v240 offset:0
	v_mfma_f32_16x16x32_bf16 v[54:57], v[214:217], v[190:193], v[54:57]
	ds_read_b128 v[134:137], v240 offset:1024
	v_mfma_f32_16x16x32_bf16 v[58:61], v[218:221], v[190:193], v[58:61]
	ds_read_b128 v[138:141], v240 offset:2048
	v_mfma_f32_16x16x32_bf16 v[62:65], v[222:225], v[190:193], v[62:65]
	ds_read_b128 v[142:145], v240 offset:3072
	global_load_lds_dwordx4 v226, s[54:55] offset:2048
	v_mfma_f32_16x16x32_bf16 v[66:69], v[210:213], v[194:197], v[66:69]
	ds_read_b128 v[146:149], v240 offset:4096
	v_mfma_f32_16x16x32_bf16 v[70:73], v[214:217], v[194:197], v[70:73]
	ds_read_b128 v[150:153], v240 offset:5120
	v_mfma_f32_16x16x32_bf16 v[74:77], v[218:221], v[194:197], v[74:77]
	ds_read_b128 v[154:157], v240 offset:6144
	v_mfma_f32_16x16x32_bf16 v[78:81], v[222:225], v[194:197], v[78:81]
	ds_read_b128 v[158:161], v240 offset:7168
	v_mfma_f32_16x16x32_bf16 v[82:85], v[210:213], v[198:201], v[82:85]
	global_load_lds_dwordx4 v226, s[54:55] offset:3072
	v_mfma_f32_16x16x32_bf16 v[86:89], v[214:217], v[198:201], v[86:89]
	v_mfma_f32_16x16x32_bf16 v[90:93], v[218:221], v[198:201], v[90:93]
	v_mfma_f32_16x16x32_bf16 v[94:97], v[222:225], v[198:201], v[94:97]
	v_mfma_f32_16x16x32_bf16 v[98:101], v[210:213], v[202:205], v[98:101]
	s_add_i32 m0, s60, s63
	v_mfma_f32_16x16x32_bf16 v[102:105], v[214:217], v[202:205], v[102:105]
	global_load_lds_dwordx4 v230, s[56:57]
	v_mfma_f32_16x16x32_bf16 v[106:109], v[218:221], v[202:205], v[106:109]
	v_mfma_f32_16x16x32_bf16 v[110:113], v[222:225], v[202:205], v[110:113]
	v_mfma_f32_16x16x32_bf16 v[114:117], v[210:213], v[206:209], v[114:117]
	v_mfma_f32_16x16x32_bf16 v[118:121], v[214:217], v[206:209], v[118:121]
	v_mfma_f32_16x16x32_bf16 v[122:125], v[218:221], v[206:209], v[122:125]
	global_load_lds_dwordx4 v231, s[56:57] offset:1024
	v_mfma_f32_16x16x32_bf16 v[126:129], v[222:225], v[206:209], v[126:129]
	s_setprio 0
	s_add_i32 s60, s60, 0x6000
	s_cmp_eq_u32 s60, 0x12000
	s_cselect_b32 s60, 0, s60
	s_add_u32 s54, s54, s72
	s_addc_u32 s55, s55, 0
	s_add_u32 s56, s56, s73
	s_addc_u32 s57, s57, 0
	s_add_i32 s61, s61, 0x6000
	s_cmp_eq_u32 s61, 0x12000
	s_cselect_b32 s61, 0, s61

.Lup_kloop:
	s_waitcnt lgkmcnt(0)
	v_add_u32_e32 v240, s61, v238
	v_add_u32_e32 v241, s61, v239
	s_setprio 1
	v_mfma_f32_16x16x32_bf16 v[2:5], v[162:165], v[130:133], v[2:5]
	v_mfma_f32_16x16x32_bf16 v[6:9], v[166:169], v[130:133], v[6:9]
	v_mfma_f32_16x16x32_bf16 v[10:13], v[170:173], v[130:133], v[10:13]
	v_mfma_f32_16x16x32_bf16 v[14:17], v[174:177], v[130:133], v[14:17]
	s_waitcnt vmcnt(6)
	s_barrier
	v_mfma_f32_16x16x32_bf16 v[18:21], v[162:165], v[134:137], v[18:21]
	s_add_i32 m0, s60, s62
	v_mfma_f32_16x16x32_bf16 v[22:25], v[166:169], v[134:137], v[22:25]
	global_load_lds_dwordx4 v226, s[54:55]
	v_mfma_f32_16x16x32_bf16 v[26:29], v[170:173], v[134:137], v[26:29]
	v_mfma_f32_16x16x32_bf16 v[30:33], v[174:177], v[134:137], v[30:33]
	v_mfma_f32_16x16x32_bf16 v[34:37], v[162:165], v[138:141], v[34:37]
	ds_read_b128 v[210:213], v241 offset:0
	v_mfma_f32_16x16x32_bf16 v[38:41], v[166:169], v[138:141], v[38:41]
	ds_read_b128 v[214:217], v241 offset:256
	v_mfma_f32_16x16x32_bf16 v[42:45], v[170:173], v[138:141], v[42:45]
	ds_read_b128 v[218:221], v241 offset:2048
	global_load_lds_dwordx4 v226, s[54:55] offset:1024
	v_mfma_f32_16x16x32_bf16 v[46:49], v[174:177], v[138:141], v[46:49]
	ds_read_b128 v[222:225], v241 offset:2304
	v_mfma_f32_16x16x32_bf16 v[50:53], v[162:165], v[142:145], v[50:53]
	ds_read_b128 v[178:181], v240 offset:0
	v_mfma_f32_16x16x32_bf16 v[54:57], v[166:169], v[142:145], v[54:57]
	ds_read_b128 v[182:185], v240 offset:1024
	v_mfma_f32_16x16x32_bf16 v[58:61], v[170:173], v[142:145], v[58:61]
	ds_read_b128 v[186:189], v240 offset:2048
	v_mfma_f32_16x16x32_bf16 v[62:65], v[174:177], v[142:145], v[62:65]
	ds_read_b128 v[190:193], v240 offset:3072
	global_load_lds_dwordx4 v226, s[54:55] offset:2048
	v_mfma_f32_16x16x32_bf16 v[66:69], v[162:165], v[146:149], v[66:69]
	ds_read_b128 v[194:197], v240 offset:4096
	v_mfma_f32_16x16x32_bf16 v[70:73], v[166:169], v[146:149], v[70:73]
	ds_read_b128 v[198:201], v240 offset:5120
	v_mfma_f32_16x16x32_bf16 v[74:77], v[170:173], v[146:149], v[74:77]
	ds_read_b128 v[202:205], v240 offset:6144
	v_mfma_f32_16x16x32_bf16 v[78:81], v[174:177], v[146:149], v[78:81]
	ds_read_b128 v[206:209], v240 offset:7168
	v_mfma_f32_16x16x32_bf16 v[82:85], v[162:165], v[150:153], v[82:85]
	global_load_lds_dwordx4 v226, s[54:55] offset:3072
	v_mfma_f32_16x16x32_bf16 v[86:89], v[166:169], v[150:153], v[86:89]
	v_mfma_f32_16x16x32_bf16 v[90:93], v[170:173], v[150:153], v[90:93]
	v_mfma_f32_16x16x32_bf16 v[94:97], v[174:177], v[150:153], v[94:97]
	v_mfma_f32_16x16x32_bf16 v[98:101], v[162:165], v[154:157], v[98:101]
	s_add_i32 m0, s60, s63
	v_mfma_f32_16x16x32_bf16 v[102:105], v[166:169], v[154:157], v[102:105]
	global_load_lds_dwordx4 v230, s[56:57]
	v_mfma_f32_16x16x32_bf16 v[106:109], v[170:173], v[154:157], v[106:109]
	v_mfma_f32_16x16x32_bf16 v[110:113], v[174:177], v[154:157], v[110:113]
	v_mfma_f32_16x16x32_bf16 v[114:117], v[162:165], v[158:161], v[114:117]
	v_mfma_f32_16x16x32_bf16 v[118:121], v[166:169], v[158:161], v[118:121]
	v_mfma_f32_16x16x32_bf16 v[122:125], v[170:173], v[158:161], v[122:125]
	global_load_lds_dwordx4 v231, s[56:57] offset:1024
	v_mfma_f32_16x16x32_bf16 v[126:129], v[174:177], v[158:161], v[126:129]
	s_setprio 0
	s_add_i32 s60, s60, 0x6000
	s_cmp_eq_u32 s60, 0x12000
	s_cselect_b32 s60, 0, s60
	s_add_u32 s54, s54, s72
	s_addc_u32 s55, s55, 0
	s_add_u32 s56, s56, s73
	s_addc_u32 s57, s57, 0
	s_add_i32 s61, s61, 0x6000
	s_cmp_eq_u32 s61, 0x12000
	s_cselect_b32 s61, 0, s61
	s_waitcnt lgkmcnt(0)
	v_add_u32_e32 v240, s61, v238
	v_add_u32_e32 v241, s61, v239
	s_setprio 1
	v_mfma_f32_16x16x32_bf16 v[2:5], v[210:213], v[178:181], v[2:5]
	v_mfma_f32_16x16x32_bf16 v[6:9], v[214:217], v[178:181], v[6:9]
	v_mfma_f32_16x16x32_bf16 v[10:13], v[218:221], v[178:181], v[10:13]
	v_mfma_f32_16x16x32_bf16 v[14:17], v[222:225], v[178:181], v[14:17]
	s_waitcnt vmcnt(6)
	s_barrier
	v_mfma_f32_16x16x32_bf16 v[18:21], v[210:213], v[182:185], v[18:21]
	s_add_i32 m0, s60, s62
	v_mfma_f32_16x16x32_bf16 v[22:25], v[214:217], v[182:185], v[22:25]
	global_load_lds_dwordx4 v226, s[54:55]
	v_mfma_f32_16x16x32_bf16 v[26:29], v[218:221], v[182:185], v[26:29]
	v_mfma_f32_16x16x32_bf16 v[30:33], v[222:225], v[182:185], v[30:33]
	v_mfma_f32_16x16x32_bf16 v[34:37], v[210:213], v[186:189], v[34:37]
	ds_read_b128 v[162:165], v241 offset:0
	v_mfma_f32_16x16x32_bf16 v[38:41], v[214:217], v[186:189], v[38:41]
	ds_read_b128 v[166:169], v241 offset:256
	v_mfma_f32_16x16x32_bf16 v[42:45], v[218:221], v[186:189], v[42:45]
	ds_read_b128 v[170:173], v241 offset:2048
	global_load_lds_dwordx4 v226, s[54:55] offset:1024
	v_mfma_f32_16x16x32_bf16 v[46:49], v[222:225], v[186:189], v[46:49]
	ds_read_b128 v[174:177], v241 offset:2304
	v_mfma_f32_16x16x32_bf16 v[50:53], v[210:213], v[190:193], v[50:53]
	ds_read_b128 v[130:133], v240 offset:0
	v_mfma_f32_16x16x32_bf16 v[54:57], v[214:217], v[190:193], v[54:57]
	ds_read_b128 v[134:137], v240 offset:1024
	v_mfma_f32_16x16x32_bf16 v[58:61], v[218:221], v[190:193], v[58:61]
	ds_read_b128 v[138:141], v240 offset:2048
	v_mfma_f32_16x16x32_bf16 v[62:65], v[222:225], v[190:193], v[62:65]
	ds_read_b128 v[142:145], v240 offset:3072
	global_load_lds_dwordx4 v226, s[54:55] offset:2048
	v_mfma_f32_16x16x32_bf16 v[66:69], v[210:213], v[194:197], v[66:69]
	ds_read_b128 v[146:149], v240 offset:4096
	v_mfma_f32_16x16x32_bf16 v[70:73], v[214:217], v[194:197], v[70:73]
	ds_read_b128 v[150:153], v240 offset:5120
	v_mfma_f32_16x16x32_bf16 v[74:77], v[218:221], v[194:197], v[74:77]
	ds_read_b128 v[154:157], v240 offset:6144
	v_mfma_f32_16x16x32_bf16 v[78:81], v[222:225], v[194:197], v[78:81]
	ds_read_b128 v[158:161], v240 offset:7168
	v_mfma_f32_16x16x32_bf16 v[82:85], v[210:213], v[198:201], v[82:85]
	global_load_lds_dwordx4 v226, s[54:55] offset:3072
	v_mfma_f32_16x16x32_bf16 v[86:89], v[214:217], v[198:201], v[86:89]
	v_mfma_f32_16x16x32_bf16 v[90:93], v[218:221], v[198:201], v[90:93]
	v_mfma_f32_16x16x32_bf16 v[94:97], v[222:225], v[198:201], v[94:97]
	v_mfma_f32_16x16x32_bf16 v[98:101], v[210:213], v[202:205], v[98:101]
	s_add_i32 m0, s60, s63
	v_mfma_f32_16x16x32_bf16 v[102:105], v[214:217], v[202:205], v[102:105]
	global_load_lds_dwordx4 v230, s[56:57]
	v_mfma_f32_16x16x32_bf16 v[106:109], v[218:221], v[202:205], v[106:109]
	v_mfma_f32_16x16x32_bf16 v[110:113], v[222:225], v[202:205], v[110:113]
	v_mfma_f32_16x16x32_bf16 v[114:117], v[210:213], v[206:209], v[114:117]
	v_mfma_f32_16x16x32_bf16 v[118:121], v[214:217], v[206:209], v[118:121]
	v_mfma_f32_16x16x32_bf16 v[122:125], v[218:221], v[206:209], v[122:125]
	global_load_lds_dwordx4 v231, s[56:57] offset:1024
	v_mfma_f32_16x16x32_bf16 v[126:129], v[222:225], v[206:209], v[126:129]
	s_setprio 0
	s_add_i32 s60, s60, 0x6000
	s_cmp_eq_u32 s60, 0x12000
	s_cselect_b32 s60, 0, s60
	s_add_u32 s54, s54, s72
	s_addc_u32 s55, s55, 0
	s_add_u32 s56, s56, s73
	s_addc_u32 s57, s57, 0
	s_add_i32 s61, s61, 0x6000
	s_cmp_eq_u32 s61, 0x12000
	s_cselect_b32 s61, 0, s61
	s_add_i32 s40, s40, -1
	s_cmp_lg_u32 s40, 0
	s_cbranch_scc1 .Lup_kloop
.Lup_kdone:
	s_cmp_eq_u32 s37, 0
	s_cbranch_scc1 .Lup_tail_last
	s_waitcnt lgkmcnt(0)
	v_add_u32_e32 v240, s61, v238
	v_add_u32_e32 v241, s61, v239
	s_setprio 1
	v_mfma_f32_16x16x32_bf16 v[2:5], v[162:165], v[130:133], v[2:5]
	v_mfma_f32_16x16x32_bf16 v[6:9], v[166:169], v[130:133], v[6:9]
	v_mfma_f32_16x16x32_bf16 v[10:13], v[170:173], v[130:133], v[10:13]
	v_mfma_f32_16x16x32_bf16 v[14:17], v[174:177], v[130:133], v[14:17]
	s_waitcnt vmcnt(6)
	s_barrier
	v_mfma_f32_16x16x32_bf16 v[18:21], v[162:165], v[134:137], v[18:21]
	s_add_i32 m0, s60, s62
	v_mfma_f32_16x16x32_bf16 v[22:25], v[166:169], v[134:137], v[22:25]
	global_load_lds_dwordx4 v226, s[54:55]
	v_mfma_f32_16x16x32_bf16 v[26:29], v[170:173], v[134:137], v[26:29]
	v_mfma_f32_16x16x32_bf16 v[30:33], v[174:177], v[134:137], v[30:33]
	v_mfma_f32_16x16x32_bf16 v[34:37], v[162:165], v[138:141], v[34:37]
	ds_read_b128 v[210:213], v241 offset:0
	v_mfma_f32_16x16x32_bf16 v[38:41], v[166:169], v[138:141], v[38:41]
	ds_read_b128 v[214:217], v241 offset:256
	v_mfma_f32_16x16x32_bf16 v[42:45], v[170:173], v[138:141], v[42:45]
	ds_read_b128 v[218:221], v241 offset:2048
	global_load_lds_dwordx4 v226, s[54:55] offset:1024
	v_mfma_f32_16x16x32_bf16 v[46:49], v[174:177], v[138:141], v[46:49]
	ds_read_b128 v[222:225], v241 offset:2304
	v_mfma_f32_16x16x32_bf16 v[50:53], v[162:165], v[142:145], v[50:53]
	ds_read_b128 v[178:181], v240 offset:0
	v_mfma_f32_16x16x32_bf16 v[54:57], v[166:169], v[142:145], v[54:57]
	ds_read_b128 v[182:185], v240 offset:1024
	v_mfma_f32_16x16x32_bf16 v[58:61], v[170:173], v[142:145], v[58:61]
	ds_read_b128 v[186:189], v240 offset:2048
	v_mfma_f32_16x16x32_bf16 v[62:65], v[174:177], v[142:145], v[62:65]
	ds_read_b128 v[190:193], v240 offset:3072
	global_load_lds_dwordx4 v226, s[54:55] offset:2048
	v_mfma_f32_16x16x32_bf16 v[66:69], v[162:165], v[146:149], v[66:69]
	ds_read_b128 v[194:197], v240 offset:4096
	v_mfma_f32_16x16x32_bf16 v[70:73], v[166:169], v[146:149], v[70:73]
	ds_read_b128 v[198:201], v240 offset:5120
	v_mfma_f32_16x16x32_bf16 v[74:77], v[170:173], v[146:149], v[74:77]
	ds_read_b128 v[202:205], v240 offset:6144
	v_mfma_f32_16x16x32_bf16 v[78:81], v[174:177], v[146:149], v[78:81]
	ds_read_b128 v[206:209], v240 offset:7168
	v_mfma_f32_16x16x32_bf16 v[82:85], v[162:165], v[150:153], v[82:85]
	global_load_lds_dwordx4 v226, s[54:55] offset:3072
	v_mfma_f32_16x16x32_bf16 v[86:89], v[166:169], v[150:153], v[86:89]
	v_mfma_f32_16x16x32_bf16 v[90:93], v[170:173], v[150:153], v[90:93]
	v_mfma_f32_16x16x32_bf16 v[94:97], v[174:177], v[150:153], v[94:97]
	v_mfma_f32_16x16x32_bf16 v[98:101], v[162:165], v[154:157], v[98:101]
	s_add_i32 m0, s60, s63
	v_mfma_f32_16x16x32_bf16 v[102:105], v[166:169], v[154:157], v[102:105]
	global_load_lds_dwordx4 v230, s[56:57]
	v_mfma_f32_16x16x32_bf16 v[106:109], v[170:173], v[154:157], v[106:109]
	v_mfma_f32_16x16x32_bf16 v[110:113], v[174:177], v[154:157], v[110:113]
	v_mfma_f32_16x16x32_bf16 v[114:117], v[162:165], v[158:161], v[114:117]
	v_mfma_f32_16x16x32_bf16 v[118:121], v[166:169], v[158:161], v[118:121]
	v_mfma_f32_16x16x32_bf16 v[122:125], v[170:173], v[158:161], v[122:125]
	global_load_lds_dwordx4 v231, s[56:57] offset:1024
	v_mfma_f32_16x16x32_bf16 v[126:129], v[174:177], v[158:161], v[126:129]
	s_setprio 0
	s_add_i32 s60, s60, 0x6000
	s_cmp_eq_u32 s60, 0x12000
	s_cselect_b32 s60, 0, s60
	s_add_u32 s54, s54, s72
	s_addc_u32 s55, s55, 0
	s_add_u32 s56, s56, s73
	s_addc_u32 s57, s57, 0
	s_add_i32 s61, s61, 0x6000
	s_cmp_eq_u32 s61, 0x12000
	s_cselect_b32 s61, 0, s61
	v_mov_b32_e32 v226, v232
	v_mov_b32_e32 v230, v236
	v_mov_b32_e32 v231, v237
	s_mov_b64 s[54:55], s[48:49]
	s_mov_b64 s[56:57], s[50:51]
	s_waitcnt lgkmcnt(0)
	v_add_u32_e32 v240, s61, v238
	v_add_u32_e32 v241, s61, v239
	s_setprio 1
	v_mfma_f32_16x16x32_bf16 v[2:5], v[210:213], v[178:181], v[2:5]
	v_mfma_f32_16x16x32_bf16 v[6:9], v[214:217], v[178:181], v[6:9]
	v_mfma_f32_16x16x32_bf16 v[10:13], v[218:221], v[178:181], v[10:13]
	v_mfma_f32_16x16x32_bf16 v[14:17], v[222:225], v[178:181], v[14:17]
	s_waitcnt vmcnt(6)
	s_barrier
	v_mfma_f32_16x16x32_bf16 v[18:21], v[210:213], v[182:185], v[18:21]
	s_add_i32 m0, s60, s62
	v_mfma_f32_16x16x32_bf16 v[22:25], v[214:217], v[182:185], v[22:25]
	global_load_lds_dwordx4 v226, s[54:55]
	v_mfma_f32_16x16x32_bf16 v[26:29], v[218:221], v[182:185], v[26:29]
	v_mfma_f32_16x16x32_bf16 v[30:33], v[222:225], v[182:185], v[30:33]
	v_mfma_f32_16x16x32_bf16 v[34:37], v[210:213], v[186:189], v[34:37]
	ds_read_b128 v[162:165], v241 offset:0
	v_mfma_f32_16x16x32_bf16 v[38:41], v[214:217], v[186:189], v[38:41]
	ds_read_b128 v[166:169], v241 offset:256
	v_mfma_f32_16x16x32_bf16 v[42:45], v[218:221], v[186:189], v[42:45]
	ds_read_b128 v[170:173], v241 offset:2048
	global_load_lds_dwordx4 v226, s[54:55] offset:1024
	v_mfma_f32_16x16x32_bf16 v[46:49], v[222:225], v[186:189], v[46:49]
	ds_read_b128 v[174:177], v241 offset:2304
	v_mfma_f32_16x16x32_bf16 v[50:53], v[210:213], v[190:193], v[50:53]
	ds_read_b128 v[130:133], v240 offset:0
	v_mfma_f32_16x16x32_bf16 v[54:57], v[214:217], v[190:193], v[54:57]
	ds_read_b128 v[134:137], v240 offset:1024
	v_mfma_f32_16x16x32_bf16 v[58:61], v[218:221], v[190:193], v[58:61]
	ds_read_b128 v[138:141], v240 offset:2048
	v_mfma_f32_16x16x32_bf16 v[62:65], v[222:225], v[190:193], v[62:65]
	ds_read_b128 v[142:145], v240 offset:3072
	global_load_lds_dwordx4 v226, s[54:55] offset:2048
	v_mfma_f32_16x16x32_bf16 v[66:69], v[210:213], v[194:197], v[66:69]
	ds_read_b128 v[146:149], v240 offset:4096
	v_mfma_f32_16x16x32_bf16 v[70:73], v[214:217], v[194:197], v[70:73]
	ds_read_b128 v[150:153], v240 offset:5120
	v_mfma_f32_16x16x32_bf16 v[74:77], v[218:221], v[194:197], v[74:77]
	ds_read_b128 v[154:157], v240 offset:6144
	v_mfma_f32_16x16x32_bf16 v[78:81], v[222:225], v[194:197], v[78:81]
	ds_read_b128 v[158:161], v240 offset:7168
	v_mfma_f32_16x16x32_bf16 v[82:85], v[210:213], v[198:201], v[82:85]
	global_load_lds_dwordx4 v226, s[54:55] offset:3072
	v_mfma_f32_16x16x32_bf16 v[86:89], v[214:217], v[198:201], v[86:89]
	v_mfma_f32_16x16x32_bf16 v[90:93], v[218:221], v[198:201], v[90:93]
	v_mfma_f32_16x16x32_bf16 v[94:97], v[222:225], v[198:201], v[94:97]
	v_mfma_f32_16x16x32_bf16 v[98:101], v[210:213], v[202:205], v[98:101]
	s_add_i32 m0, s60, s63
	v_mfma_f32_16x16x32_bf16 v[102:105], v[214:217], v[202:205], v[102:105]
	global_load_lds_dwordx4 v230, s[56:57]
	v_mfma_f32_16x16x32_bf16 v[106:109], v[218:221], v[202:205], v[106:109]
	v_mfma_f32_16x16x32_bf16 v[110:113], v[222:225], v[202:205], v[110:113]
	v_mfma_f32_16x16x32_bf16 v[114:117], v[210:213], v[206:209], v[114:117]
	v_mfma_f32_16x16x32_bf16 v[118:121], v[214:217], v[206:209], v[118:121]
	v_mfma_f32_16x16x32_bf16 v[122:125], v[218:221], v[206:209], v[122:125]
	global_load_lds_dwordx4 v231, s[56:57] offset:1024
	v_mfma_f32_16x16x32_bf16 v[126:129], v[222:225], v[206:209], v[126:129]
	s_setprio 0
	s_add_i32 s60, s60, 0x6000
	s_cmp_eq_u32 s60, 0x12000
	s_cselect_b32 s60, 0, s60
	s_add_u32 s54, s54, s72
	s_addc_u32 s55, s55, 0
	s_add_u32 s56, s56, s73
	s_addc_u32 s57, s57, 0
	s_add_i32 s61, s61, 0x6000
	s_cmp_eq_u32 s61, 0x12000
	s_cselect_b32 s61, 0, s61
	s_waitcnt lgkmcnt(0)
	v_add_u32_e32 v240, s61, v238
	v_add_u32_e32 v241, s61, v239
	s_setprio 1
	v_mfma_f32_16x16x32_bf16 v[2:5], v[162:165], v[130:133], v[2:5]
	v_mfma_f32_16x16x32_bf16 v[6:9], v[166:169], v[130:133], v[6:9]
	v_mfma_f32_16x16x32_bf16 v[10:13], v[170:173], v[130:133], v[10:13]
	v_mfma_f32_16x16x32_bf16 v[14:17], v[174:177], v[130:133], v[14:17]
	s_waitcnt vmcnt(6)
	s_barrier
	v_mfma_f32_16x16x32_bf16 v[18:21], v[162:165], v[134:137], v[18:21]
	s_add_i32 m0, s60, s62
	v_mfma_f32_16x16x32_bf16 v[22:25], v[166:169], v[134:137], v[22:25]
	global_load_lds_dwordx4 v226, s[54:55]
	v_mfma_f32_16x16x32_bf16 v[26:29], v[170:173], v[134:137], v[26:29]
	v_mfma_f32_16x16x32_bf16 v[30:33], v[174:177], v[134:137], v[30:33]
	v_mfma_f32_16x16x32_bf16 v[34:37], v[162:165], v[138:141], v[34:37]
	ds_read_b128 v[210:213], v241 offset:0
	v_mfma_f32_16x16x32_bf16 v[38:41], v[166:169], v[138:141], v[38:41]
	ds_read_b128 v[214:217], v241 offset:256
	v_mfma_f32_16x16x32_bf16 v[42:45], v[170:173], v[138:141], v[42:45]
	ds_read_b128 v[218:221], v241 offset:2048
	global_load_lds_dwordx4 v226, s[54:55] offset:1024
	v_mfma_f32_16x16x32_bf16 v[46:49], v[174:177], v[138:141], v[46:49]
	ds_read_b128 v[222:225], v241 offset:2304
	v_mfma_f32_16x16x32_bf16 v[50:53], v[162:165], v[142:145], v[50:53]
	ds_read_b128 v[178:181], v240 offset:0
	v_mfma_f32_16x16x32_bf16 v[54:57], v[166:169], v[142:145], v[54:57]
	ds_read_b128 v[182:185], v240 offset:1024
	v_mfma_f32_16x16x32_bf16 v[58:61], v[170:173], v[142:145], v[58:61]
	ds_read_b128 v[186:189], v240 offset:2048
	v_mfma_f32_16x16x32_bf16 v[62:65], v[174:177], v[142:145], v[62:65]
	ds_read_b128 v[190:193], v240 offset:3072
	global_load_lds_dwordx4 v226, s[54:55] offset:2048
	v_mfma_f32_16x16x32_bf16 v[66:69], v[162:165], v[146:149], v[66:69]
	ds_read_b128 v[194:197], v240 offset:4096
	v_mfma_f32_16x16x32_bf16 v[70:73], v[166:169], v[146:149], v[70:73]
	ds_read_b128 v[198:201], v240 offset:5120
	v_mfma_f32_16x16x32_bf16 v[74:77], v[170:173], v[146:149], v[74:77]
	ds_read_b128 v[202:205], v240 offset:6144
	v_mfma_f32_16x16x32_bf16 v[78:81], v[174:177], v[146:149], v[78:81]
	ds_read_b128 v[206:209], v240 offset:7168
	v_mfma_f32_16x16x32_bf16 v[82:85], v[162:165], v[150:153], v[82:85]
	global_load_lds_dwordx4 v226, s[54:55] offset:3072
	v_mfma_f32_16x16x32_bf16 v[86:89], v[166:169], v[150:153], v[86:89]
	v_mfma_f32_16x16x32_bf16 v[90:93], v[170:173], v[150:153], v[90:93]
	v_mfma_f32_16x16x32_bf16 v[94:97], v[174:177], v[150:153], v[94:97]
	v_mfma_f32_16x16x32_bf16 v[98:101], v[162:165], v[154:157], v[98:101]
	s_add_i32 m0, s60, s63
	v_mfma_f32_16x16x32_bf16 v[102:105], v[166:169], v[154:157], v[102:105]
	global_load_lds_dwordx4 v230, s[56:57]
	v_mfma_f32_16x16x32_bf16 v[106:109], v[170:173], v[154:157], v[106:109]
	v_mfma_f32_16x16x32_bf16 v[110:113], v[174:177], v[154:157], v[110:113]
	v_mfma_f32_16x16x32_bf16 v[114:117], v[162:165], v[158:161], v[114:117]
	v_mfma_f32_16x16x32_bf16 v[118:121], v[166:169], v[158:161], v[118:121]
	v_mfma_f32_16x16x32_bf16 v[122:125], v[170:173], v[158:161], v[122:125]
	global_load_lds_dwordx4 v231, s[56:57] offset:1024
	v_mfma_f32_16x16x32_bf16 v[126:129], v[174:177], v[158:161], v[126:129]
	s_setprio 0
	s_add_i32 s60, s60, 0x6000
	s_cmp_eq_u32 s60, 0x12000
	s_cselect_b32 s60, 0, s60
	s_add_u32 s54, s54, s72
	s_addc_u32 s55, s55, 0
	s_add_u32 s56, s56, s73
	s_addc_u32 s57, s57, 0
	s_add_i32 s61, s61, 0x6000
	s_cmp_eq_u32 s61, 0x12000
	s_cselect_b32 s61, 0, s61
	s_waitcnt lgkmcnt(0)
	v_add_u32_e32 v240, s61, v238
	v_add_u32_e32 v241, s61, v239
	s_setprio 1
	v_mfma_f32_16x16x32_bf16 v[2:5], v[210:213], v[178:181], v[2:5]
	v_mfma_f32_16x16x32_bf16 v[6:9], v[214:217], v[178:181], v[6:9]
	v_mfma_f32_16x16x32_bf16 v[10:13], v[218:221], v[178:181], v[10:13]
	v_mfma_f32_16x16x32_bf16 v[14:17], v[222:225], v[178:181], v[14:17]
	s_waitcnt vmcnt(6)
	s_barrier
	v_mfma_f32_16x16x32_bf16 v[18:21], v[210:213], v[182:185], v[18:21]
	s_add_i32 m0, s60, s62
	v_mfma_f32_16x16x32_bf16 v[22:25], v[214:217], v[182:185], v[22:25]
	global_load_lds_dwordx4 v226, s[54:55]
	v_mfma_f32_16x16x32_bf16 v[26:29], v[218:221], v[182:185], v[26:29]
	v_mfma_f32_16x16x32_bf16 v[30:33], v[222:225], v[182:185], v[30:33]
	v_mfma_f32_16x16x32_bf16 v[34:37], v[210:213], v[186:189], v[34:37]
	ds_read_b128 v[162:165], v241 offset:0
	v_mfma_f32_16x16x32_bf16 v[38:41], v[214:217], v[186:189], v[38:41]
	ds_read_b128 v[166:169], v241 offset:256
	v_mfma_f32_16x16x32_bf16 v[42:45], v[218:221], v[186:189], v[42:45]
	ds_read_b128 v[170:173], v241 offset:2048
	global_load_lds_dwordx4 v226, s[54:55] offset:1024
	v_mfma_f32_16x16x32_bf16 v[46:49], v[222:225], v[186:189], v[46:49]
	ds_read_b128 v[174:177], v241 offset:2304
	v_mfma_f32_16x16x32_bf16 v[50:53], v[210:213], v[190:193], v[50:53]
	ds_read_b128 v[130:133], v240 offset:0
	v_mfma_f32_16x16x32_bf16 v[54:57], v[214:217], v[190:193], v[54:57]
	ds_read_b128 v[134:137], v240 offset:1024
	v_mfma_f32_16x16x32_bf16 v[58:61], v[218:221], v[190:193], v[58:61]
	ds_read_b128 v[138:141], v240 offset:2048
	v_mfma_f32_16x16x32_bf16 v[62:65], v[222:225], v[190:193], v[62:65]
	ds_read_b128 v[142:145], v240 offset:3072
	global_load_lds_dwordx4 v226, s[54:55] offset:2048
	v_mfma_f32_16x16x32_bf16 v[66:69], v[210:213], v[194:197], v[66:69]
	ds_read_b128 v[146:149], v240 offset:4096
	v_mfma_f32_16x16x32_bf16 v[70:73], v[214:217], v[194:197], v[70:73]
	ds_read_b128 v[150:153], v240 offset:5120
	v_mfma_f32_16x16x32_bf16 v[74:77], v[218:221], v[194:197], v[74:77]
	ds_read_b128 v[154:157], v240 offset:6144
	v_mfma_f32_16x16x32_bf16 v[78:81], v[222:225], v[194:197], v[78:81]
	ds_read_b128 v[158:161], v240 offset:7168
	v_mfma_f32_16x16x32_bf16 v[82:85], v[210:213], v[198:201], v[82:85]
	global_load_lds_dwordx4 v226, s[54:55] offset:3072
	v_mfma_f32_16x16x32_bf16 v[86:89], v[214:217], v[198:201], v[86:89]
	v_mfma_f32_16x16x32_bf16 v[90:93], v[218:221], v[198:201], v[90:93]
	v_mfma_f32_16x16x32_bf16 v[94:97], v[222:225], v[198:201], v[94:97]
	v_mfma_f32_16x16x32_bf16 v[98:101], v[210:213], v[202:205], v[98:101]
	s_add_i32 m0, s60, s63
	v_mfma_f32_16x16x32_bf16 v[102:105], v[214:217], v[202:205], v[102:105]
	global_load_lds_dwordx4 v230, s[56:57]
	v_mfma_f32_16x16x32_bf16 v[106:109], v[218:221], v[202:205], v[106:109]
	v_mfma_f32_16x16x32_bf16 v[110:113], v[222:225], v[202:205], v[110:113]
	v_mfma_f32_16x16x32_bf16 v[114:117], v[210:213], v[206:209], v[114:117]
	v_mfma_f32_16x16x32_bf16 v[118:121], v[214:217], v[206:209], v[118:121]
	v_mfma_f32_16x16x32_bf16 v[122:125], v[218:221], v[206:209], v[122:125]
	global_load_lds_dwordx4 v231, s[56:57] offset:1024
	v_mfma_f32_16x16x32_bf16 v[126:129], v[222:225], v[206:209], v[126:129]
	s_setprio 0
	s_add_i32 s60, s60, 0x6000
	s_cmp_eq_u32 s60, 0x12000
	s_cselect_b32 s60, 0, s60
	s_add_u32 s54, s54, s72
	s_addc_u32 s55, s55, 0
	s_add_u32 s56, s56, s73
	s_addc_u32 s57, s57, 0
	s_add_i32 s61, s61, 0x6000
	s_cmp_eq_u32 s61, 0x12000
	s_cselect_b32 s61, 0, s61
	s_and_b32 s39, s35, 0xfff
	s_lshr_b32 s21, s36, 7
	s_waitcnt vmcnt(18)
	v_mbcnt_lo_u32_b32 v217, -1, 0
	v_mbcnt_hi_u32_b32 v217, -1, v217
	v_lshlrev_b32_e32 v217, 5, v217
	s_lshl_b32 s26, s43, 11
	v_add_u32_e32 v248, s26, v217
	s_add_i32 s26, s26, 0x12010
	v_add_u32_e32 v217, s26, v217
	s_cmp_eq_u32 s42, 0
	s_cbranch_scc0 .Lup_en_nowr
	ds_write_b128 v217, v[114:117]
	ds_write_b128 v217, v[118:121] offset:16
	s_branch .Lup_en_wrd

.Lup_tail_last:
	s_waitcnt lgkmcnt(0)
	v_add_u32_e32 v240, s61, v238
	v_add_u32_e32 v241, s61, v239
	s_setprio 1
	v_mfma_f32_16x16x32_bf16 v[2:5], v[162:165], v[130:133], v[2:5]
	v_mfma_f32_16x16x32_bf16 v[6:9], v[166:169], v[130:133], v[6:9]
	v_mfma_f32_16x16x32_bf16 v[10:13], v[170:173], v[130:133], v[10:13]
	v_mfma_f32_16x16x32_bf16 v[14:17], v[174:177], v[130:133], v[14:17]
	s_waitcnt vmcnt(6)
	s_barrier
	v_mfma_f32_16x16x32_bf16 v[18:21], v[162:165], v[134:137], v[18:21]
	s_add_i32 m0, s60, s62
	v_mfma_f32_16x16x32_bf16 v[22:25], v[166:169], v[134:137], v[22:25]
	global_load_lds_dwordx4 v226, s[54:55]
	v_mfma_f32_16x16x32_bf16 v[26:29], v[170:173], v[134:137], v[26:29]
	v_mfma_f32_16x16x32_bf16 v[30:33], v[174:177], v[134:137], v[30:33]
	v_mfma_f32_16x16x32_bf16 v[34:37], v[162:165], v[138:141], v[34:37]
	ds_read_b128 v[210:213], v241 offset:0
	v_mfma_f32_16x16x32_bf16 v[38:41], v[166:169], v[138:141], v[38:41]
	ds_read_b128 v[214:217], v241 offset:256
	v_mfma_f32_16x16x32_bf16 v[42:45], v[170:173], v[138:141], v[42:45]
	ds_read_b128 v[218:221], v241 offset:2048
	global_load_lds_dwordx4 v226, s[54:55] offset:1024
	v_mfma_f32_16x16x32_bf16 v[46:49], v[174:177], v[138:141], v[46:49]
	ds_read_b128 v[222:225], v241 offset:2304
	v_mfma_f32_16x16x32_bf16 v[50:53], v[162:165], v[142:145], v[50:53]
	ds_read_b128 v[178:181], v240 offset:0
	v_mfma_f32_16x16x32_bf16 v[54:57], v[166:169], v[142:145], v[54:57]
	ds_read_b128 v[182:185], v240 offset:1024
	v_mfma_f32_16x16x32_bf16 v[58:61], v[170:173], v[142:145], v[58:61]
	ds_read_b128 v[186:189], v240 offset:2048
	v_mfma_f32_16x16x32_bf16 v[62:65], v[174:177], v[142:145], v[62:65]
	ds_read_b128 v[190:193], v240 offset:3072
	global_load_lds_dwordx4 v226, s[54:55] offset:2048
	v_mfma_f32_16x16x32_bf16 v[66:69], v[162:165], v[146:149], v[66:69]
	ds_read_b128 v[194:197], v240 offset:4096
	v_mfma_f32_16x16x32_bf16 v[70:73], v[166:169], v[146:149], v[70:73]
	ds_read_b128 v[198:201], v240 offset:5120
	v_mfma_f32_16x16x32_bf16 v[74:77], v[170:173], v[146:149], v[74:77]
	ds_read_b128 v[202:205], v240 offset:6144
	v_mfma_f32_16x16x32_bf16 v[78:81], v[174:177], v[146:149], v[78:81]
	ds_read_b128 v[206:209], v240 offset:7168
	v_mfma_f32_16x16x32_bf16 v[82:85], v[162:165], v[150:153], v[82:85]
	global_load_lds_dwordx4 v226, s[54:55] offset:3072
	v_mfma_f32_16x16x32_bf16 v[86:89], v[166:169], v[150:153], v[86:89]
	v_mfma_f32_16x16x32_bf16 v[90:93], v[170:173], v[150:153], v[90:93]
	v_mfma_f32_16x16x32_bf16 v[94:97], v[174:177], v[150:153], v[94:97]
	v_mfma_f32_16x16x32_bf16 v[98:101], v[162:165], v[154:157], v[98:101]
	s_add_i32 m0, s60, s63
	v_mfma_f32_16x16x32_bf16 v[102:105], v[166:169], v[154:157], v[102:105]
	global_load_lds_dwordx4 v230, s[56:57]
	v_mfma_f32_16x16x32_bf16 v[106:109], v[170:173], v[154:157], v[106:109]
	v_mfma_f32_16x16x32_bf16 v[110:113], v[174:177], v[154:157], v[110:113]
	v_mfma_f32_16x16x32_bf16 v[114:117], v[162:165], v[158:161], v[114:117]
	v_mfma_f32_16x16x32_bf16 v[118:121], v[166:169], v[158:161], v[118:121]
	v_mfma_f32_16x16x32_bf16 v[122:125], v[170:173], v[158:161], v[122:125]
	global_load_lds_dwordx4 v231, s[56:57] offset:1024
	v_mfma_f32_16x16x32_bf16 v[126:129], v[174:177], v[158:161], v[126:129]
	s_setprio 0
	s_add_i32 s60, s60, 0x6000
	s_cmp_eq_u32 s60, 0x12000
	s_cselect_b32 s60, 0, s60
	s_add_u32 s54, s54, s72
	s_addc_u32 s55, s55, 0
	s_add_u32 s56, s56, s73
	s_addc_u32 s57, s57, 0
	s_add_i32 s61, s61, 0x6000
	s_cmp_eq_u32 s61, 0x12000
	s_cselect_b32 s61, 0, s61
	s_waitcnt lgkmcnt(0)
	v_add_u32_e32 v240, s61, v238
	v_add_u32_e32 v241, s61, v239
	s_setprio 1
	v_mfma_f32_16x16x32_bf16 v[2:5], v[210:213], v[178:181], v[2:5]
	v_mfma_f32_16x16x32_bf16 v[6:9], v[214:217], v[178:181], v[6:9]
	v_mfma_f32_16x16x32_bf16 v[10:13], v[218:221], v[178:181], v[10:13]
	v_mfma_f32_16x16x32_bf16 v[14:17], v[222:225], v[178:181], v[14:17]
	s_waitcnt vmcnt(6)
	s_barrier
	v_mfma_f32_16x16x32_bf16 v[18:21], v[210:213], v[182:185], v[18:21]
	v_mfma_f32_16x16x32_bf16 v[22:25], v[214:217], v[182:185], v[22:25]
	v_mfma_f32_16x16x32_bf16 v[26:29], v[218:221], v[182:185], v[26:29]
	v_mfma_f32_16x16x32_bf16 v[30:33], v[222:225], v[182:185], v[30:33]
	v_mfma_f32_16x16x32_bf16 v[34:37], v[210:213], v[186:189], v[34:37]
	ds_read_b128 v[162:165], v241 offset:0
	v_mfma_f32_16x16x32_bf16 v[38:41], v[214:217], v[186:189], v[38:41]
	ds_read_b128 v[166:169], v241 offset:256
	v_mfma_f32_16x16x32_bf16 v[42:45], v[218:221], v[186:189], v[42:45]
	ds_read_b128 v[170:173], v241 offset:2048
	v_mfma_f32_16x16x32_bf16 v[46:49], v[222:225], v[186:189], v[46:49]
	ds_read_b128 v[174:177], v241 offset:2304
	v_mfma_f32_16x16x32_bf16 v[50:53], v[210:213], v[190:193], v[50:53]
	ds_read_b128 v[130:133], v240 offset:0
	v_mfma_f32_16x16x32_bf16 v[54:57], v[214:217], v[190:193], v[54:57]
	ds_read_b128 v[134:137], v240 offset:1024
	v_mfma_f32_16x16x32_bf16 v[58:61], v[218:221], v[190:193], v[58:61]
	ds_read_b128 v[138:141], v240 offset:2048
	v_mfma_f32_16x16x32_bf16 v[62:65], v[222:225], v[190:193], v[62:65]
	ds_read_b128 v[142:145], v240 offset:3072
	v_mfma_f32_16x16x32_bf16 v[66:69], v[210:213], v[194:197], v[66:69]
	ds_read_b128 v[146:149], v240 offset:4096
	v_mfma_f32_16x16x32_bf16 v[70:73], v[214:217], v[194:197], v[70:73]
	ds_read_b128 v[150:153], v240 offset:5120
	v_mfma_f32_16x16x32_bf16 v[74:77], v[218:221], v[194:197], v[74:77]
	ds_read_b128 v[154:157], v240 offset:6144
	v_mfma_f32_16x16x32_bf16 v[78:81], v[222:225], v[194:197], v[78:81]
	ds_read_b128 v[158:161], v240 offset:7168
	v_mfma_f32_16x16x32_bf16 v[82:85], v[210:213], v[198:201], v[82:85]
	v_mfma_f32_16x16x32_bf16 v[86:89], v[214:217], v[198:201], v[86:89]
	v_mfma_f32_16x16x32_bf16 v[90:93], v[218:221], v[198:201], v[90:93]
	v_mfma_f32_16x16x32_bf16 v[94:97], v[222:225], v[198:201], v[94:97]
	v_mfma_f32_16x16x32_bf16 v[98:101], v[210:213], v[202:205], v[98:101]
	v_mfma_f32_16x16x32_bf16 v[102:105], v[214:217], v[202:205], v[102:105]
	v_mfma_f32_16x16x32_bf16 v[106:109], v[218:221], v[202:205], v[106:109]
	v_mfma_f32_16x16x32_bf16 v[110:113], v[222:225], v[202:205], v[110:113]
	v_mfma_f32_16x16x32_bf16 v[114:117], v[210:213], v[206:209], v[114:117]
	v_mfma_f32_16x16x32_bf16 v[118:121], v[214:217], v[206:209], v[118:121]
	v_mfma_f32_16x16x32_bf16 v[122:125], v[218:221], v[206:209], v[122:125]
	v_mfma_f32_16x16x32_bf16 v[126:129], v[222:225], v[206:209], v[126:129]
	s_setprio 0
	s_add_i32 s61, s61, 0x6000
	s_cmp_eq_u32 s61, 0x12000
	s_cselect_b32 s61, 0, s61
	s_waitcnt lgkmcnt(0)
	v_add_u32_e32 v240, s61, v238
	v_add_u32_e32 v241, s61, v239
	s_setprio 1
	v_mfma_f32_16x16x32_bf16 v[2:5], v[162:165], v[130:133], v[2:5]
	v_mfma_f32_16x16x32_bf16 v[6:9], v[166:169], v[130:133], v[6:9]
	v_mfma_f32_16x16x32_bf16 v[10:13], v[170:173], v[130:133], v[10:13]
	v_mfma_f32_16x16x32_bf16 v[14:17], v[174:177], v[130:133], v[14:17]
	s_waitcnt vmcnt(0)
	s_barrier
	v_mfma_f32_16x16x32_bf16 v[18:21], v[162:165], v[134:137], v[18:21]
	v_mfma_f32_16x16x32_bf16 v[22:25], v[166:169], v[134:137], v[22:25]
	v_mfma_f32_16x16x32_bf16 v[26:29], v[170:173], v[134:137], v[26:29]
	v_mfma_f32_16x16x32_bf16 v[30:33], v[174:177], v[134:137], v[30:33]
	v_mfma_f32_16x16x32_bf16 v[34:37], v[162:165], v[138:141], v[34:37]
	ds_read_b128 v[210:213], v241 offset:0
	v_mfma_f32_16x16x32_bf16 v[38:41], v[166:169], v[138:141], v[38:41]
	ds_read_b128 v[214:217], v241 offset:256
	v_mfma_f32_16x16x32_bf16 v[42:45], v[170:173], v[138:141], v[42:45]
	ds_read_b128 v[218:221], v241 offset:2048
	v_mfma_f32_16x16x32_bf16 v[46:49], v[174:177], v[138:141], v[46:49]
	ds_read_b128 v[222:225], v241 offset:2304
	v_mfma_f32_16x16x32_bf16 v[50:53], v[162:165], v[142:145], v[50:53]
	ds_read_b128 v[178:181], v240 offset:0
	v_mfma_f32_16x16x32_bf16 v[54:57], v[166:169], v[142:145], v[54:57]
	ds_read_b128 v[182:185], v240 offset:1024
	v_mfma_f32_16x16x32_bf16 v[58:61], v[170:173], v[142:145], v[58:61]
	ds_read_b128 v[186:189], v240 offset:2048
	v_mfma_f32_16x16x32_bf16 v[62:65], v[174:177], v[142:145], v[62:65]
	ds_read_b128 v[190:193], v240 offset:3072
	v_mfma_f32_16x16x32_bf16 v[66:69], v[162:165], v[146:149], v[66:69]
	ds_read_b128 v[194:197], v240 offset:4096
	v_mfma_f32_16x16x32_bf16 v[70:73], v[166:169], v[146:149], v[70:73]
	ds_read_b128 v[198:201], v240 offset:5120
	v_mfma_f32_16x16x32_bf16 v[74:77], v[170:173], v[146:149], v[74:77]
	ds_read_b128 v[202:205], v240 offset:6144
	v_mfma_f32_16x16x32_bf16 v[78:81], v[174:177], v[146:149], v[78:81]
	ds_read_b128 v[206:209], v240 offset:7168
	v_mfma_f32_16x16x32_bf16 v[82:85], v[162:165], v[150:153], v[82:85]
	v_mfma_f32_16x16x32_bf16 v[86:89], v[166:169], v[150:153], v[86:89]
	v_mfma_f32_16x16x32_bf16 v[90:93], v[170:173], v[150:153], v[90:93]
	v_mfma_f32_16x16x32_bf16 v[94:97], v[174:177], v[150:153], v[94:97]
	v_mfma_f32_16x16x32_bf16 v[98:101], v[162:165], v[154:157], v[98:101]
	v_mfma_f32_16x16x32_bf16 v[102:105], v[166:169], v[154:157], v[102:105]
	v_mfma_f32_16x16x32_bf16 v[106:109], v[170:173], v[154:157], v[106:109]
	v_mfma_f32_16x16x32_bf16 v[110:113], v[174:177], v[154:157], v[110:113]
	v_mfma_f32_16x16x32_bf16 v[114:117], v[162:165], v[158:161], v[114:117]
	v_mfma_f32_16x16x32_bf16 v[118:121], v[166:169], v[158:161], v[118:121]
	v_mfma_f32_16x16x32_bf16 v[122:125], v[170:173], v[158:161], v[122:125]
	v_mfma_f32_16x16x32_bf16 v[126:129], v[174:177], v[158:161], v[126:129]
	s_setprio 0
	s_add_i32 s61, s61, 0x6000
	s_cmp_eq_u32 s61, 0x12000
	s_cselect_b32 s61, 0, s61
	s_waitcnt lgkmcnt(0)
	s_setprio 1
	v_mfma_f32_16x16x32_bf16 v[2:5], v[210:213], v[178:181], v[2:5]
	v_mfma_f32_16x16x32_bf16 v[6:9], v[214:217], v[178:181], v[6:9]
	v_mfma_f32_16x16x32_bf16 v[10:13], v[218:221], v[178:181], v[10:13]
	v_mfma_f32_16x16x32_bf16 v[14:17], v[222:225], v[178:181], v[14:17]
	s_barrier
	v_mfma_f32_16x16x32_bf16 v[18:21], v[210:213], v[182:185], v[18:21]
	v_mfma_f32_16x16x32_bf16 v[22:25], v[214:217], v[182:185], v[22:25]
	v_mfma_f32_16x16x32_bf16 v[26:29], v[218:221], v[182:185], v[26:29]
	v_mfma_f32_16x16x32_bf16 v[30:33], v[222:225], v[182:185], v[30:33]
	v_mfma_f32_16x16x32_bf16 v[34:37], v[210:213], v[186:189], v[34:37]
	v_mfma_f32_16x16x32_bf16 v[38:41], v[214:217], v[186:189], v[38:41]
	v_mfma_f32_16x16x32_bf16 v[42:45], v[218:221], v[186:189], v[42:45]
	v_mfma_f32_16x16x32_bf16 v[46:49], v[222:225], v[186:189], v[46:49]
	v_mfma_f32_16x16x32_bf16 v[50:53], v[210:213], v[190:193], v[50:53]
	v_mfma_f32_16x16x32_bf16 v[54:57], v[214:217], v[190:193], v[54:57]
	v_mfma_f32_16x16x32_bf16 v[58:61], v[218:221], v[190:193], v[58:61]
	v_mfma_f32_16x16x32_bf16 v[62:65], v[222:225], v[190:193], v[62:65]
	v_mfma_f32_16x16x32_bf16 v[66:69], v[210:213], v[194:197], v[66:69]
	v_mfma_f32_16x16x32_bf16 v[70:73], v[214:217], v[194:197], v[70:73]
	v_mfma_f32_16x16x32_bf16 v[74:77], v[218:221], v[194:197], v[74:77]
	v_mfma_f32_16x16x32_bf16 v[78:81], v[222:225], v[194:197], v[78:81]
	v_mfma_f32_16x16x32_bf16 v[82:85], v[210:213], v[198:201], v[82:85]
	v_mfma_f32_16x16x32_bf16 v[86:89], v[214:217], v[198:201], v[86:89]
	v_mfma_f32_16x16x32_bf16 v[90:93], v[218:221], v[198:201], v[90:93]
	v_mfma_f32_16x16x32_bf16 v[94:97], v[222:225], v[198:201], v[94:97]
	v_mfma_f32_16x16x32_bf16 v[98:101], v[210:213], v[202:205], v[98:101]
	v_mfma_f32_16x16x32_bf16 v[102:105], v[214:217], v[202:205], v[102:105]
	v_mfma_f32_16x16x32_bf16 v[106:109], v[218:221], v[202:205], v[106:109]
	v_mfma_f32_16x16x32_bf16 v[110:113], v[222:225], v[202:205], v[110:113]
	v_mfma_f32_16x16x32_bf16 v[114:117], v[210:213], v[206:209], v[114:117]
	v_mfma_f32_16x16x32_bf16 v[118:121], v[214:217], v[206:209], v[118:121]
	v_mfma_f32_16x16x32_bf16 v[122:125], v[218:221], v[206:209], v[122:125]
	v_mfma_f32_16x16x32_bf16 v[126:129], v[222:225], v[206:209], v[126:129]
	s_setprio 0
	s_and_b32 s39, s35, 0xfff
	s_lshr_b32 s21, s36, 7
	s_waitcnt vmcnt(0)
	v_mbcnt_lo_u32_b32 v217, -1, 0
	v_mbcnt_hi_u32_b32 v217, -1, v217
	v_lshlrev_b32_e32 v217, 5, v217
	s_lshl_b32 s26, s43, 11
	v_add_u32_e32 v248, s26, v217
	s_add_i32 s26, s26, 0x12010
	v_add_u32_e32 v217, s26, v217
	s_cmp_eq_u32 s42, 0
	s_cbranch_scc0 .Lup_el_nowr
	ds_write_b128 v217, v[114:117]
	ds_write_b128 v217, v[118:121] offset:16
	s_branch .Lup_el_wrd

.Lpj_nn_a:
	s_waitcnt lgkmcnt(0)
	v_add_u32_e32 v240, s61, v238
	v_add_u32_e32 v241, s61, v239
	s_setprio 1
	v_mfma_f32_16x16x32_bf16 v[2:5], v[162:165], v[130:133], 0
	v_mfma_f32_16x16x32_bf16 v[6:9], v[166:169], v[130:133], 0
	v_mfma_f32_16x16x32_bf16 v[10:13], v[170:173], v[130:133], 0
	v_mfma_f32_16x16x32_bf16 v[14:17], v[174:177], v[130:133], 0
	s_waitcnt vmcnt(6)
	s_barrier
	v_mfma_f32_16x16x32_bf16 v[18:21], v[162:165], v[134:137], 0
	s_add_i32 m0, s60, s62
	v_mfma_f32_16x16x32_bf16 v[22:25], v[166:169], v[134:137], 0
	global_load_lds_dwordx4 v226, s[54:55]
	v_mfma_f32_16x16x32_bf16 v[26:29], v[170:173], v[134:137], 0
	v_mfma_f32_16x16x32_bf16 v[30:33], v[174:177], v[134:137], 0
	v_mfma_f32_16x16x32_bf16 v[34:37], v[162:165], v[138:141], 0
	ds_read_b128 v[210:213], v241 offset:0
	v_mfma_f32_16x16x32_bf16 v[38:41], v[166:169], v[138:141], 0
	ds_read_b128 v[214:217], v241 offset:256
	v_mfma_f32_16x16x32_bf16 v[42:45], v[170:173], v[138:141], 0
	ds_read_b128 v[218:221], v241 offset:2048
	global_load_lds_dwordx4 v226, s[54:55] offset:1024
	v_mfma_f32_16x16x32_bf16 v[46:49], v[174:177], v[138:141], 0
	ds_read_b128 v[222:225], v241 offset:2304
	v_mfma_f32_16x16x32_bf16 v[50:53], v[162:165], v[142:145], 0
	ds_read_b128 v[178:181], v240 offset:0
	v_mfma_f32_16x16x32_bf16 v[54:57], v[166:169], v[142:145], 0
	ds_read_b128 v[182:185], v240 offset:1024
	v_mfma_f32_16x16x32_bf16 v[58:61], v[170:173], v[142:145], 0
	ds_read_b128 v[186:189], v240 offset:2048
	v_mfma_f32_16x16x32_bf16 v[62:65], v[174:177], v[142:145], 0
	ds_read_b128 v[190:193], v240 offset:3072
	global_load_lds_dwordx4 v226, s[54:55] offset:2048
	v_mfma_f32_16x16x32_bf16 v[66:69], v[162:165], v[146:149], 0
	ds_read_b128 v[194:197], v240 offset:4096
	v_mfma_f32_16x16x32_bf16 v[70:73], v[166:169], v[146:149], 0
	ds_read_b128 v[198:201], v240 offset:5120
	v_mfma_f32_16x16x32_bf16 v[74:77], v[170:173], v[146:149], 0
	ds_read_b128 v[202:205], v240 offset:6144
	v_mfma_f32_16x16x32_bf16 v[78:81], v[174:177], v[146:149], 0
	ds_read_b128 v[206:209], v240 offset:7168
	v_mfma_f32_16x16x32_bf16 v[82:85], v[162:165], v[150:153], 0
	global_load_lds_dwordx4 v226, s[54:55] offset:3072
	v_mfma_f32_16x16x32_bf16 v[86:89], v[166:169], v[150:153], 0
	v_mfma_f32_16x16x32_bf16 v[90:93], v[170:173], v[150:153], 0
	v_mfma_f32_16x16x32_bf16 v[94:97], v[174:177], v[150:153], 0
	v_mfma_f32_16x16x32_bf16 v[98:101], v[162:165], v[154:157], 0
	s_add_i32 m0, s60, s63
	v_mfma_f32_16x16x32_bf16 v[102:105], v[166:169], v[154:157], 0
	global_load_lds_dwordx4 v230, s[56:57]
	v_mfma_f32_16x16x32_bf16 v[106:109], v[170:173], v[154:157], 0
	v_mfma_f32_16x16x32_bf16 v[110:113], v[174:177], v[154:157], 0
	v_mfma_f32_16x16x32_bf16 v[114:117], v[162:165], v[158:161], 0
	v_mfma_f32_16x16x32_bf16 v[118:121], v[166:169], v[158:161], 0
	v_mfma_f32_16x16x32_bf16 v[122:125], v[170:173], v[158:161], 0
	global_load_lds_dwordx4 v231, s[56:57] offset:1024
	v_mfma_f32_16x16x32_bf16 v[126:129], v[174:177], v[158:161], 0
	s_setprio 0
	s_add_i32 s60, s60, 0x6000
	s_cmp_eq_u32 s60, 0x12000
	s_cselect_b32 s60, 0, s60
	s_add_u32 s54, s54, s72
	s_addc_u32 s55, s55, 0
	s_add_u32 s56, s56, s73
	s_addc_u32 s57, s57, 0
	s_add_i32 s61, s61, 0x6000
	s_cmp_eq_u32 s61, 0x12000
	s_cselect_b32 s61, 0, s61
	s_waitcnt lgkmcnt(0)
	v_add_u32_e32 v240, s61, v238
	v_add_u32_e32 v241, s61, v239
	s_setprio 1
	v_mfma_f32_16x16x32_bf16 v[2:5], v[210:213], v[178:181], v[2:5]
	v_mfma_f32_16x16x32_bf16 v[6:9], v[214:217], v[178:181], v[6:9]
	v_mfma_f32_16x16x32_bf16 v[10:13], v[218:221], v[178:181], v[10:13]
	v_mfma_f32_16x16x32_bf16 v[14:17], v[222:225], v[178:181], v[14:17]
	s_waitcnt vmcnt(6)
	s_barrier
	v_mfma_f32_16x16x32_bf16 v[18:21], v[210:213], v[182:185], v[18:21]
	s_add_i32 m0, s60, s62
	v_mfma_f32_16x16x32_bf16 v[22:25], v[214:217], v[182:185], v[22:25]
	global_load_lds_dwordx4 v226, s[54:55]
	v_mfma_f32_16x16x32_bf16 v[26:29], v[218:221], v[182:185], v[26:29]
	v_mfma_f32_16x16x32_bf16 v[30:33], v[222:225], v[182:185], v[30:33]
	v_mfma_f32_16x16x32_bf16 v[34:37], v[210:213], v[186:189], v[34:37]
	ds_read_b128 v[162:165], v241 offset:0
	v_mfma_f32_16x16x32_bf16 v[38:41], v[214:217], v[186:189], v[38:41]
	ds_read_b128 v[166:169], v241 offset:256
	v_mfma_f32_16x16x32_bf16 v[42:45], v[218:221], v[186:189], v[42:45]
	ds_read_b128 v[170:173], v241 offset:2048
	global_load_lds_dwordx4 v226, s[54:55] offset:1024
	v_mfma_f32_16x16x32_bf16 v[46:49], v[222:225], v[186:189], v[46:49]
	ds_read_b128 v[174:177], v241 offset:2304
	v_mfma_f32_16x16x32_bf16 v[50:53], v[210:213], v[190:193], v[50:53]
	ds_read_b128 v[130:133], v240 offset:0
	v_mfma_f32_16x16x32_bf16 v[54:57], v[214:217], v[190:193], v[54:57]
	ds_read_b128 v[134:137], v240 offset:1024
	v_mfma_f32_16x16x32_bf16 v[58:61], v[218:221], v[190:193], v[58:61]
	ds_read_b128 v[138:141], v240 offset:2048
	v_mfma_f32_16x16x32_bf16 v[62:65], v[222:225], v[190:193], v[62:65]
	ds_read_b128 v[142:145], v240 offset:3072
	global_load_lds_dwordx4 v226, s[54:55] offset:2048
	v_mfma_f32_16x16x32_bf16 v[66:69], v[210:213], v[194:197], v[66:69]
	ds_read_b128 v[146:149], v240 offset:4096
	v_mfma_f32_16x16x32_bf16 v[70:73], v[214:217], v[194:197], v[70:73]
	ds_read_b128 v[150:153], v240 offset:5120
	v_mfma_f32_16x16x32_bf16 v[74:77], v[218:221], v[194:197], v[74:77]
	ds_read_b128 v[154:157], v240 offset:6144
	v_mfma_f32_16x16x32_bf16 v[78:81], v[222:225], v[194:197], v[78:81]
	ds_read_b128 v[158:161], v240 offset:7168
	v_mfma_f32_16x16x32_bf16 v[82:85], v[210:213], v[198:201], v[82:85]
	global_load_lds_dwordx4 v226, s[54:55] offset:3072
	v_mfma_f32_16x16x32_bf16 v[86:89], v[214:217], v[198:201], v[86:89]
	v_mfma_f32_16x16x32_bf16 v[90:93], v[218:221], v[198:201], v[90:93]
	v_mfma_f32_16x16x32_bf16 v[94:97], v[222:225], v[198:201], v[94:97]
	v_mfma_f32_16x16x32_bf16 v[98:101], v[210:213], v[202:205], v[98:101]
	s_add_i32 m0, s60, s63
	v_mfma_f32_16x16x32_bf16 v[102:105], v[214:217], v[202:205], v[102:105]
	global_load_lds_dwordx4 v230, s[56:57]
	v_mfma_f32_16x16x32_bf16 v[106:109], v[218:221], v[202:205], v[106:109]
	v_mfma_f32_16x16x32_bf16 v[110:113], v[222:225], v[202:205], v[110:113]
	v_mfma_f32_16x16x32_bf16 v[114:117], v[210:213], v[206:209], v[114:117]
	v_mfma_f32_16x16x32_bf16 v[118:121], v[214:217], v[206:209], v[118:121]
	v_mfma_f32_16x16x32_bf16 v[122:125], v[218:221], v[206:209], v[122:125]
	global_load_lds_dwordx4 v231, s[56:57] offset:1024
	v_mfma_f32_16x16x32_bf16 v[126:129], v[222:225], v[206:209], v[126:129]
	s_setprio 0
	s_add_i32 s60, s60, 0x6000
	s_cmp_eq_u32 s60, 0x12000
	s_cselect_b32 s60, 0, s60
	s_add_u32 s54, s54, s72
	s_addc_u32 s55, s55, 0
	s_add_u32 s56, s56, s73
	s_addc_u32 s57, s57, 0
	s_add_i32 s61, s61, 0x6000
	s_cmp_eq_u32 s61, 0x12000
	s_cselect_b32 s61, 0, s61
	s_branch .Lpj_main

.Lpj_nn_b:
	s_waitcnt lgkmcnt(0)
	v_add_u32_e32 v240, s61, v238
	v_add_u32_e32 v241, s61, v239
	s_setprio 1
	v_mfma_f32_16x16x32_bf16 v[2:5], v[162:165], v[130:133], 0
	v_mfma_f32_16x16x32_bf16 v[6:9], v[166:169], v[130:133], 0
	v_mfma_f32_16x16x32_bf16 v[10:13], v[170:173], v[130:133], 0
	v_mfma_f32_16x16x32_bf16 v[14:17], v[174:177], v[130:133], 0
	s_waitcnt vmcnt(63)
	s_barrier
	v_mfma_f32_16x16x32_bf16 v[18:21], v[162:165], v[134:137], 0
	s_add_i32 m0, s60, s62
	v_mfma_f32_16x16x32_bf16 v[22:25], v[166:169], v[134:137], 0
	global_load_lds_dwordx4 v226, s[54:55]
	v_mfma_f32_16x16x32_bf16 v[26:29], v[170:173], v[134:137], 0
	v_mfma_f32_16x16x32_bf16 v[30:33], v[174:177], v[134:137], 0
	v_mfma_f32_16x16x32_bf16 v[34:37], v[162:165], v[138:141], 0
	ds_read_b128 v[210:213], v241 offset:0
	v_mfma_f32_16x16x32_bf16 v[38:41], v[166:169], v[138:141], 0
	ds_read_b128 v[214:217], v241 offset:256
	v_mfma_f32_16x16x32_bf16 v[42:45], v[170:173], v[138:141], 0
	ds_read_b128 v[218:221], v241 offset:2048
	global_load_lds_dwordx4 v226, s[54:55] offset:1024
	v_mfma_f32_16x16x32_bf16 v[46:49], v[174:177], v[138:141], 0
	ds_read_b128 v[222:225], v241 offset:2304
	v_mfma_f32_16x16x32_bf16 v[50:53], v[162:165], v[142:145], 0
	ds_read_b128 v[178:181], v240 offset:0
	v_mfma_f32_16x16x32_bf16 v[54:57], v[166:169], v[142:145], 0
	ds_read_b128 v[182:185], v240 offset:1024
	v_mfma_f32_16x16x32_bf16 v[58:61], v[170:173], v[142:145], 0
	ds_read_b128 v[186:189], v240 offset:2048
	v_mfma_f32_16x16x32_bf16 v[62:65], v[174:177], v[142:145], 0
	ds_read_b128 v[190:193], v240 offset:3072
	global_load_lds_dwordx4 v226, s[54:55] offset:2048
	v_mfma_f32_16x16x32_bf16 v[66:69], v[162:165], v[146:149], 0
	ds_read_b128 v[194:197], v240 offset:4096
	v_mfma_f32_16x16x32_bf16 v[70:73], v[166:169], v[146:149], 0
	ds_read_b128 v[198:201], v240 offset:5120
	v_mfma_f32_16x16x32_bf16 v[74:77], v[170:173], v[146:149], 0
	ds_read_b128 v[202:205], v240 offset:6144
	v_mfma_f32_16x16x32_bf16 v[78:81], v[174:177], v[146:149], 0
	ds_read_b128 v[206:209], v240 offset:7168
	v_mfma_f32_16x16x32_bf16 v[82:85], v[162:165], v[150:153], 0
	global_load_lds_dwordx4 v226, s[54:55] offset:3072
	v_mfma_f32_16x16x32_bf16 v[86:89], v[166:169], v[150:153], 0
	v_mfma_f32_16x16x32_bf16 v[90:93], v[170:173], v[150:153], 0
	v_mfma_f32_16x16x32_bf16 v[94:97], v[174:177], v[150:153], 0
	v_mfma_f32_16x16x32_bf16 v[98:101], v[162:165], v[154:157], 0
	s_add_i32 m0, s60, s63
	v_mfma_f32_16x16x32_bf16 v[102:105], v[166:169], v[154:157], 0
	global_load_lds_dwordx4 v230, s[56:57]
	v_mfma_f32_16x16x32_bf16 v[106:109], v[170:173], v[154:157], 0
	v_mfma_f32_16x16x32_bf16 v[110:113], v[174:177], v[154:157], 0
	v_mfma_f32_16x16x32_bf16 v[114:117], v[162:165], v[158:161], 0
	v_mfma_f32_16x16x32_bf16 v[118:121], v[166:169], v[158:161], 0
	v_mfma_f32_16x16x32_bf16 v[122:125], v[170:173], v[158:161], 0
	global_load_lds_dwordx4 v231, s[56:57] offset:1024
	v_mfma_f32_16x16x32_bf16 v[126:129], v[174:177], v[158:161], 0
	s_setprio 0
	s_add_i32 s60, s60, 0x6000
	s_cmp_eq_u32 s60, 0x12000
	s_cselect_b32 s60, 0, s60
	s_add_u32 s54, s54, s72
	s_addc_u32 s55, s55, 0
	s_add_u32 s56, s56, s73
	s_addc_u32 s57, s57, 0
	s_add_i32 s61, s61, 0x6000
	s_cmp_eq_u32 s61, 0x12000
	s_cselect_b32 s61, 0, s61
	s_waitcnt lgkmcnt(0)
	v_add_u32_e32 v240, s61, v238
	v_add_u32_e32 v241, s61, v239
	s_setprio 1
	v_mfma_f32_16x16x32_bf16 v[2:5], v[210:213], v[178:181], v[2:5]
	v_mfma_f32_16x16x32_bf16 v[6:9], v[214:217], v[178:181], v[6:9]
	v_mfma_f32_16x16x32_bf16 v[10:13], v[218:221], v[178:181], v[10:13]
	v_mfma_f32_16x16x32_bf16 v[14:17], v[222:225], v[178:181], v[14:17]
	s_waitcnt vmcnt(63)
	s_barrier
	v_mfma_f32_16x16x32_bf16 v[18:21], v[210:213], v[182:185], v[18:21]
	s_add_i32 m0, s60, s62
	v_mfma_f32_16x16x32_bf16 v[22:25], v[214:217], v[182:185], v[22:25]
	global_load_lds_dwordx4 v226, s[54:55]
	v_mfma_f32_16x16x32_bf16 v[26:29], v[218:221], v[182:185], v[26:29]
	v_mfma_f32_16x16x32_bf16 v[30:33], v[222:225], v[182:185], v[30:33]
	v_mfma_f32_16x16x32_bf16 v[34:37], v[210:213], v[186:189], v[34:37]
	ds_read_b128 v[162:165], v241 offset:0
	v_mfma_f32_16x16x32_bf16 v[38:41], v[214:217], v[186:189], v[38:41]
	ds_read_b128 v[166:169], v241 offset:256
	v_mfma_f32_16x16x32_bf16 v[42:45], v[218:221], v[186:189], v[42:45]
	ds_read_b128 v[170:173], v241 offset:2048
	global_load_lds_dwordx4 v226, s[54:55] offset:1024
	v_mfma_f32_16x16x32_bf16 v[46:49], v[222:225], v[186:189], v[46:49]
	ds_read_b128 v[174:177], v241 offset:2304
	v_mfma_f32_16x16x32_bf16 v[50:53], v[210:213], v[190:193], v[50:53]
	ds_read_b128 v[130:133], v240 offset:0
	v_mfma_f32_16x16x32_bf16 v[54:57], v[214:217], v[190:193], v[54:57]
	ds_read_b128 v[134:137], v240 offset:1024
	v_mfma_f32_16x16x32_bf16 v[58:61], v[218:221], v[190:193], v[58:61]
	ds_read_b128 v[138:141], v240 offset:2048
	v_mfma_f32_16x16x32_bf16 v[62:65], v[222:225], v[190:193], v[62:65]
	ds_read_b128 v[142:145], v240 offset:3072
	global_load_lds_dwordx4 v226, s[54:55] offset:2048
	v_mfma_f32_16x16x32_bf16 v[66:69], v[210:213], v[194:197], v[66:69]
	ds_read_b128 v[146:149], v240 offset:4096
	v_mfma_f32_16x16x32_bf16 v[70:73], v[214:217], v[194:197], v[70:73]
	ds_read_b128 v[150:153], v240 offset:5120
	v_mfma_f32_16x16x32_bf16 v[74:77], v[218:221], v[194:197], v[74:77]
	ds_read_b128 v[154:157], v240 offset:6144
	v_mfma_f32_16x16x32_bf16 v[78:81], v[222:225], v[194:197], v[78:81]
	ds_read_b128 v[158:161], v240 offset:7168
	v_mfma_f32_16x16x32_bf16 v[82:85], v[210:213], v[198:201], v[82:85]
	global_load_lds_dwordx4 v226, s[54:55] offset:3072
	v_mfma_f32_16x16x32_bf16 v[86:89], v[214:217], v[198:201], v[86:89]
	v_mfma_f32_16x16x32_bf16 v[90:93], v[218:221], v[198:201], v[90:93]
	v_mfma_f32_16x16x32_bf16 v[94:97], v[222:225], v[198:201], v[94:97]
	v_mfma_f32_16x16x32_bf16 v[98:101], v[210:213], v[202:205], v[98:101]
	s_add_i32 m0, s60, s63
	v_mfma_f32_16x16x32_bf16 v[102:105], v[214:217], v[202:205], v[102:105]
	global_load_lds_dwordx4 v230, s[56:57]
	v_mfma_f32_16x16x32_bf16 v[106:109], v[218:221], v[202:205], v[106:109]
	v_mfma_f32_16x16x32_bf16 v[110:113], v[222:225], v[202:205], v[110:113]
	v_mfma_f32_16x16x32_bf16 v[114:117], v[210:213], v[206:209], v[114:117]
	v_mfma_f32_16x16x32_bf16 v[118:121], v[214:217], v[206:209], v[118:121]
	v_mfma_f32_16x16x32_bf16 v[122:125], v[218:221], v[206:209], v[122:125]
	global_load_lds_dwordx4 v231, s[56:57] offset:1024
	v_mfma_f32_16x16x32_bf16 v[126:129], v[222:225], v[206:209], v[126:129]
	s_setprio 0
	s_add_i32 s60, s60, 0x6000
	s_cmp_eq_u32 s60, 0x12000
	s_cselect_b32 s60, 0, s60
	s_add_u32 s54, s54, s72
	s_addc_u32 s55, s55, 0
	s_add_u32 s56, s56, s73
	s_addc_u32 s57, s57, 0
	s_add_i32 s61, s61, 0x6000
	s_cmp_eq_u32 s61, 0x12000
	s_cselect_b32 s61, 0, s61

.Lpj_kdone:
	s_cmp_eq_u32 s37, 0
	s_cbranch_scc1 .Lpj_tail_last
	s_waitcnt lgkmcnt(0)
	v_add_u32_e32 v240, s61, v238
	v_add_u32_e32 v241, s61, v239
	s_setprio 1
	v_mfma_f32_16x16x32_bf16 v[2:5], v[162:165], v[130:133], v[2:5]
	v_mfma_f32_16x16x32_bf16 v[6:9], v[166:169], v[130:133], v[6:9]
	v_mfma_f32_16x16x32_bf16 v[10:13], v[170:173], v[130:133], v[10:13]
	v_mfma_f32_16x16x32_bf16 v[14:17], v[174:177], v[130:133], v[14:17]
	s_waitcnt vmcnt(6)
	s_barrier
	v_mfma_f32_16x16x32_bf16 v[18:21], v[162:165], v[134:137], v[18:21]
	s_add_i32 m0, s60, s62
	v_mfma_f32_16x16x32_bf16 v[22:25], v[166:169], v[134:137], v[22:25]
	global_load_lds_dwordx4 v226, s[54:55]
	v_mfma_f32_16x16x32_bf16 v[26:29], v[170:173], v[134:137], v[26:29]
	v_mfma_f32_16x16x32_bf16 v[30:33], v[174:177], v[134:137], v[30:33]
	v_mfma_f32_16x16x32_bf16 v[34:37], v[162:165], v[138:141], v[34:37]
	ds_read_b128 v[210:213], v241 offset:0
	v_mfma_f32_16x16x32_bf16 v[38:41], v[166:169], v[138:141], v[38:41]
	ds_read_b128 v[214:217], v241 offset:256
	v_mfma_f32_16x16x32_bf16 v[42:45], v[170:173], v[138:141], v[42:45]
	ds_read_b128 v[218:221], v241 offset:2048
	global_load_lds_dwordx4 v226, s[54:55] offset:1024
	v_mfma_f32_16x16x32_bf16 v[46:49], v[174:177], v[138:141], v[46:49]
	ds_read_b128 v[222:225], v241 offset:2304
	v_mfma_f32_16x16x32_bf16 v[50:53], v[162:165], v[142:145], v[50:53]
	ds_read_b128 v[178:181], v240 offset:0
	v_mfma_f32_16x16x32_bf16 v[54:57], v[166:169], v[142:145], v[54:57]
	ds_read_b128 v[182:185], v240 offset:1024
	v_mfma_f32_16x16x32_bf16 v[58:61], v[170:173], v[142:145], v[58:61]
	ds_read_b128 v[186:189], v240 offset:2048
	v_mfma_f32_16x16x32_bf16 v[62:65], v[174:177], v[142:145], v[62:65]
	ds_read_b128 v[190:193], v240 offset:3072
	global_load_lds_dwordx4 v226, s[54:55] offset:2048
	v_mfma_f32_16x16x32_bf16 v[66:69], v[162:165], v[146:149], v[66:69]
	ds_read_b128 v[194:197], v240 offset:4096
	v_mfma_f32_16x16x32_bf16 v[70:73], v[166:169], v[146:149], v[70:73]
	ds_read_b128 v[198:201], v240 offset:5120
	v_mfma_f32_16x16x32_bf16 v[74:77], v[170:173], v[146:149], v[74:77]
	ds_read_b128 v[202:205], v240 offset:6144
	v_mfma_f32_16x16x32_bf16 v[78:81], v[174:177], v[146:149], v[78:81]
	ds_read_b128 v[206:209], v240 offset:7168
	v_mfma_f32_16x16x32_bf16 v[82:85], v[162:165], v[150:153], v[82:85]
	global_load_lds_dwordx4 v226, s[54:55] offset:3072
	v_mfma_f32_16x16x32_bf16 v[86:89], v[166:169], v[150:153], v[86:89]
	v_mfma_f32_16x16x32_bf16 v[90:93], v[170:173], v[150:153], v[90:93]
	v_mfma_f32_16x16x32_bf16 v[94:97], v[174:177], v[150:153], v[94:97]
	v_mfma_f32_16x16x32_bf16 v[98:101], v[162:165], v[154:157], v[98:101]
	s_add_i32 m0, s60, s63
	v_mfma_f32_16x16x32_bf16 v[102:105], v[166:169], v[154:157], v[102:105]
	global_load_lds_dwordx4 v230, s[56:57]
	v_mfma_f32_16x16x32_bf16 v[106:109], v[170:173], v[154:157], v[106:109]
	v_mfma_f32_16x16x32_bf16 v[110:113], v[174:177], v[154:157], v[110:113]
	v_mfma_f32_16x16x32_bf16 v[114:117], v[162:165], v[158:161], v[114:117]
	v_mfma_f32_16x16x32_bf16 v[118:121], v[166:169], v[158:161], v[118:121]
	v_mfma_f32_16x16x32_bf16 v[122:125], v[170:173], v[158:161], v[122:125]
	global_load_lds_dwordx4 v231, s[56:57] offset:1024
	v_mfma_f32_16x16x32_bf16 v[126:129], v[174:177], v[158:161], v[126:129]
	s_setprio 0
	s_add_i32 s60, s60, 0x6000
	s_cmp_eq_u32 s60, 0x12000
	s_cselect_b32 s60, 0, s60
	s_add_u32 s54, s54, s72
	s_addc_u32 s55, s55, 0
	s_add_u32 s56, s56, s73
	s_addc_u32 s57, s57, 0
	s_add_i32 s61, s61, 0x6000
	s_cmp_eq_u32 s61, 0x12000
	s_cselect_b32 s61, 0, s61
	v_mov_b32_e32 v226, v232
	v_mov_b32_e32 v230, v236
	v_mov_b32_e32 v231, v237
	s_mov_b64 s[54:55], s[48:49]
	s_mov_b64 s[56:57], s[50:51]
	s_waitcnt lgkmcnt(0)
	v_add_u32_e32 v240, s61, v238
	v_add_u32_e32 v241, s61, v239
	s_setprio 1
	v_mfma_f32_16x16x32_bf16 v[2:5], v[210:213], v[178:181], v[2:5]
	v_mfma_f32_16x16x32_bf16 v[6:9], v[214:217], v[178:181], v[6:9]
	v_mfma_f32_16x16x32_bf16 v[10:13], v[218:221], v[178:181], v[10:13]
	v_mfma_f32_16x16x32_bf16 v[14:17], v[222:225], v[178:181], v[14:17]
	s_waitcnt vmcnt(6)
	s_barrier
	v_mfma_f32_16x16x32_bf16 v[18:21], v[210:213], v[182:185], v[18:21]
	s_add_i32 m0, s60, s62
	v_mfma_f32_16x16x32_bf16 v[22:25], v[214:217], v[182:185], v[22:25]
	global_load_lds_dwordx4 v226, s[54:55]
	v_mfma_f32_16x16x32_bf16 v[26:29], v[218:221], v[182:185], v[26:29]
	v_mfma_f32_16x16x32_bf16 v[30:33], v[222:225], v[182:185], v[30:33]
	v_mfma_f32_16x16x32_bf16 v[34:37], v[210:213], v[186:189], v[34:37]
	ds_read_b128 v[162:165], v241 offset:0
	v_mfma_f32_16x16x32_bf16 v[38:41], v[214:217], v[186:189], v[38:41]
	ds_read_b128 v[166:169], v241 offset:256
	v_mfma_f32_16x16x32_bf16 v[42:45], v[218:221], v[186:189], v[42:45]
	ds_read_b128 v[170:173], v241 offset:2048
	global_load_lds_dwordx4 v226, s[54:55] offset:1024
	v_mfma_f32_16x16x32_bf16 v[46:49], v[222:225], v[186:189], v[46:49]
	ds_read_b128 v[174:177], v241 offset:2304
	v_mfma_f32_16x16x32_bf16 v[50:53], v[210:213], v[190:193], v[50:53]
	ds_read_b128 v[130:133], v240 offset:0
	v_mfma_f32_16x16x32_bf16 v[54:57], v[214:217], v[190:193], v[54:57]
	ds_read_b128 v[134:137], v240 offset:1024
	v_mfma_f32_16x16x32_bf16 v[58:61], v[218:221], v[190:193], v[58:61]
	ds_read_b128 v[138:141], v240 offset:2048
	v_mfma_f32_16x16x32_bf16 v[62:65], v[222:225], v[190:193], v[62:65]
	ds_read_b128 v[142:145], v240 offset:3072
	global_load_lds_dwordx4 v226, s[54:55] offset:2048
	v_mfma_f32_16x16x32_bf16 v[66:69], v[210:213], v[194:197], v[66:69]
	ds_read_b128 v[146:149], v240 offset:4096
	v_mfma_f32_16x16x32_bf16 v[70:73], v[214:217], v[194:197], v[70:73]
	ds_read_b128 v[150:153], v240 offset:5120
	v_mfma_f32_16x16x32_bf16 v[74:77], v[218:221], v[194:197], v[74:77]
	ds_read_b128 v[154:157], v240 offset:6144
	v_mfma_f32_16x16x32_bf16 v[78:81], v[222:225], v[194:197], v[78:81]
	ds_read_b128 v[158:161], v240 offset:7168
	v_mfma_f32_16x16x32_bf16 v[82:85], v[210:213], v[198:201], v[82:85]
	global_load_lds_dwordx4 v226, s[54:55] offset:3072
	v_mfma_f32_16x16x32_bf16 v[86:89], v[214:217], v[198:201], v[86:89]
	v_mfma_f32_16x16x32_bf16 v[90:93], v[218:221], v[198:201], v[90:93]
	v_mfma_f32_16x16x32_bf16 v[94:97], v[222:225], v[198:201], v[94:97]
	v_mfma_f32_16x16x32_bf16 v[98:101], v[210:213], v[202:205], v[98:101]
	s_add_i32 m0, s60, s63
	v_mfma_f32_16x16x32_bf16 v[102:105], v[214:217], v[202:205], v[102:105]
	global_load_lds_dwordx4 v230, s[56:57]
	v_mfma_f32_16x16x32_bf16 v[106:109], v[218:221], v[202:205], v[106:109]
	v_mfma_f32_16x16x32_bf16 v[110:113], v[222:225], v[202:205], v[110:113]
	v_mfma_f32_16x16x32_bf16 v[114:117], v[210:213], v[206:209], v[114:117]
	v_mfma_f32_16x16x32_bf16 v[118:121], v[214:217], v[206:209], v[118:121]
	v_mfma_f32_16x16x32_bf16 v[122:125], v[218:221], v[206:209], v[122:125]
	global_load_lds_dwordx4 v231, s[56:57] offset:1024
	v_mfma_f32_16x16x32_bf16 v[126:129], v[222:225], v[206:209], v[126:129]
	s_setprio 0
	s_add_i32 s60, s60, 0x6000
	s_cmp_eq_u32 s60, 0x12000
	s_cselect_b32 s60, 0, s60
	s_add_u32 s54, s54, s72
	s_addc_u32 s55, s55, 0
	s_add_u32 s56, s56, s73
	s_addc_u32 s57, s57, 0
	s_add_i32 s61, s61, 0x6000
	s_cmp_eq_u32 s61, 0x12000
	s_cselect_b32 s61, 0, s61
	s_waitcnt lgkmcnt(0)
	v_add_u32_e32 v240, s61, v238
	v_add_u32_e32 v241, s61, v239
	s_setprio 1
	v_mfma_f32_16x16x32_bf16 v[2:5], v[162:165], v[130:133], v[2:5]
	v_mfma_f32_16x16x32_bf16 v[6:9], v[166:169], v[130:133], v[6:9]
	v_mfma_f32_16x16x32_bf16 v[10:13], v[170:173], v[130:133], v[10:13]
	v_mfma_f32_16x16x32_bf16 v[14:17], v[174:177], v[130:133], v[14:17]
	s_waitcnt vmcnt(6)
	s_barrier
	v_mfma_f32_16x16x32_bf16 v[18:21], v[162:165], v[134:137], v[18:21]
	s_add_i32 m0, s60, s62
	v_mfma_f32_16x16x32_bf16 v[22:25], v[166:169], v[134:137], v[22:25]
	global_load_lds_dwordx4 v226, s[54:55]
	v_mfma_f32_16x16x32_bf16 v[26:29], v[170:173], v[134:137], v[26:29]
	v_mfma_f32_16x16x32_bf16 v[30:33], v[174:177], v[134:137], v[30:33]
	v_mfma_f32_16x16x32_bf16 v[34:37], v[162:165], v[138:141], v[34:37]
	ds_read_b128 v[210:213], v241 offset:0
	v_mfma_f32_16x16x32_bf16 v[38:41], v[166:169], v[138:141], v[38:41]
	ds_read_b128 v[214:217], v241 offset:256
	v_mfma_f32_16x16x32_bf16 v[42:45], v[170:173], v[138:141], v[42:45]
	ds_read_b128 v[218:221], v241 offset:2048
	global_load_lds_dwordx4 v226, s[54:55] offset:1024
	v_mfma_f32_16x16x32_bf16 v[46:49], v[174:177], v[138:141], v[46:49]
	ds_read_b128 v[222:225], v241 offset:2304
	v_mfma_f32_16x16x32_bf16 v[50:53], v[162:165], v[142:145], v[50:53]
	ds_read_b128 v[178:181], v240 offset:0
	v_mfma_f32_16x16x32_bf16 v[54:57], v[166:169], v[142:145], v[54:57]
	ds_read_b128 v[182:185], v240 offset:1024
	v_mfma_f32_16x16x32_bf16 v[58:61], v[170:173], v[142:145], v[58:61]
	ds_read_b128 v[186:189], v240 offset:2048
	v_mfma_f32_16x16x32_bf16 v[62:65], v[174:177], v[142:145], v[62:65]
	ds_read_b128 v[190:193], v240 offset:3072
	global_load_lds_dwordx4 v226, s[54:55] offset:2048
	v_mfma_f32_16x16x32_bf16 v[66:69], v[162:165], v[146:149], v[66:69]
	ds_read_b128 v[194:197], v240 offset:4096
	v_mfma_f32_16x16x32_bf16 v[70:73], v[166:169], v[146:149], v[70:73]
	ds_read_b128 v[198:201], v240 offset:5120
	v_mfma_f32_16x16x32_bf16 v[74:77], v[170:173], v[146:149], v[74:77]
	ds_read_b128 v[202:205], v240 offset:6144
	v_mfma_f32_16x16x32_bf16 v[78:81], v[174:177], v[146:149], v[78:81]
	ds_read_b128 v[206:209], v240 offset:7168
	v_mfma_f32_16x16x32_bf16 v[82:85], v[162:165], v[150:153], v[82:85]
	global_load_lds_dwordx4 v226, s[54:55] offset:3072
	v_mfma_f32_16x16x32_bf16 v[86:89], v[166:169], v[150:153], v[86:89]
	v_mfma_f32_16x16x32_bf16 v[90:93], v[170:173], v[150:153], v[90:93]
	v_mfma_f32_16x16x32_bf16 v[94:97], v[174:177], v[150:153], v[94:97]
	v_mfma_f32_16x16x32_bf16 v[98:101], v[162:165], v[154:157], v[98:101]
	s_add_i32 m0, s60, s63
	v_mfma_f32_16x16x32_bf16 v[102:105], v[166:169], v[154:157], v[102:105]
	global_load_lds_dwordx4 v230, s[56:57]
	v_mfma_f32_16x16x32_bf16 v[106:109], v[170:173], v[154:157], v[106:109]
	v_mfma_f32_16x16x32_bf16 v[110:113], v[174:177], v[154:157], v[110:113]
	v_mfma_f32_16x16x32_bf16 v[114:117], v[162:165], v[158:161], v[114:117]
	v_mfma_f32_16x16x32_bf16 v[118:121], v[166:169], v[158:161], v[118:121]
	v_mfma_f32_16x16x32_bf16 v[122:125], v[170:173], v[158:161], v[122:125]
	global_load_lds_dwordx4 v231, s[56:57] offset:1024
	v_mfma_f32_16x16x32_bf16 v[126:129], v[174:177], v[158:161], v[126:129]
	s_setprio 0
	s_add_i32 s60, s60, 0x6000
	s_cmp_eq_u32 s60, 0x12000
	s_cselect_b32 s60, 0, s60
	s_add_u32 s54, s54, s72
	s_addc_u32 s55, s55, 0
	s_add_u32 s56, s56, s73
	s_addc_u32 s57, s57, 0
	s_add_i32 s61, s61, 0x6000
	s_cmp_eq_u32 s61, 0x12000
	s_cselect_b32 s61, 0, s61
	s_waitcnt lgkmcnt(0)
	v_add_u32_e32 v240, s61, v238
	v_add_u32_e32 v241, s61, v239
	s_setprio 1
	v_mfma_f32_16x16x32_bf16 v[2:5], v[210:213], v[178:181], v[2:5]
	v_mfma_f32_16x16x32_bf16 v[6:9], v[214:217], v[178:181], v[6:9]
	v_mfma_f32_16x16x32_bf16 v[10:13], v[218:221], v[178:181], v[10:13]
	v_mfma_f32_16x16x32_bf16 v[14:17], v[222:225], v[178:181], v[14:17]
	s_waitcnt vmcnt(6)
	s_barrier
	v_mfma_f32_16x16x32_bf16 v[18:21], v[210:213], v[182:185], v[18:21]
	s_add_i32 m0, s60, s62
	v_mfma_f32_16x16x32_bf16 v[22:25], v[214:217], v[182:185], v[22:25]
	global_load_lds_dwordx4 v226, s[54:55]
	v_mfma_f32_16x16x32_bf16 v[26:29], v[218:221], v[182:185], v[26:29]
	v_mfma_f32_16x16x32_bf16 v[30:33], v[222:225], v[182:185], v[30:33]
	v_mfma_f32_16x16x32_bf16 v[34:37], v[210:213], v[186:189], v[34:37]
	ds_read_b128 v[162:165], v241 offset:0
	v_mfma_f32_16x16x32_bf16 v[38:41], v[214:217], v[186:189], v[38:41]
	ds_read_b128 v[166:169], v241 offset:256
	v_mfma_f32_16x16x32_bf16 v[42:45], v[218:221], v[186:189], v[42:45]
	ds_read_b128 v[170:173], v241 offset:2048
	global_load_lds_dwordx4 v226, s[54:55] offset:1024
	v_mfma_f32_16x16x32_bf16 v[46:49], v[222:225], v[186:189], v[46:49]
	ds_read_b128 v[174:177], v241 offset:2304
	v_mfma_f32_16x16x32_bf16 v[50:53], v[210:213], v[190:193], v[50:53]
	ds_read_b128 v[130:133], v240 offset:0
	v_mfma_f32_16x16x32_bf16 v[54:57], v[214:217], v[190:193], v[54:57]
	ds_read_b128 v[134:137], v240 offset:1024
	v_mfma_f32_16x16x32_bf16 v[58:61], v[218:221], v[190:193], v[58:61]
	ds_read_b128 v[138:141], v240 offset:2048
	v_mfma_f32_16x16x32_bf16 v[62:65], v[222:225], v[190:193], v[62:65]
	ds_read_b128 v[142:145], v240 offset:3072
	global_load_lds_dwordx4 v226, s[54:55] offset:2048
	v_mfma_f32_16x16x32_bf16 v[66:69], v[210:213], v[194:197], v[66:69]
	ds_read_b128 v[146:149], v240 offset:4096
	v_mfma_f32_16x16x32_bf16 v[70:73], v[214:217], v[194:197], v[70:73]
	ds_read_b128 v[150:153], v240 offset:5120
	v_mfma_f32_16x16x32_bf16 v[74:77], v[218:221], v[194:197], v[74:77]
	ds_read_b128 v[154:157], v240 offset:6144
	v_mfma_f32_16x16x32_bf16 v[78:81], v[222:225], v[194:197], v[78:81]
	ds_read_b128 v[158:161], v240 offset:7168
	v_mfma_f32_16x16x32_bf16 v[82:85], v[210:213], v[198:201], v[82:85]
	global_load_lds_dwordx4 v226, s[54:55] offset:3072
	v_mfma_f32_16x16x32_bf16 v[86:89], v[214:217], v[198:201], v[86:89]
	v_mfma_f32_16x16x32_bf16 v[90:93], v[218:221], v[198:201], v[90:93]
	v_mfma_f32_16x16x32_bf16 v[94:97], v[222:225], v[198:201], v[94:97]
	v_mfma_f32_16x16x32_bf16 v[98:101], v[210:213], v[202:205], v[98:101]
	s_add_i32 m0, s60, s63
	v_mfma_f32_16x16x32_bf16 v[102:105], v[214:217], v[202:205], v[102:105]
	global_load_lds_dwordx4 v230, s[56:57]
	v_mfma_f32_16x16x32_bf16 v[106:109], v[218:221], v[202:205], v[106:109]
	v_mfma_f32_16x16x32_bf16 v[110:113], v[222:225], v[202:205], v[110:113]
	v_mfma_f32_16x16x32_bf16 v[114:117], v[210:213], v[206:209], v[114:117]
	v_mfma_f32_16x16x32_bf16 v[118:121], v[214:217], v[206:209], v[118:121]
	v_mfma_f32_16x16x32_bf16 v[122:125], v[218:221], v[206:209], v[122:125]
	global_load_lds_dwordx4 v231, s[56:57] offset:1024
	v_mfma_f32_16x16x32_bf16 v[126:129], v[222:225], v[206:209], v[126:129]
	s_setprio 0
	s_add_i32 s60, s60, 0x6000
	s_cmp_eq_u32 s60, 0x12000
	s_cselect_b32 s60, 0, s60
	s_add_u32 s54, s54, s72
	s_addc_u32 s55, s55, 0
	s_add_u32 s56, s56, s73
	s_addc_u32 s57, s57, 0
	s_add_i32 s61, s61, 0x6000
	s_cmp_eq_u32 s61, 0x12000
	s_cselect_b32 s61, 0, s61
	s_branch .Lpj_epi

.Lpj_tail_last:
	s_waitcnt lgkmcnt(0)
	v_add_u32_e32 v240, s61, v238
	v_add_u32_e32 v241, s61, v239
	s_setprio 1
	v_mfma_f32_16x16x32_bf16 v[2:5], v[162:165], v[130:133], v[2:5]
	v_mfma_f32_16x16x32_bf16 v[6:9], v[166:169], v[130:133], v[6:9]
	v_mfma_f32_16x16x32_bf16 v[10:13], v[170:173], v[130:133], v[10:13]
	v_mfma_f32_16x16x32_bf16 v[14:17], v[174:177], v[130:133], v[14:17]
	s_waitcnt vmcnt(6)
	s_barrier
	v_mfma_f32_16x16x32_bf16 v[18:21], v[162:165], v[134:137], v[18:21]
	s_add_i32 m0, s60, s62
	v_mfma_f32_16x16x32_bf16 v[22:25], v[166:169], v[134:137], v[22:25]
	global_load_lds_dwordx4 v226, s[54:55]
	v_mfma_f32_16x16x32_bf16 v[26:29], v[170:173], v[134:137], v[26:29]
	v_mfma_f32_16x16x32_bf16 v[30:33], v[174:177], v[134:137], v[30:33]
	v_mfma_f32_16x16x32_bf16 v[34:37], v[162:165], v[138:141], v[34:37]
	ds_read_b128 v[210:213], v241 offset:0
	v_mfma_f32_16x16x32_bf16 v[38:41], v[166:169], v[138:141], v[38:41]
	ds_read_b128 v[214:217], v241 offset:256
	v_mfma_f32_16x16x32_bf16 v[42:45], v[170:173], v[138:141], v[42:45]
	ds_read_b128 v[218:221], v241 offset:2048
	global_load_lds_dwordx4 v226, s[54:55] offset:1024
	v_mfma_f32_16x16x32_bf16 v[46:49], v[174:177], v[138:141], v[46:49]
	ds_read_b128 v[222:225], v241 offset:2304
	v_mfma_f32_16x16x32_bf16 v[50:53], v[162:165], v[142:145], v[50:53]
	ds_read_b128 v[178:181], v240 offset:0
	v_mfma_f32_16x16x32_bf16 v[54:57], v[166:169], v[142:145], v[54:57]
	ds_read_b128 v[182:185], v240 offset:1024
	v_mfma_f32_16x16x32_bf16 v[58:61], v[170:173], v[142:145], v[58:61]
	ds_read_b128 v[186:189], v240 offset:2048
	v_mfma_f32_16x16x32_bf16 v[62:65], v[174:177], v[142:145], v[62:65]
	ds_read_b128 v[190:193], v240 offset:3072
	global_load_lds_dwordx4 v226, s[54:55] offset:2048
	v_mfma_f32_16x16x32_bf16 v[66:69], v[162:165], v[146:149], v[66:69]
	ds_read_b128 v[194:197], v240 offset:4096
	v_mfma_f32_16x16x32_bf16 v[70:73], v[166:169], v[146:149], v[70:73]
	ds_read_b128 v[198:201], v240 offset:5120
	v_mfma_f32_16x16x32_bf16 v[74:77], v[170:173], v[146:149], v[74:77]
	ds_read_b128 v[202:205], v240 offset:6144
	v_mfma_f32_16x16x32_bf16 v[78:81], v[174:177], v[146:149], v[78:81]
	ds_read_b128 v[206:209], v240 offset:7168
	v_mfma_f32_16x16x32_bf16 v[82:85], v[162:165], v[150:153], v[82:85]
	global_load_lds_dwordx4 v226, s[54:55] offset:3072
	v_mfma_f32_16x16x32_bf16 v[86:89], v[166:169], v[150:153], v[86:89]
	v_mfma_f32_16x16x32_bf16 v[90:93], v[170:173], v[150:153], v[90:93]
	v_mfma_f32_16x16x32_bf16 v[94:97], v[174:177], v[150:153], v[94:97]
	v_mfma_f32_16x16x32_bf16 v[98:101], v[162:165], v[154:157], v[98:101]
	s_add_i32 m0, s60, s63
	v_mfma_f32_16x16x32_bf16 v[102:105], v[166:169], v[154:157], v[102:105]
	global_load_lds_dwordx4 v230, s[56:57]
	v_mfma_f32_16x16x32_bf16 v[106:109], v[170:173], v[154:157], v[106:109]
	v_mfma_f32_16x16x32_bf16 v[110:113], v[174:177], v[154:157], v[110:113]
	v_mfma_f32_16x16x32_bf16 v[114:117], v[162:165], v[158:161], v[114:117]
	v_mfma_f32_16x16x32_bf16 v[118:121], v[166:169], v[158:161], v[118:121]
	v_mfma_f32_16x16x32_bf16 v[122:125], v[170:173], v[158:161], v[122:125]
	global_load_lds_dwordx4 v231, s[56:57] offset:1024
	v_mfma_f32_16x16x32_bf16 v[126:129], v[174:177], v[158:161], v[126:129]
	s_setprio 0
	s_add_i32 s60, s60, 0x6000
	s_cmp_eq_u32 s60, 0x12000
	s_cselect_b32 s60, 0, s60
	s_add_u32 s54, s54, s72
	s_addc_u32 s55, s55, 0
	s_add_u32 s56, s56, s73
	s_addc_u32 s57, s57, 0
	s_add_i32 s61, s61, 0x6000
	s_cmp_eq_u32 s61, 0x12000
	s_cselect_b32 s61, 0, s61
	s_waitcnt lgkmcnt(0)
	v_add_u32_e32 v240, s61, v238
	v_add_u32_e32 v241, s61, v239
	s_setprio 1
	v_mfma_f32_16x16x32_bf16 v[2:5], v[210:213], v[178:181], v[2:5]
	v_mfma_f32_16x16x32_bf16 v[6:9], v[214:217], v[178:181], v[6:9]
	v_mfma_f32_16x16x32_bf16 v[10:13], v[218:221], v[178:181], v[10:13]
	v_mfma_f32_16x16x32_bf16 v[14:17], v[222:225], v[178:181], v[14:17]
	s_waitcnt vmcnt(6)
	s_barrier
	v_mfma_f32_16x16x32_bf16 v[18:21], v[210:213], v[182:185], v[18:21]
	v_mfma_f32_16x16x32_bf16 v[22:25], v[214:217], v[182:185], v[22:25]
	v_mfma_f32_16x16x32_bf16 v[26:29], v[218:221], v[182:185], v[26:29]
	v_mfma_f32_16x16x32_bf16 v[30:33], v[222:225], v[182:185], v[30:33]
	v_mfma_f32_16x16x32_bf16 v[34:37], v[210:213], v[186:189], v[34:37]
	ds_read_b128 v[162:165], v241 offset:0
	v_mfma_f32_16x16x32_bf16 v[38:41], v[214:217], v[186:189], v[38:41]
	ds_read_b128 v[166:169], v241 offset:256
	v_mfma_f32_16x16x32_bf16 v[42:45], v[218:221], v[186:189], v[42:45]
	ds_read_b128 v[170:173], v241 offset:2048
	v_mfma_f32_16x16x32_bf16 v[46:49], v[222:225], v[186:189], v[46:49]
	ds_read_b128 v[174:177], v241 offset:2304
	v_mfma_f32_16x16x32_bf16 v[50:53], v[210:213], v[190:193], v[50:53]
	ds_read_b128 v[130:133], v240 offset:0
	v_mfma_f32_16x16x32_bf16 v[54:57], v[214:217], v[190:193], v[54:57]
	ds_read_b128 v[134:137], v240 offset:1024
	v_mfma_f32_16x16x32_bf16 v[58:61], v[218:221], v[190:193], v[58:61]
	ds_read_b128 v[138:141], v240 offset:2048
	v_mfma_f32_16x16x32_bf16 v[62:65], v[222:225], v[190:193], v[62:65]
	ds_read_b128 v[142:145], v240 offset:3072
	v_mfma_f32_16x16x32_bf16 v[66:69], v[210:213], v[194:197], v[66:69]
	ds_read_b128 v[146:149], v240 offset:4096
	v_mfma_f32_16x16x32_bf16 v[70:73], v[214:217], v[194:197], v[70:73]
	ds_read_b128 v[150:153], v240 offset:5120
	v_mfma_f32_16x16x32_bf16 v[74:77], v[218:221], v[194:197], v[74:77]
	ds_read_b128 v[154:157], v240 offset:6144
	v_mfma_f32_16x16x32_bf16 v[78:81], v[222:225], v[194:197], v[78:81]
	ds_read_b128 v[158:161], v240 offset:7168
	v_mfma_f32_16x16x32_bf16 v[82:85], v[210:213], v[198:201], v[82:85]
	v_mfma_f32_16x16x32_bf16 v[86:89], v[214:217], v[198:201], v[86:89]
	v_mfma_f32_16x16x32_bf16 v[90:93], v[218:221], v[198:201], v[90:93]
	v_mfma_f32_16x16x32_bf16 v[94:97], v[222:225], v[198:201], v[94:97]
	v_mfma_f32_16x16x32_bf16 v[98:101], v[210:213], v[202:205], v[98:101]
	v_mfma_f32_16x16x32_bf16 v[102:105], v[214:217], v[202:205], v[102:105]
	v_mfma_f32_16x16x32_bf16 v[106:109], v[218:221], v[202:205], v[106:109]
	v_mfma_f32_16x16x32_bf16 v[110:113], v[222:225], v[202:205], v[110:113]
	v_mfma_f32_16x16x32_bf16 v[114:117], v[210:213], v[206:209], v[114:117]
	v_mfma_f32_16x16x32_bf16 v[118:121], v[214:217], v[206:209], v[118:121]
	v_mfma_f32_16x16x32_bf16 v[122:125], v[218:221], v[206:209], v[122:125]
	v_mfma_f32_16x16x32_bf16 v[126:129], v[222:225], v[206:209], v[126:129]
	s_setprio 0
	s_add_i32 s61, s61, 0x6000
	s_cmp_eq_u32 s61, 0x12000
	s_cselect_b32 s61, 0, s61
	s_waitcnt lgkmcnt(0)
	v_add_u32_e32 v240, s61, v238
	v_add_u32_e32 v241, s61, v239
	s_setprio 1
	v_mfma_f32_16x16x32_bf16 v[2:5], v[162:165], v[130:133], v[2:5]
	v_mfma_f32_16x16x32_bf16 v[6:9], v[166:169], v[130:133], v[6:9]
	v_mfma_f32_16x16x32_bf16 v[10:13], v[170:173], v[130:133], v[10:13]
	v_mfma_f32_16x16x32_bf16 v[14:17], v[174:177], v[130:133], v[14:17]
	s_waitcnt vmcnt(0)
	s_barrier
	v_mfma_f32_16x16x32_bf16 v[18:21], v[162:165], v[134:137], v[18:21]
	v_mfma_f32_16x16x32_bf16 v[22:25], v[166:169], v[134:137], v[22:25]
	v_mfma_f32_16x16x32_bf16 v[26:29], v[170:173], v[134:137], v[26:29]
	v_mfma_f32_16x16x32_bf16 v[30:33], v[174:177], v[134:137], v[30:33]
	v_mfma_f32_16x16x32_bf16 v[34:37], v[162:165], v[138:141], v[34:37]
	ds_read_b128 v[210:213], v241 offset:0
	v_mfma_f32_16x16x32_bf16 v[38:41], v[166:169], v[138:141], v[38:41]
	ds_read_b128 v[214:217], v241 offset:256
	v_mfma_f32_16x16x32_bf16 v[42:45], v[170:173], v[138:141], v[42:45]
	ds_read_b128 v[218:221], v241 offset:2048
	v_mfma_f32_16x16x32_bf16 v[46:49], v[174:177], v[138:141], v[46:49]
	ds_read_b128 v[222:225], v241 offset:2304
	v_mfma_f32_16x16x32_bf16 v[50:53], v[162:165], v[142:145], v[50:53]
	ds_read_b128 v[178:181], v240 offset:0
	v_mfma_f32_16x16x32_bf16 v[54:57], v[166:169], v[142:145], v[54:57]
	ds_read_b128 v[182:185], v240 offset:1024
	v_mfma_f32_16x16x32_bf16 v[58:61], v[170:173], v[142:145], v[58:61]
	ds_read_b128 v[186:189], v240 offset:2048
	v_mfma_f32_16x16x32_bf16 v[62:65], v[174:177], v[142:145], v[62:65]
	ds_read_b128 v[190:193], v240 offset:3072
	v_mfma_f32_16x16x32_bf16 v[66:69], v[162:165], v[146:149], v[66:69]
	ds_read_b128 v[194:197], v240 offset:4096
	v_mfma_f32_16x16x32_bf16 v[70:73], v[166:169], v[146:149], v[70:73]
	ds_read_b128 v[198:201], v240 offset:5120
	v_mfma_f32_16x16x32_bf16 v[74:77], v[170:173], v[146:149], v[74:77]
	ds_read_b128 v[202:205], v240 offset:6144
	v_mfma_f32_16x16x32_bf16 v[78:81], v[174:177], v[146:149], v[78:81]
	ds_read_b128 v[206:209], v240 offset:7168
	v_mfma_f32_16x16x32_bf16 v[82:85], v[162:165], v[150:153], v[82:85]
	v_mfma_f32_16x16x32_bf16 v[86:89], v[166:169], v[150:153], v[86:89]
	v_mfma_f32_16x16x32_bf16 v[90:93], v[170:173], v[150:153], v[90:93]
	v_mfma_f32_16x16x32_bf16 v[94:97], v[174:177], v[150:153], v[94:97]
	v_mfma_f32_16x16x32_bf16 v[98:101], v[162:165], v[154:157], v[98:101]
	v_mfma_f32_16x16x32_bf16 v[102:105], v[166:169], v[154:157], v[102:105]
	v_mfma_f32_16x16x32_bf16 v[106:109], v[170:173], v[154:157], v[106:109]
	v_mfma_f32_16x16x32_bf16 v[110:113], v[174:177], v[154:157], v[110:113]
	v_mfma_f32_16x16x32_bf16 v[114:117], v[162:165], v[158:161], v[114:117]
	v_mfma_f32_16x16x32_bf16 v[118:121], v[166:169], v[158:161], v[118:121]
	v_mfma_f32_16x16x32_bf16 v[122:125], v[170:173], v[158:161], v[122:125]
	v_mfma_f32_16x16x32_bf16 v[126:129], v[174:177], v[158:161], v[126:129]
	s_setprio 0
	s_add_i32 s61, s61, 0x6000
	s_cmp_eq_u32 s61, 0x12000
	s_cselect_b32 s61, 0, s61
	s_waitcnt lgkmcnt(0)
	s_setprio 1
	v_mfma_f32_16x16x32_bf16 v[2:5], v[210:213], v[178:181], v[2:5]
	v_mfma_f32_16x16x32_bf16 v[6:9], v[214:217], v[178:181], v[6:9]
	v_mfma_f32_16x16x32_bf16 v[10:13], v[218:221], v[178:181], v[10:13]
	v_mfma_f32_16x16x32_bf16 v[14:17], v[222:225], v[178:181], v[14:17]
	s_barrier
	v_mfma_f32_16x16x32_bf16 v[18:21], v[210:213], v[182:185], v[18:21]
	v_mfma_f32_16x16x32_bf16 v[22:25], v[214:217], v[182:185], v[22:25]
	v_mfma_f32_16x16x32_bf16 v[26:29], v[218:221], v[182:185], v[26:29]
	v_mfma_f32_16x16x32_bf16 v[30:33], v[222:225], v[182:185], v[30:33]
	v_mfma_f32_16x16x32_bf16 v[34:37], v[210:213], v[186:189], v[34:37]
	v_mfma_f32_16x16x32_bf16 v[38:41], v[214:217], v[186:189], v[38:41]
	v_mfma_f32_16x16x32_bf16 v[42:45], v[218:221], v[186:189], v[42:45]
	v_mfma_f32_16x16x32_bf16 v[46:49], v[222:225], v[186:189], v[46:49]
	v_mfma_f32_16x16x32_bf16 v[50:53], v[210:213], v[190:193], v[50:53]
	v_mfma_f32_16x16x32_bf16 v[54:57], v[214:217], v[190:193], v[54:57]
	v_mfma_f32_16x16x32_bf16 v[58:61], v[218:221], v[190:193], v[58:61]
	v_mfma_f32_16x16x32_bf16 v[62:65], v[222:225], v[190:193], v[62:65]
	v_mfma_f32_16x16x32_bf16 v[66:69], v[210:213], v[194:197], v[66:69]
	v_mfma_f32_16x16x32_bf16 v[70:73], v[214:217], v[194:197], v[70:73]
	v_mfma_f32_16x16x32_bf16 v[74:77], v[218:221], v[194:197], v[74:77]
	v_mfma_f32_16x16x32_bf16 v[78:81], v[222:225], v[194:197], v[78:81]
	v_mfma_f32_16x16x32_bf16 v[82:85], v[210:213], v[198:201], v[82:85]
	v_mfma_f32_16x16x32_bf16 v[86:89], v[214:217], v[198:201], v[86:89]
	v_mfma_f32_16x16x32_bf16 v[90:93], v[218:221], v[198:201], v[90:93]
	v_mfma_f32_16x16x32_bf16 v[94:97], v[222:225], v[198:201], v[94:97]
	v_mfma_f32_16x16x32_bf16 v[98:101], v[210:213], v[202:205], v[98:101]
	v_mfma_f32_16x16x32_bf16 v[102:105], v[214:217], v[202:205], v[102:105]
	v_mfma_f32_16x16x32_bf16 v[106:109], v[218:221], v[202:205], v[106:109]
	v_mfma_f32_16x16x32_bf16 v[110:113], v[222:225], v[202:205], v[110:113]
	v_mfma_f32_16x16x32_bf16 v[114:117], v[210:213], v[206:209], v[114:117]
	v_mfma_f32_16x16x32_bf16 v[118:121], v[214:217], v[206:209], v[118:121]
	v_mfma_f32_16x16x32_bf16 v[122:125], v[218:221], v[206:209], v[122:125]
	v_mfma_f32_16x16x32_bf16 v[126:129], v[222:225], v[206:209], v[126:129]
	s_setprio 0
